# GEMM mainloops: all per-cluster s_setprio flips deleted (attention keeps its static younger-half raise)
# speedup vs baseline: 1.0045x; 1.0032x over previous
; #define PG8_STAGE(bufoff, gbase, voff) do { _Pragma("unroll") for (int _i = 0; _i < 2; ++_i) \
;         __builtin_amdgcn_global_load_lds((const unsigned*)((const char*)(gbase) + (voff)[_i]), (PG8_LAS unsigned*)(lds + (bufoff) + ldsw + _i * 8192), 16, 0, 0); } while (0)
; #define PG8_LDA(dst, b, h) do { _Pragma("unroll") for (int m = 0; m < 4; ++m) _Pragma("unroll") for (int k = 0; k < 2; ++k) dst[m][k] = *(const PG8_LAS bf16x8*)(lds + PG8_SA(b, h) + aoff + m * 2048 + k * 1024); } while (0)
; #define PG8_LDB(dst, b, h) do { _Pragma("unroll") for (int n = 0; n < 2; ++n) _Pragma("unroll") for (int k = 0; k < 2; ++k) dst[n][k] = *(const PG8_LAS bf16x8*)(lds + PG8_SB(b, h) + boff + n * 2048 + k * 1024); } while (0)
; #define PG8_MMA(ai, bj, At, Bt) do { __builtin_amdgcn_s_setprio(1); _Pragma("unroll") for (int m = 0; m < 4; ++m) _Pragma("unroll") for (int n = 0; n < 2; ++n) _Pragma("unroll") for (int k = 0; k < 2; ++k) \
;         acc[ai][bj][m][n] = __builtin_amdgcn_mfma_f32_16x16x32_bf16(Bt[n][k], At[m][k], acc[ai][bj][m][n], 0, 0, 0); __builtin_amdgcn_s_setprio(0); } while (0)
; #define PG8_WAIT_V(n) asm volatile("s_waitcnt vmcnt(" #n ")" ::: "memory")
; #define PG8_WAIT_L(n) asm volatile("s_waitcnt lgkmcnt(" #n ")" ::: "memory")
; #define PG8_BAR __builtin_amdgcn_s_barrier()
; #define PG8_SCHED __builtin_amdgcn_sched_barrier(0)
; template <class Epi, class Sched>
; __device__ __forceinline__ void gemm_phase(PG8_LAS unsigned char* lds, const int tid, const Gemm g, const Sched& S, const Epi& E) {
;     ...
;             PG8_LDB(B0, 0, 0); PG8_LDB(B1, 0, 1); PG8_SCHED; PG8_LDA(At, 0, 0); PG8_STAGE(PG8_SA(1, 1), a1 + hstepA, voffA);
;             PG8_WAIT_V(8); PG8_WAIT_L(0); PG8_BAR; PG8_MMA(0, 0, At, B0); PG8_MMA(0, 1, At, B1); PG8_BAR; PG8_SCHED;
;             PG8_LDA(At, 0, 1); PG8_STAGE(PG8_SB(0, 0), b2, voffB); PG8_STAGE(PG8_SB(0, 1), b2 + hstepB, voffB); PG8_STAGE(PG8_SA(0, 0), a2, voffA);
;             PG8_WAIT_V(8); PG8_WAIT_L(0); PG8_BAR; PG8_MMA(1, 0, At, B0); PG8_MMA(1, 1, At, B1); PG8_BAR; PG8_SCHED;
.LBB0_45:
	ds_read_b128 v[138:141], v165
	ds_read_b128 v[184:187], v165 offset:1024
	ds_read_b128 v[188:191], v165 offset:2048
	ds_read_b128 v[192:195], v165 offset:3072
	ds_read_b128 v[200:203], v167
	ds_read_b128 v[204:207], v167 offset:1024
	ds_read_b128 v[208:211], v167 offset:2048
	ds_read_b128 v[212:215], v167 offset:3072
	s_add_u32 s20, s2, 0x100
	s_addc_u32 s21, s3, 0
	s_cmp_eq_u32 s86, 40
	s_cselect_b32 s27, s9, s21
	s_cselect_b32 s26, s8, s20
	s_cselect_b32 s25, s19, s39
	s_cselect_b32 s24, s18, s36
	v_lshl_add_u64 v[142:143], s[2:3], 0, v[136:137]
	s_add_i32 m0, s41, 0xc000
	ds_read_b128 v[216:219], v168
	ds_read_b128 v[220:223], v168 offset:1024
	ds_read_b128 v[224:227], v168 offset:2048
	ds_read_b128 v[228:231], v168 offset:3072
	ds_read_b128 v[232:235], v168 offset:4096
	ds_read_b128 v[236:239], v168 offset:5120
	ds_read_b128 v[240:243], v168 offset:6144
	ds_read_b128 v[244:247], v168 offset:7168
	global_load_lds_dwordx4 v[142:143], off
	v_lshl_add_u64 v[142:143], s[2:3], 0, v[134:135]
	s_add_i32 m0, s41, 0xe000
	s_nop 0
	global_load_lds_dwordx4 v[142:143], off
	s_waitcnt vmcnt(8)
	s_waitcnt lgkmcnt(0)
	s_barrier
	s_waitcnt lgkmcnt(0)
	v_mfma_f32_16x16x32_bf16 v[126:129], v[138:141], v[216:219], v[126:129]
	v_mfma_f32_16x16x32_bf16 v[122:125], v[188:191], v[216:219], v[122:125]
	v_mfma_f32_16x16x32_bf16 v[110:113], v[138:141], v[224:227], v[110:113]
	v_mfma_f32_16x16x32_bf16 v[106:109], v[188:191], v[224:227], v[106:109]
	v_mfma_f32_16x16x32_bf16 v[94:97], v[138:141], v[232:235], v[94:97]
	v_mfma_f32_16x16x32_bf16 v[90:93], v[188:191], v[232:235], v[90:93]
	v_mfma_f32_16x16x32_bf16 v[78:81], v[138:141], v[240:243], v[78:81]
	v_mfma_f32_16x16x32_bf16 v[74:77], v[188:191], v[240:243], v[74:77]
	v_mfma_f32_16x16x32_bf16 v[126:129], v[184:187], v[220:223], v[126:129]
	v_mfma_f32_16x16x32_bf16 v[122:125], v[192:195], v[220:223], v[122:125]
	v_mfma_f32_16x16x32_bf16 v[110:113], v[184:187], v[228:231], v[110:113]
	v_mfma_f32_16x16x32_bf16 v[106:109], v[192:195], v[228:231], v[106:109]
	v_mfma_f32_16x16x32_bf16 v[94:97], v[184:187], v[236:239], v[94:97]
	v_mfma_f32_16x16x32_bf16 v[90:93], v[192:195], v[236:239], v[90:93]
	v_mfma_f32_16x16x32_bf16 v[78:81], v[184:187], v[244:247], v[78:81]
	v_mfma_f32_16x16x32_bf16 v[74:77], v[192:195], v[244:247], v[74:77]
	v_mfma_f32_16x16x32_bf16 v[118:121], v[200:203], v[216:219], v[118:121]
	v_mfma_f32_16x16x32_bf16 v[114:117], v[208:211], v[216:219], v[114:117]
	v_mfma_f32_16x16x32_bf16 v[102:105], v[200:203], v[224:227], v[102:105]
	v_mfma_f32_16x16x32_bf16 v[98:101], v[208:211], v[224:227], v[98:101]
	v_mfma_f32_16x16x32_bf16 v[86:89], v[200:203], v[232:235], v[86:89]
	v_mfma_f32_16x16x32_bf16 v[82:85], v[208:211], v[232:235], v[82:85]
	v_mfma_f32_16x16x32_bf16 v[70:73], v[200:203], v[240:243], v[70:73]
	v_mfma_f32_16x16x32_bf16 v[66:69], v[208:211], v[240:243], v[66:69]
	v_mfma_f32_16x16x32_bf16 v[118:121], v[204:207], v[220:223], v[118:121]
	v_mfma_f32_16x16x32_bf16 v[114:117], v[212:215], v[220:223], v[114:117]
	v_mfma_f32_16x16x32_bf16 v[102:105], v[204:207], v[228:231], v[102:105]
	v_mfma_f32_16x16x32_bf16 v[98:101], v[212:215], v[228:231], v[98:101]
	v_mfma_f32_16x16x32_bf16 v[86:89], v[204:207], v[236:239], v[86:89]
	v_mfma_f32_16x16x32_bf16 v[82:85], v[212:215], v[236:239], v[82:85]
	v_mfma_f32_16x16x32_bf16 v[70:73], v[204:207], v[244:247], v[70:73]
	v_mfma_f32_16x16x32_bf16 v[66:69], v[212:215], v[244:247], v[66:69]
	s_barrier
	s_mov_b32 m0, s31
	v_lshl_add_u64 v[142:143], s[24:25], 0, v[130:131]
	s_add_u32 s2, s24, 0xb0000
	ds_read_b128 v[216:219], v168 offset:16384
	ds_read_b128 v[220:223], v168 offset:17408
	ds_read_b128 v[224:227], v168 offset:18432
	ds_read_b128 v[228:231], v168 offset:19456
	ds_read_b128 v[232:235], v168 offset:20480
	ds_read_b128 v[236:239], v168 offset:21504
	ds_read_b128 v[240:243], v168 offset:22528
	ds_read_b128 v[244:247], v168 offset:23552
	global_load_lds_dwordx4 v[142:143], off
	v_lshl_add_u64 v[196:197], s[24:25], 0, v[132:133]
	s_mov_b32 m0, s34
	s_addc_u32 s3, s25, 0
	global_load_lds_dwordx4 v[196:197], off
	v_lshl_add_u64 v[248:249], s[2:3], 0, v[130:131]
	s_mov_b32 m0, s35
	v_lshl_add_u64 v[250:251], s[26:27], 0, v[132:133]
	global_load_lds_dwordx4 v[248:249], off
	v_lshl_add_u64 v[248:249], s[2:3], 0, v[132:133]
	s_mov_b32 m0, s40
	s_nop 0
	global_load_lds_dwordx4 v[248:249], off
	v_lshl_add_u64 v[248:249], s[26:27], 0, v[130:131]
	s_mov_b32 m0, s41
	s_nop 0
	global_load_lds_dwordx4 v[248:249], off
	s_mov_b32 m0, s42
	s_nop 0
	global_load_lds_dwordx4 v[250:251], off
	s_waitcnt vmcnt(8)
	s_waitcnt lgkmcnt(0)
	s_barrier
; #define PG8_STAGE(bufoff, gbase, voff) do { _Pragma("unroll") for (int _i = 0; _i < 2; ++_i) \
;         __builtin_amdgcn_global_load_lds((const unsigned*)((const char*)(gbase) + (voff)[_i]), (PG8_LAS unsigned*)(lds + (bufoff) + ldsw + _i * 8192), 16, 0, 0); } while (0)
; #define PG8_LDA(dst, b, h) do { _Pragma("unroll") for (int m = 0; m < 4; ++m) _Pragma("unroll") for (int k = 0; k < 2; ++k) dst[m][k] = *(const PG8_LAS bf16x8*)(lds + PG8_SA(b, h) + aoff + m * 2048 + k * 1024); } while (0)
; #define PG8_LDB(dst, b, h) do { _Pragma("unroll") for (int n = 0; n < 2; ++n) _Pragma("unroll") for (int k = 0; k < 2; ++k) dst[n][k] = *(const PG8_LAS bf16x8*)(lds + PG8_SB(b, h) + boff + n * 2048 + k * 1024); } while (0)
; #define PG8_MMA(ai, bj, At, Bt) do { __builtin_amdgcn_s_setprio(1); _Pragma("unroll") for (int m = 0; m < 4; ++m) _Pragma("unroll") for (int n = 0; n < 2; ++n) _Pragma("unroll") for (int k = 0; k < 2; ++k) \
;         acc[ai][bj][m][n] = __builtin_amdgcn_mfma_f32_16x16x32_bf16(Bt[n][k], At[m][k], acc[ai][bj][m][n], 0, 0, 0); __builtin_amdgcn_s_setprio(0); } while (0)
; #define PG8_WAIT_V(n) asm volatile("s_waitcnt vmcnt(" #n ")" ::: "memory")
; #define PG8_WAIT_L(n) asm volatile("s_waitcnt lgkmcnt(" #n ")" ::: "memory")
; #define PG8_BAR __builtin_amdgcn_s_barrier()
; #define PG8_SCHED __builtin_amdgcn_sched_barrier(0)
; template <class Epi, class Sched>
; __device__ __forceinline__ void gemm_phase(PG8_LAS unsigned char* lds, const int tid, const Gemm g, const Sched& S, const Epi& E) {
;     ...
;             PG8_WAIT_V(8); PG8_WAIT_L(0); PG8_BAR; PG8_MMA(1, 0, At, B0); PG8_MMA(1, 1, At, B1); PG8_BAR; PG8_SCHED;
;             PG8_LDB(B0, 1, 0); PG8_LDB(B1, 1, 1); PG8_SCHED; PG8_LDA(At, 1, 0); PG8_STAGE(PG8_SA(0, 1), a2 + hstepA, voffA);
;             PG8_WAIT_V(8); PG8_WAIT_L(0); PG8_BAR; PG8_MMA(0, 0, At, B0); PG8_MMA(0, 1, At, B1); PG8_BAR; PG8_SCHED;
	s_waitcnt lgkmcnt(0)
	v_mfma_f32_16x16x32_bf16 v[62:65], v[138:141], v[216:219], v[62:65]
	v_mfma_f32_16x16x32_bf16 v[58:61], v[188:191], v[216:219], v[58:61]
	v_mfma_f32_16x16x32_bf16 v[46:49], v[138:141], v[224:227], v[46:49]
	v_mfma_f32_16x16x32_bf16 v[42:45], v[188:191], v[224:227], v[42:45]
	v_mfma_f32_16x16x32_bf16 v[30:33], v[138:141], v[232:235], v[30:33]
	v_mfma_f32_16x16x32_bf16 v[26:29], v[188:191], v[232:235], v[26:29]
	v_mfma_f32_16x16x32_bf16 v[14:17], v[138:141], v[240:243], v[14:17]
	v_mfma_f32_16x16x32_bf16 v[10:13], v[188:191], v[240:243], v[10:13]
	v_mfma_f32_16x16x32_bf16 v[62:65], v[184:187], v[220:223], v[62:65]
	v_mfma_f32_16x16x32_bf16 v[58:61], v[192:195], v[220:223], v[58:61]
	v_mfma_f32_16x16x32_bf16 v[46:49], v[184:187], v[228:231], v[46:49]
	v_mfma_f32_16x16x32_bf16 v[42:45], v[192:195], v[228:231], v[42:45]
	v_mfma_f32_16x16x32_bf16 v[30:33], v[184:187], v[236:239], v[30:33]
	v_mfma_f32_16x16x32_bf16 v[26:29], v[192:195], v[236:239], v[26:29]
	v_mfma_f32_16x16x32_bf16 v[14:17], v[184:187], v[244:247], v[14:17]
	v_mfma_f32_16x16x32_bf16 v[10:13], v[192:195], v[244:247], v[10:13]
	v_mfma_f32_16x16x32_bf16 v[54:57], v[200:203], v[216:219], v[54:57]
	v_mfma_f32_16x16x32_bf16 v[50:53], v[208:211], v[216:219], v[50:53]
	v_mfma_f32_16x16x32_bf16 v[38:41], v[200:203], v[224:227], v[38:41]
	v_mfma_f32_16x16x32_bf16 v[34:37], v[208:211], v[224:227], v[34:37]
	v_mfma_f32_16x16x32_bf16 v[22:25], v[200:203], v[232:235], v[22:25]
	v_mfma_f32_16x16x32_bf16 v[18:21], v[208:211], v[232:235], v[18:21]
	v_mfma_f32_16x16x32_bf16 v[6:9], v[200:203], v[240:243], v[6:9]
	v_mfma_f32_16x16x32_bf16 v[2:5], v[208:211], v[240:243], v[2:5]
	v_mfma_f32_16x16x32_bf16 v[54:57], v[204:207], v[220:223], v[54:57]
	v_mfma_f32_16x16x32_bf16 v[50:53], v[212:215], v[220:223], v[50:53]
	v_mfma_f32_16x16x32_bf16 v[38:41], v[204:207], v[228:231], v[38:41]
	v_mfma_f32_16x16x32_bf16 v[34:37], v[212:215], v[228:231], v[34:37]
	v_mfma_f32_16x16x32_bf16 v[22:25], v[204:207], v[236:239], v[22:25]
	v_mfma_f32_16x16x32_bf16 v[18:21], v[212:215], v[236:239], v[18:21]
	v_mfma_f32_16x16x32_bf16 v[6:9], v[204:207], v[244:247], v[6:9]
	v_mfma_f32_16x16x32_bf16 v[2:5], v[212:215], v[244:247], v[2:5]
	s_barrier
	ds_read_b128 v[138:141], v169
	ds_read_b128 v[184:187], v169 offset:1024
	ds_read_b128 v[188:191], v169 offset:2048
	ds_read_b128 v[192:195], v169 offset:3072
	ds_read_b128 v[200:203], v170
	ds_read_b128 v[204:207], v170 offset:1024
	ds_read_b128 v[208:211], v170 offset:2048
	ds_read_b128 v[212:215], v170 offset:3072
	s_add_u32 s2, s26, 0xb0000
	s_addc_u32 s3, s27, 0
	s_mov_b32 m0, s44
	v_lshl_add_u64 v[252:253], s[2:3], 0, v[130:131]
	ds_read_b128 v[216:219], v168 offset:32768
	ds_read_b128 v[220:223], v168 offset:33792
	ds_read_b128 v[224:227], v168 offset:34816
	ds_read_b128 v[228:231], v168 offset:35840
	ds_read_b128 v[232:235], v168 offset:36864
	ds_read_b128 v[236:239], v168 offset:37888
	ds_read_b128 v[240:243], v168 offset:38912
	ds_read_b128 v[244:247], v168 offset:39936
	global_load_lds_dwordx4 v[252:253], off
	v_lshl_add_u64 v[252:253], s[2:3], 0, v[132:133]
	s_mov_b32 m0, s45
	s_nop 0
	global_load_lds_dwordx4 v[252:253], off
	s_waitcnt vmcnt(8)
	s_waitcnt lgkmcnt(0)
	s_barrier
	s_waitcnt lgkmcnt(0)
	v_mfma_f32_16x16x32_bf16 v[126:129], v[138:141], v[216:219], v[126:129]
	v_mfma_f32_16x16x32_bf16 v[122:125], v[188:191], v[216:219], v[122:125]
	v_mfma_f32_16x16x32_bf16 v[110:113], v[138:141], v[224:227], v[110:113]
	v_mfma_f32_16x16x32_bf16 v[106:109], v[188:191], v[224:227], v[106:109]
	v_mfma_f32_16x16x32_bf16 v[94:97], v[138:141], v[232:235], v[94:97]
	v_mfma_f32_16x16x32_bf16 v[90:93], v[188:191], v[232:235], v[90:93]
	v_mfma_f32_16x16x32_bf16 v[78:81], v[138:141], v[240:243], v[78:81]
	v_mfma_f32_16x16x32_bf16 v[74:77], v[188:191], v[240:243], v[74:77]
	v_mfma_f32_16x16x32_bf16 v[126:129], v[184:187], v[220:223], v[126:129]
	v_mfma_f32_16x16x32_bf16 v[122:125], v[192:195], v[220:223], v[122:125]
	v_mfma_f32_16x16x32_bf16 v[110:113], v[184:187], v[228:231], v[110:113]
	v_mfma_f32_16x16x32_bf16 v[106:109], v[192:195], v[228:231], v[106:109]
	v_mfma_f32_16x16x32_bf16 v[94:97], v[184:187], v[236:239], v[94:97]
	v_mfma_f32_16x16x32_bf16 v[90:93], v[192:195], v[236:239], v[90:93]
	v_mfma_f32_16x16x32_bf16 v[78:81], v[184:187], v[244:247], v[78:81]
	v_mfma_f32_16x16x32_bf16 v[74:77], v[192:195], v[244:247], v[74:77]
	v_mfma_f32_16x16x32_bf16 v[118:121], v[200:203], v[216:219], v[118:121]
	v_mfma_f32_16x16x32_bf16 v[114:117], v[208:211], v[216:219], v[114:117]
	v_mfma_f32_16x16x32_bf16 v[102:105], v[200:203], v[224:227], v[102:105]
	v_mfma_f32_16x16x32_bf16 v[98:101], v[208:211], v[224:227], v[98:101]
	v_mfma_f32_16x16x32_bf16 v[86:89], v[200:203], v[232:235], v[86:89]
	v_mfma_f32_16x16x32_bf16 v[82:85], v[208:211], v[232:235], v[82:85]
	v_mfma_f32_16x16x32_bf16 v[70:73], v[200:203], v[240:243], v[70:73]
	v_mfma_f32_16x16x32_bf16 v[66:69], v[208:211], v[240:243], v[66:69]
	v_mfma_f32_16x16x32_bf16 v[118:121], v[204:207], v[220:223], v[118:121]
	v_mfma_f32_16x16x32_bf16 v[114:117], v[212:215], v[220:223], v[114:117]
	v_mfma_f32_16x16x32_bf16 v[102:105], v[204:207], v[228:231], v[102:105]
	v_mfma_f32_16x16x32_bf16 v[98:101], v[212:215], v[228:231], v[98:101]
	v_mfma_f32_16x16x32_bf16 v[86:89], v[204:207], v[236:239], v[86:89]
	v_mfma_f32_16x16x32_bf16 v[82:85], v[212:215], v[236:239], v[82:85]
	v_mfma_f32_16x16x32_bf16 v[70:73], v[204:207], v[244:247], v[70:73]
	v_mfma_f32_16x16x32_bf16 v[66:69], v[212:215], v[244:247], v[66:69]
	s_barrier
; #define PG8_STAGE(bufoff, gbase, voff) do { _Pragma("unroll") for (int _i = 0; _i < 2; ++_i) \
;         __builtin_amdgcn_global_load_lds((const unsigned*)((const char*)(gbase) + (voff)[_i]), (PG8_LAS unsigned*)(lds + (bufoff) + ldsw + _i * 8192), 16, 0, 0); } while (0)
; #define PG8_LDA(dst, b, h) do { _Pragma("unroll") for (int m = 0; m < 4; ++m) _Pragma("unroll") for (int k = 0; k < 2; ++k) dst[m][k] = *(const PG8_LAS bf16x8*)(lds + PG8_SA(b, h) + aoff + m * 2048 + k * 1024); } while (0)
; #define PG8_MMA(ai, bj, At, Bt) do { __builtin_amdgcn_s_setprio(1); _Pragma("unroll") for (int m = 0; m < 4; ++m) _Pragma("unroll") for (int n = 0; n < 2; ++n) _Pragma("unroll") for (int k = 0; k < 2; ++k) \
;         acc[ai][bj][m][n] = __builtin_amdgcn_mfma_f32_16x16x32_bf16(Bt[n][k], At[m][k], acc[ai][bj][m][n], 0, 0, 0); __builtin_amdgcn_s_setprio(0); } while (0)
; #define PG8_WAIT_V(n) asm volatile("s_waitcnt vmcnt(" #n ")" ::: "memory")
; #define PG8_WAIT_L(n) asm volatile("s_waitcnt lgkmcnt(" #n ")" ::: "memory")
; #define PG8_BAR __builtin_amdgcn_s_barrier()
; #define PG8_SCHED __builtin_amdgcn_sched_barrier(0)
; template <class Epi, class Sched>
; __device__ __forceinline__ void gemm_phase(PG8_LAS unsigned char* lds, const int tid, const Gemm g, const Sched& S, const Epi& E) {
;     ...
;             PG8_LDA(At, 1, 1); PG8_STAGE(PG8_SB(1, 0), b3, voffB); PG8_STAGE(PG8_SB(1, 1), b3 + hstepB, voffB); PG8_STAGE(PG8_SA(1, 0), a3, voffA);
;             PG8_WAIT_V(8); PG8_WAIT_L(0); PG8_BAR; PG8_MMA(1, 0, At, B0); PG8_MMA(1, 1, At, B1); PG8_BAR; PG8_SCHED;
;         }
;         if constexpr (ALIGN_EPI) { if (wr == 0) PG8_BAR; }
	s_mov_b32 m0, s49
	v_lshl_add_u64 v[142:143], v[142:143], 0, s[54:55]
	s_add_u32 s2, s24, 0xb0080
	ds_read_b128 v[216:219], v168 offset:49152
	ds_read_b128 v[220:223], v168 offset:50176
	ds_read_b128 v[224:227], v168 offset:51200
	ds_read_b128 v[228:231], v168 offset:52224
	ds_read_b128 v[232:235], v168 offset:53248
	ds_read_b128 v[236:239], v168 offset:54272
	ds_read_b128 v[240:243], v168 offset:55296
	ds_read_b128 v[244:247], v168 offset:56320
	global_load_lds_dwordx4 v[142:143], off
	v_lshl_add_u64 v[142:143], v[196:197], 0, s[54:55]
	s_mov_b32 m0, s58
	s_addc_u32 s3, s25, 0
	global_load_lds_dwordx4 v[142:143], off
	v_lshl_add_u64 v[142:143], s[2:3], 0, v[130:131]
	s_mov_b32 m0, s73
	s_nop 0
	global_load_lds_dwordx4 v[142:143], off
	v_lshl_add_u64 v[142:143], s[2:3], 0, v[132:133]
	s_mov_b32 m0, s80
	s_nop 0
	global_load_lds_dwordx4 v[142:143], off
	v_lshl_add_u64 v[142:143], v[248:249], 0, s[54:55]
	s_mov_b32 m0, s59
	s_nop 0
	global_load_lds_dwordx4 v[142:143], off
	v_lshl_add_u64 v[142:143], v[250:251], 0, s[54:55]
	s_mov_b32 m0, s72
	s_nop 0
	global_load_lds_dwordx4 v[142:143], off
	s_waitcnt vmcnt(8)
	s_waitcnt lgkmcnt(0)
	s_barrier
	s_waitcnt lgkmcnt(0)
	v_mfma_f32_16x16x32_bf16 v[62:65], v[138:141], v[216:219], v[62:65]
	v_mfma_f32_16x16x32_bf16 v[58:61], v[188:191], v[216:219], v[58:61]
	v_mfma_f32_16x16x32_bf16 v[46:49], v[138:141], v[224:227], v[46:49]
	v_mfma_f32_16x16x32_bf16 v[42:45], v[188:191], v[224:227], v[42:45]
	v_mfma_f32_16x16x32_bf16 v[30:33], v[138:141], v[232:235], v[30:33]
	v_mfma_f32_16x16x32_bf16 v[26:29], v[188:191], v[232:235], v[26:29]
	v_mfma_f32_16x16x32_bf16 v[14:17], v[138:141], v[240:243], v[14:17]
	v_mfma_f32_16x16x32_bf16 v[10:13], v[188:191], v[240:243], v[10:13]
	v_mfma_f32_16x16x32_bf16 v[62:65], v[184:187], v[220:223], v[62:65]
	v_mfma_f32_16x16x32_bf16 v[58:61], v[192:195], v[220:223], v[58:61]
	v_mfma_f32_16x16x32_bf16 v[46:49], v[184:187], v[228:231], v[46:49]
	v_mfma_f32_16x16x32_bf16 v[42:45], v[192:195], v[228:231], v[42:45]
	v_mfma_f32_16x16x32_bf16 v[30:33], v[184:187], v[236:239], v[30:33]
	v_mfma_f32_16x16x32_bf16 v[26:29], v[192:195], v[236:239], v[26:29]
	v_mfma_f32_16x16x32_bf16 v[14:17], v[184:187], v[244:247], v[14:17]
	v_mfma_f32_16x16x32_bf16 v[10:13], v[192:195], v[244:247], v[10:13]
	v_mfma_f32_16x16x32_bf16 v[54:57], v[200:203], v[216:219], v[54:57]
	v_mfma_f32_16x16x32_bf16 v[50:53], v[208:211], v[216:219], v[50:53]
	v_mfma_f32_16x16x32_bf16 v[38:41], v[200:203], v[224:227], v[38:41]
	v_mfma_f32_16x16x32_bf16 v[34:37], v[208:211], v[224:227], v[34:37]
	v_mfma_f32_16x16x32_bf16 v[22:25], v[200:203], v[232:235], v[22:25]
	v_mfma_f32_16x16x32_bf16 v[18:21], v[208:211], v[232:235], v[18:21]
	v_mfma_f32_16x16x32_bf16 v[6:9], v[200:203], v[240:243], v[6:9]
	v_mfma_f32_16x16x32_bf16 v[2:5], v[208:211], v[240:243], v[2:5]
	v_mfma_f32_16x16x32_bf16 v[54:57], v[204:207], v[220:223], v[54:57]
	v_mfma_f32_16x16x32_bf16 v[50:53], v[212:215], v[220:223], v[50:53]
	v_mfma_f32_16x16x32_bf16 v[38:41], v[204:207], v[228:231], v[38:41]
	v_mfma_f32_16x16x32_bf16 v[34:37], v[212:215], v[228:231], v[34:37]
	v_mfma_f32_16x16x32_bf16 v[22:25], v[204:207], v[236:239], v[22:25]
	v_mfma_f32_16x16x32_bf16 v[18:21], v[212:215], v[236:239], v[18:21]
	v_mfma_f32_16x16x32_bf16 v[6:9], v[204:207], v[244:247], v[6:9]
	v_mfma_f32_16x16x32_bf16 v[2:5], v[212:215], v[244:247], v[2:5]
	s_barrier
	s_add_i32 s86, s86, 2
	s_add_u32 s36, s36, 0x100
	s_addc_u32 s39, s39, 0
	s_cmp_gt_u32 s86, 41
	s_mov_b64 s[2:3], s[20:21]
	s_cbranch_scc0 .LBB0_45
	s_and_b64 vcc, exec, s[14:15]
	s_cbranch_vccz .LBB0_48
	s_barrier

; #define PG8_STAGE(bufoff, gbase, voff) do { _Pragma("unroll") for (int _i = 0; _i < 2; ++_i) \
;         __builtin_amdgcn_global_load_lds((const unsigned*)((const char*)(gbase) + (voff)[_i]), (PG8_LAS unsigned*)(lds + (bufoff) + ldsw + _i * 8192), 16, 0, 0); } while (0)
; #define PG8_LDA(dst, b, h) do { _Pragma("unroll") for (int m = 0; m < 4; ++m) _Pragma("unroll") for (int k = 0; k < 2; ++k) dst[m][k] = *(const PG8_LAS bf16x8*)(lds + PG8_SA(b, h) + aoff + m * 2048 + k * 1024); } while (0)
; #define PG8_LDB(dst, b, h) do { _Pragma("unroll") for (int n = 0; n < 2; ++n) _Pragma("unroll") for (int k = 0; k < 2; ++k) dst[n][k] = *(const PG8_LAS bf16x8*)(lds + PG8_SB(b, h) + boff + n * 2048 + k * 1024); } while (0)
; #define PG8_MMA(ai, bj, At, Bt) do { __builtin_amdgcn_s_setprio(1); _Pragma("unroll") for (int m = 0; m < 4; ++m) _Pragma("unroll") for (int n = 0; n < 2; ++n) _Pragma("unroll") for (int k = 0; k < 2; ++k) \
;         acc[ai][bj][m][n] = __builtin_amdgcn_mfma_f32_16x16x32_bf16(Bt[n][k], At[m][k], acc[ai][bj][m][n], 0, 0, 0); __builtin_amdgcn_s_setprio(0); } while (0)
; #define PG8_WAIT_V(n) asm volatile("s_waitcnt vmcnt(" #n ")" ::: "memory")
; #define PG8_WAIT_L(n) asm volatile("s_waitcnt lgkmcnt(" #n ")" ::: "memory")
; #define PG8_BAR __builtin_amdgcn_s_barrier()
; #define PG8_SCHED __builtin_amdgcn_sched_barrier(0)
; template <class Epi, class Sched>
; __device__ __forceinline__ void gemm_phase(PG8_LAS unsigned char* lds, const int tid, const Gemm g, const Sched& S, const Epi& E) {
;     ...
;             PG8_LDB(B0, 0, 0); PG8_LDB(B1, 0, 1); PG8_SCHED; PG8_LDA(At, 0, 0); PG8_STAGE(PG8_SA(1, 1), a1 + hstepA, voffA);
;             PG8_WAIT_V(8); PG8_WAIT_L(0); PG8_BAR; PG8_MMA(0, 0, At, B0); PG8_MMA(0, 1, At, B1); PG8_BAR; PG8_SCHED;
;             PG8_LDA(At, 0, 1); PG8_STAGE(PG8_SB(0, 0), b2, voffB); PG8_STAGE(PG8_SB(0, 1), b2 + hstepB, voffB); PG8_STAGE(PG8_SA(0, 0), a2, voffA);
;             PG8_WAIT_V(8); PG8_WAIT_L(0); PG8_BAR; PG8_MMA(1, 0, At, B0); PG8_MMA(1, 1, At, B1); PG8_BAR; PG8_SCHED;
.LBB0_64:
	v_add_u32_e32 v142, s31, v150
	ds_read_b128 v[168:171], v142
	ds_read_b128 v[184:187], v142 offset:1024
	ds_read_b128 v[188:191], v142 offset:2048
	ds_read_b128 v[192:195], v142 offset:3072
	v_add_u32_e32 v142, s49, v150
	ds_read_b128 v[200:203], v142
	ds_read_b128 v[204:207], v142 offset:1024
	ds_read_b128 v[208:211], v142 offset:2048
	ds_read_b128 v[212:215], v142 offset:3072
	s_add_u32 s34, s2, 0xfffc0080
	s_addc_u32 s35, s3, -1
	s_cmp_eq_u32 s39, 12
	s_cselect_b32 s45, s21, s35
	s_cselect_b32 s44, s36, s34
	s_cselect_b32 s35, s19, vcc_hi
	s_cselect_b32 s34, s97, vcc_lo
	v_lshl_add_u64 v[142:143], s[2:3], 0, v[140:141]
	s_add_i32 m0, s72, 0xc000
	ds_read_b128 v[216:219], v167
	ds_read_b128 v[220:223], v167 offset:1024
	ds_read_b128 v[224:227], v167 offset:2048
	ds_read_b128 v[228:231], v167 offset:3072
	ds_read_b128 v[232:235], v167 offset:4096
	ds_read_b128 v[236:239], v167 offset:5120
	ds_read_b128 v[240:243], v167 offset:6144
	ds_read_b128 v[244:247], v167 offset:7168
	global_load_lds_dwordx4 v[142:143], off
	v_lshl_add_u64 v[142:143], s[2:3], 0, v[138:139]
	s_add_i32 m0, s72, 0xe000
	s_nop 0
	global_load_lds_dwordx4 v[142:143], off
	s_waitcnt vmcnt(8)
	s_waitcnt lgkmcnt(0)
	s_barrier
	s_waitcnt lgkmcnt(0)
	v_mfma_f32_16x16x32_bf16 v[126:129], v[168:171], v[216:219], v[126:129]
	v_mfma_f32_16x16x32_bf16 v[122:125], v[188:191], v[216:219], v[122:125]
	v_mfma_f32_16x16x32_bf16 v[110:113], v[168:171], v[224:227], v[110:113]
	v_mfma_f32_16x16x32_bf16 v[106:109], v[188:191], v[224:227], v[106:109]
	v_mfma_f32_16x16x32_bf16 v[94:97], v[168:171], v[232:235], v[94:97]
	v_mfma_f32_16x16x32_bf16 v[90:93], v[188:191], v[232:235], v[90:93]
	v_mfma_f32_16x16x32_bf16 v[78:81], v[168:171], v[240:243], v[78:81]
	v_mfma_f32_16x16x32_bf16 v[74:77], v[188:191], v[240:243], v[74:77]
	v_mfma_f32_16x16x32_bf16 v[126:129], v[184:187], v[220:223], v[126:129]
	v_mfma_f32_16x16x32_bf16 v[122:125], v[192:195], v[220:223], v[122:125]
	v_mfma_f32_16x16x32_bf16 v[110:113], v[184:187], v[228:231], v[110:113]
	v_mfma_f32_16x16x32_bf16 v[106:109], v[192:195], v[228:231], v[106:109]
	v_mfma_f32_16x16x32_bf16 v[94:97], v[184:187], v[236:239], v[94:97]
	v_mfma_f32_16x16x32_bf16 v[90:93], v[192:195], v[236:239], v[90:93]
	v_mfma_f32_16x16x32_bf16 v[78:81], v[184:187], v[244:247], v[78:81]
	v_mfma_f32_16x16x32_bf16 v[74:77], v[192:195], v[244:247], v[74:77]
	v_mfma_f32_16x16x32_bf16 v[118:121], v[200:203], v[216:219], v[118:121]
	v_mfma_f32_16x16x32_bf16 v[114:117], v[208:211], v[216:219], v[114:117]
	v_mfma_f32_16x16x32_bf16 v[102:105], v[200:203], v[224:227], v[102:105]
	v_mfma_f32_16x16x32_bf16 v[98:101], v[208:211], v[224:227], v[98:101]
	v_mfma_f32_16x16x32_bf16 v[86:89], v[200:203], v[232:235], v[86:89]
	v_mfma_f32_16x16x32_bf16 v[82:85], v[208:211], v[232:235], v[82:85]
	v_mfma_f32_16x16x32_bf16 v[70:73], v[200:203], v[240:243], v[70:73]
	v_mfma_f32_16x16x32_bf16 v[66:69], v[208:211], v[240:243], v[66:69]
	v_mfma_f32_16x16x32_bf16 v[118:121], v[204:207], v[220:223], v[118:121]
	v_mfma_f32_16x16x32_bf16 v[114:117], v[212:215], v[220:223], v[114:117]
	v_mfma_f32_16x16x32_bf16 v[102:105], v[204:207], v[228:231], v[102:105]
	v_mfma_f32_16x16x32_bf16 v[98:101], v[212:215], v[228:231], v[98:101]
	v_mfma_f32_16x16x32_bf16 v[86:89], v[204:207], v[236:239], v[86:89]
	v_mfma_f32_16x16x32_bf16 v[82:85], v[212:215], v[236:239], v[82:85]
	v_mfma_f32_16x16x32_bf16 v[70:73], v[204:207], v[244:247], v[70:73]
	v_mfma_f32_16x16x32_bf16 v[66:69], v[212:215], v[244:247], v[66:69]
	s_barrier
	s_mov_b32 m0, s41
	v_lshl_add_u64 v[142:143], s[34:35], 0, v[134:135]
	s_add_u32 s62, s34, 0x40000
	ds_read_b128 v[216:219], v167 offset:16384
	ds_read_b128 v[220:223], v167 offset:17408
	ds_read_b128 v[224:227], v167 offset:18432
	ds_read_b128 v[228:231], v167 offset:19456
	ds_read_b128 v[232:235], v167 offset:20480
	ds_read_b128 v[236:239], v167 offset:21504
	ds_read_b128 v[240:243], v167 offset:22528
	ds_read_b128 v[244:247], v167 offset:23552
	global_load_lds_dwordx4 v[142:143], off
	v_lshl_add_u64 v[196:197], s[34:35], 0, v[130:131]
	s_mov_b32 m0, s42
	s_addc_u32 s63, s35, 0
	global_load_lds_dwordx4 v[196:197], off
	v_lshl_add_u64 v[248:249], s[62:63], 0, v[134:135]
	s_mov_b32 m0, s58
	v_lshl_add_u64 v[250:251], s[44:45], 0, v[132:133]
	global_load_lds_dwordx4 v[248:249], off
	v_lshl_add_u64 v[248:249], s[62:63], 0, v[130:131]
	s_mov_b32 m0, s59
	s_nop 0
	global_load_lds_dwordx4 v[248:249], off
	v_lshl_add_u64 v[248:249], s[44:45], 0, v[136:137]
	s_mov_b32 m0, s72
	s_nop 0
	global_load_lds_dwordx4 v[248:249], off
	s_mov_b32 m0, s73
	s_nop 0
	global_load_lds_dwordx4 v[250:251], off
	s_waitcnt vmcnt(8)
	s_waitcnt lgkmcnt(0)
	s_barrier
; #define PG8_STAGE(bufoff, gbase, voff) do { _Pragma("unroll") for (int _i = 0; _i < 2; ++_i) \
;         __builtin_amdgcn_global_load_lds((const unsigned*)((const char*)(gbase) + (voff)[_i]), (PG8_LAS unsigned*)(lds + (bufoff) + ldsw + _i * 8192), 16, 0, 0); } while (0)
; #define PG8_LDA(dst, b, h) do { _Pragma("unroll") for (int m = 0; m < 4; ++m) _Pragma("unroll") for (int k = 0; k < 2; ++k) dst[m][k] = *(const PG8_LAS bf16x8*)(lds + PG8_SA(b, h) + aoff + m * 2048 + k * 1024); } while (0)
; #define PG8_LDB(dst, b, h) do { _Pragma("unroll") for (int n = 0; n < 2; ++n) _Pragma("unroll") for (int k = 0; k < 2; ++k) dst[n][k] = *(const PG8_LAS bf16x8*)(lds + PG8_SB(b, h) + boff + n * 2048 + k * 1024); } while (0)
; #define PG8_MMA(ai, bj, At, Bt) do { __builtin_amdgcn_s_setprio(1); _Pragma("unroll") for (int m = 0; m < 4; ++m) _Pragma("unroll") for (int n = 0; n < 2; ++n) _Pragma("unroll") for (int k = 0; k < 2; ++k) \
;         acc[ai][bj][m][n] = __builtin_amdgcn_mfma_f32_16x16x32_bf16(Bt[n][k], At[m][k], acc[ai][bj][m][n], 0, 0, 0); __builtin_amdgcn_s_setprio(0); } while (0)
; #define PG8_WAIT_V(n) asm volatile("s_waitcnt vmcnt(" #n ")" ::: "memory")
; #define PG8_WAIT_L(n) asm volatile("s_waitcnt lgkmcnt(" #n ")" ::: "memory")
; #define PG8_BAR __builtin_amdgcn_s_barrier()
; #define PG8_SCHED __builtin_amdgcn_sched_barrier(0)
; template <class Epi, class Sched>
; __device__ __forceinline__ void gemm_phase(PG8_LAS unsigned char* lds, const int tid, const Gemm g, const Sched& S, const Epi& E) {
;     ...
;             PG8_WAIT_V(8); PG8_WAIT_L(0); PG8_BAR; PG8_MMA(1, 0, At, B0); PG8_MMA(1, 1, At, B1); PG8_BAR; PG8_SCHED;
;             PG8_LDB(B0, 1, 0); PG8_LDB(B1, 1, 1); PG8_SCHED; PG8_LDA(At, 1, 0); PG8_STAGE(PG8_SA(0, 1), a2 + hstepA, voffA);
;             PG8_WAIT_V(8); PG8_WAIT_L(0); PG8_BAR; PG8_MMA(0, 0, At, B0); PG8_MMA(0, 1, At, B1); PG8_BAR; PG8_SCHED;
	s_waitcnt lgkmcnt(0)
	v_mfma_f32_16x16x32_bf16 v[62:65], v[168:171], v[216:219], v[62:65]
	v_mfma_f32_16x16x32_bf16 v[58:61], v[188:191], v[216:219], v[58:61]
	v_mfma_f32_16x16x32_bf16 v[46:49], v[168:171], v[224:227], v[46:49]
	v_mfma_f32_16x16x32_bf16 v[42:45], v[188:191], v[224:227], v[42:45]
	v_mfma_f32_16x16x32_bf16 v[30:33], v[168:171], v[232:235], v[30:33]
	v_mfma_f32_16x16x32_bf16 v[26:29], v[188:191], v[232:235], v[26:29]
	v_mfma_f32_16x16x32_bf16 v[14:17], v[168:171], v[240:243], v[14:17]
	v_mfma_f32_16x16x32_bf16 v[10:13], v[188:191], v[240:243], v[10:13]
	v_mfma_f32_16x16x32_bf16 v[62:65], v[184:187], v[220:223], v[62:65]
	v_mfma_f32_16x16x32_bf16 v[58:61], v[192:195], v[220:223], v[58:61]
	v_mfma_f32_16x16x32_bf16 v[46:49], v[184:187], v[228:231], v[46:49]
	v_mfma_f32_16x16x32_bf16 v[42:45], v[192:195], v[228:231], v[42:45]
	v_mfma_f32_16x16x32_bf16 v[30:33], v[184:187], v[236:239], v[30:33]
	v_mfma_f32_16x16x32_bf16 v[26:29], v[192:195], v[236:239], v[26:29]
	v_mfma_f32_16x16x32_bf16 v[14:17], v[184:187], v[244:247], v[14:17]
	v_mfma_f32_16x16x32_bf16 v[10:13], v[192:195], v[244:247], v[10:13]
	v_mfma_f32_16x16x32_bf16 v[54:57], v[200:203], v[216:219], v[54:57]
	v_mfma_f32_16x16x32_bf16 v[50:53], v[208:211], v[216:219], v[50:53]
	v_mfma_f32_16x16x32_bf16 v[38:41], v[200:203], v[224:227], v[38:41]
	v_mfma_f32_16x16x32_bf16 v[34:37], v[208:211], v[224:227], v[34:37]
	v_mfma_f32_16x16x32_bf16 v[22:25], v[200:203], v[232:235], v[22:25]
	v_mfma_f32_16x16x32_bf16 v[18:21], v[208:211], v[232:235], v[18:21]
	v_mfma_f32_16x16x32_bf16 v[6:9], v[200:203], v[240:243], v[6:9]
	v_mfma_f32_16x16x32_bf16 v[2:5], v[208:211], v[240:243], v[2:5]
	v_mfma_f32_16x16x32_bf16 v[54:57], v[204:207], v[220:223], v[54:57]
	v_mfma_f32_16x16x32_bf16 v[50:53], v[212:215], v[220:223], v[50:53]
	v_mfma_f32_16x16x32_bf16 v[38:41], v[204:207], v[228:231], v[38:41]
	v_mfma_f32_16x16x32_bf16 v[34:37], v[212:215], v[228:231], v[34:37]
	v_mfma_f32_16x16x32_bf16 v[22:25], v[204:207], v[236:239], v[22:25]
	v_mfma_f32_16x16x32_bf16 v[18:21], v[212:215], v[236:239], v[18:21]
	v_mfma_f32_16x16x32_bf16 v[6:9], v[204:207], v[244:247], v[6:9]
	v_mfma_f32_16x16x32_bf16 v[2:5], v[212:215], v[244:247], v[2:5]
	s_barrier
	v_add_u32_e32 v174, s82, v150
	ds_read_b128 v[168:171], v174
	ds_read_b128 v[184:187], v174 offset:1024
	ds_read_b128 v[188:191], v174 offset:2048
	ds_read_b128 v[192:195], v174 offset:3072
	v_add_u32_e32 v174, s87, v150
	ds_read_b128 v[200:203], v174
	ds_read_b128 v[204:207], v174 offset:1024
	ds_read_b128 v[208:211], v174 offset:2048
	ds_read_b128 v[212:215], v174 offset:3072
	s_add_u32 s44, s44, 0x40000
	s_addc_u32 s45, s45, 0
	s_mov_b32 m0, s80
	v_lshl_add_u64 v[252:253], s[44:45], 0, v[136:137]
	ds_read_b128 v[216:219], v167 offset:32768
	ds_read_b128 v[220:223], v167 offset:33792
	ds_read_b128 v[224:227], v167 offset:34816
	ds_read_b128 v[228:231], v167 offset:35840
	ds_read_b128 v[232:235], v167 offset:36864
	ds_read_b128 v[236:239], v167 offset:37888
	ds_read_b128 v[240:243], v167 offset:38912
	ds_read_b128 v[244:247], v167 offset:39936
	global_load_lds_dwordx4 v[252:253], off
	v_lshl_add_u64 v[252:253], s[44:45], 0, v[132:133]
	s_mov_b32 m0, s81
	s_nop 0
	global_load_lds_dwordx4 v[252:253], off
	s_waitcnt vmcnt(8)
	s_waitcnt lgkmcnt(0)
	s_barrier
	s_waitcnt lgkmcnt(0)
	v_mfma_f32_16x16x32_bf16 v[126:129], v[168:171], v[216:219], v[126:129]
	v_mfma_f32_16x16x32_bf16 v[122:125], v[188:191], v[216:219], v[122:125]
	v_mfma_f32_16x16x32_bf16 v[110:113], v[168:171], v[224:227], v[110:113]
	v_mfma_f32_16x16x32_bf16 v[106:109], v[188:191], v[224:227], v[106:109]
	v_mfma_f32_16x16x32_bf16 v[94:97], v[168:171], v[232:235], v[94:97]
	v_mfma_f32_16x16x32_bf16 v[90:93], v[188:191], v[232:235], v[90:93]
	v_mfma_f32_16x16x32_bf16 v[78:81], v[168:171], v[240:243], v[78:81]
	v_mfma_f32_16x16x32_bf16 v[74:77], v[188:191], v[240:243], v[74:77]
	v_mfma_f32_16x16x32_bf16 v[126:129], v[184:187], v[220:223], v[126:129]
	v_mfma_f32_16x16x32_bf16 v[122:125], v[192:195], v[220:223], v[122:125]
	v_mfma_f32_16x16x32_bf16 v[110:113], v[184:187], v[228:231], v[110:113]
	v_mfma_f32_16x16x32_bf16 v[106:109], v[192:195], v[228:231], v[106:109]
	v_mfma_f32_16x16x32_bf16 v[94:97], v[184:187], v[236:239], v[94:97]
	v_mfma_f32_16x16x32_bf16 v[90:93], v[192:195], v[236:239], v[90:93]
	v_mfma_f32_16x16x32_bf16 v[78:81], v[184:187], v[244:247], v[78:81]
	v_mfma_f32_16x16x32_bf16 v[74:77], v[192:195], v[244:247], v[74:77]
	v_mfma_f32_16x16x32_bf16 v[118:121], v[200:203], v[216:219], v[118:121]
	v_mfma_f32_16x16x32_bf16 v[114:117], v[208:211], v[216:219], v[114:117]
	v_mfma_f32_16x16x32_bf16 v[102:105], v[200:203], v[224:227], v[102:105]
	v_mfma_f32_16x16x32_bf16 v[98:101], v[208:211], v[224:227], v[98:101]
	v_mfma_f32_16x16x32_bf16 v[86:89], v[200:203], v[232:235], v[86:89]
	v_mfma_f32_16x16x32_bf16 v[82:85], v[208:211], v[232:235], v[82:85]
	v_mfma_f32_16x16x32_bf16 v[70:73], v[200:203], v[240:243], v[70:73]
	v_mfma_f32_16x16x32_bf16 v[66:69], v[208:211], v[240:243], v[66:69]
	v_mfma_f32_16x16x32_bf16 v[118:121], v[204:207], v[220:223], v[118:121]
	v_mfma_f32_16x16x32_bf16 v[114:117], v[212:215], v[220:223], v[114:117]
	v_mfma_f32_16x16x32_bf16 v[102:105], v[204:207], v[228:231], v[102:105]
	v_mfma_f32_16x16x32_bf16 v[98:101], v[212:215], v[228:231], v[98:101]
	v_mfma_f32_16x16x32_bf16 v[86:89], v[204:207], v[236:239], v[86:89]
	v_mfma_f32_16x16x32_bf16 v[82:85], v[212:215], v[236:239], v[82:85]
	v_mfma_f32_16x16x32_bf16 v[70:73], v[204:207], v[244:247], v[70:73]
	v_mfma_f32_16x16x32_bf16 v[66:69], v[212:215], v[244:247], v[66:69]
	s_barrier
; #define PG8_STAGE(bufoff, gbase, voff) do { _Pragma("unroll") for (int _i = 0; _i < 2; ++_i) \
;         __builtin_amdgcn_global_load_lds((const unsigned*)((const char*)(gbase) + (voff)[_i]), (PG8_LAS unsigned*)(lds + (bufoff) + ldsw + _i * 8192), 16, 0, 0); } while (0)
; #define PG8_LDA(dst, b, h) do { _Pragma("unroll") for (int m = 0; m < 4; ++m) _Pragma("unroll") for (int k = 0; k < 2; ++k) dst[m][k] = *(const PG8_LAS bf16x8*)(lds + PG8_SA(b, h) + aoff + m * 2048 + k * 1024); } while (0)
; #define PG8_MMA(ai, bj, At, Bt) do { __builtin_amdgcn_s_setprio(1); _Pragma("unroll") for (int m = 0; m < 4; ++m) _Pragma("unroll") for (int n = 0; n < 2; ++n) _Pragma("unroll") for (int k = 0; k < 2; ++k) \
;         acc[ai][bj][m][n] = __builtin_amdgcn_mfma_f32_16x16x32_bf16(Bt[n][k], At[m][k], acc[ai][bj][m][n], 0, 0, 0); __builtin_amdgcn_s_setprio(0); } while (0)
; #define PG8_WAIT_V(n) asm volatile("s_waitcnt vmcnt(" #n ")" ::: "memory")
; #define PG8_WAIT_L(n) asm volatile("s_waitcnt lgkmcnt(" #n ")" ::: "memory")
; #define PG8_BAR __builtin_amdgcn_s_barrier()
; #define PG8_SCHED __builtin_amdgcn_sched_barrier(0)
; template <class Epi, class Sched>
; __device__ __forceinline__ void gemm_phase(PG8_LAS unsigned char* lds, const int tid, const Gemm g, const Sched& S, const Epi& E) {
;     ...
;             PG8_LDA(At, 1, 1); PG8_STAGE(PG8_SB(1, 0), b3, voffB); PG8_STAGE(PG8_SB(1, 1), b3 + hstepB, voffB); PG8_STAGE(PG8_SA(1, 0), a3, voffA);
;             PG8_WAIT_V(8); PG8_WAIT_L(0); PG8_BAR; PG8_MMA(1, 0, At, B0); PG8_MMA(1, 1, At, B1); PG8_BAR; PG8_SCHED;
;         }
;         if constexpr (ALIGN_EPI) { if (wr == 0) PG8_BAR; }
	s_mov_b32 m0, s83
	v_lshl_add_u64 v[142:143], v[142:143], 0, s[54:55]
	s_add_u32 s34, s34, 0x40080
	ds_read_b128 v[216:219], v167 offset:49152
	ds_read_b128 v[220:223], v167 offset:50176
	ds_read_b128 v[224:227], v167 offset:51200
	ds_read_b128 v[228:231], v167 offset:52224
	ds_read_b128 v[232:235], v167 offset:53248
	ds_read_b128 v[236:239], v167 offset:54272
	ds_read_b128 v[240:243], v167 offset:55296
	ds_read_b128 v[244:247], v167 offset:56320
	global_load_lds_dwordx4 v[142:143], off
	v_lshl_add_u64 v[142:143], v[196:197], 0, s[54:55]
	s_mov_b32 m0, s84
	s_addc_u32 s35, s35, 0
	global_load_lds_dwordx4 v[142:143], off
	v_lshl_add_u64 v[142:143], s[34:35], 0, v[134:135]
	s_mov_b32 m0, s92
	s_nop 0
	global_load_lds_dwordx4 v[142:143], off
	v_lshl_add_u64 v[142:143], s[34:35], 0, v[130:131]
	s_mov_b32 m0, s93
	s_nop 0
	global_load_lds_dwordx4 v[142:143], off
	v_lshl_add_u64 v[142:143], v[248:249], 0, s[54:55]
	s_mov_b32 m0, s85
	s_nop 0
	global_load_lds_dwordx4 v[142:143], off
	v_lshl_add_u64 v[142:143], v[250:251], 0, s[54:55]
	s_mov_b32 m0, s86
	s_nop 0
	global_load_lds_dwordx4 v[142:143], off
	s_waitcnt vmcnt(8)
	s_waitcnt lgkmcnt(0)
	s_barrier
	s_waitcnt lgkmcnt(0)
	v_mfma_f32_16x16x32_bf16 v[62:65], v[168:171], v[216:219], v[62:65]
	v_mfma_f32_16x16x32_bf16 v[58:61], v[188:191], v[216:219], v[58:61]
	v_mfma_f32_16x16x32_bf16 v[46:49], v[168:171], v[224:227], v[46:49]
	v_mfma_f32_16x16x32_bf16 v[42:45], v[188:191], v[224:227], v[42:45]
	v_mfma_f32_16x16x32_bf16 v[30:33], v[168:171], v[232:235], v[30:33]
	v_mfma_f32_16x16x32_bf16 v[26:29], v[188:191], v[232:235], v[26:29]
	v_mfma_f32_16x16x32_bf16 v[14:17], v[168:171], v[240:243], v[14:17]
	v_mfma_f32_16x16x32_bf16 v[10:13], v[188:191], v[240:243], v[10:13]
	v_mfma_f32_16x16x32_bf16 v[62:65], v[184:187], v[220:223], v[62:65]
	v_mfma_f32_16x16x32_bf16 v[58:61], v[192:195], v[220:223], v[58:61]
	v_mfma_f32_16x16x32_bf16 v[46:49], v[184:187], v[228:231], v[46:49]
	v_mfma_f32_16x16x32_bf16 v[42:45], v[192:195], v[228:231], v[42:45]
	v_mfma_f32_16x16x32_bf16 v[30:33], v[184:187], v[236:239], v[30:33]
	v_mfma_f32_16x16x32_bf16 v[26:29], v[192:195], v[236:239], v[26:29]
	v_mfma_f32_16x16x32_bf16 v[14:17], v[184:187], v[244:247], v[14:17]
	v_mfma_f32_16x16x32_bf16 v[10:13], v[192:195], v[244:247], v[10:13]
	v_mfma_f32_16x16x32_bf16 v[54:57], v[200:203], v[216:219], v[54:57]
	v_mfma_f32_16x16x32_bf16 v[50:53], v[208:211], v[216:219], v[50:53]
	v_mfma_f32_16x16x32_bf16 v[38:41], v[200:203], v[224:227], v[38:41]
	v_mfma_f32_16x16x32_bf16 v[34:37], v[208:211], v[224:227], v[34:37]
	v_mfma_f32_16x16x32_bf16 v[22:25], v[200:203], v[232:235], v[22:25]
	v_mfma_f32_16x16x32_bf16 v[18:21], v[208:211], v[232:235], v[18:21]
	v_mfma_f32_16x16x32_bf16 v[6:9], v[200:203], v[240:243], v[6:9]
	v_mfma_f32_16x16x32_bf16 v[2:5], v[208:211], v[240:243], v[2:5]
	v_mfma_f32_16x16x32_bf16 v[54:57], v[204:207], v[220:223], v[54:57]
	v_mfma_f32_16x16x32_bf16 v[50:53], v[212:215], v[220:223], v[50:53]
	v_mfma_f32_16x16x32_bf16 v[38:41], v[204:207], v[228:231], v[38:41]
	v_mfma_f32_16x16x32_bf16 v[34:37], v[212:215], v[228:231], v[34:37]
	v_mfma_f32_16x16x32_bf16 v[22:25], v[204:207], v[236:239], v[22:25]
	v_mfma_f32_16x16x32_bf16 v[18:21], v[212:215], v[236:239], v[18:21]
	v_mfma_f32_16x16x32_bf16 v[6:9], v[204:207], v[244:247], v[6:9]
	v_mfma_f32_16x16x32_bf16 v[2:5], v[212:215], v[244:247], v[2:5]
	s_barrier
	s_add_i32 s39, s39, 2
	s_add_u32 vcc_lo, vcc_lo, 0x100
	s_addc_u32 vcc_hi, vcc_hi, 0
	s_add_u32 s2, s2, 0x100
	s_addc_u32 s3, s3, 0
	s_cmp_gt_u32 s39, 13
	s_cbranch_scc0 .LBB0_64
	s_and_b64 vcc, exec, s[14:15]
	s_cbranch_vccz .LBB0_67
	s_barrier

; #define PG8_STAGE(bufoff, gbase, voff) do { _Pragma("unroll") for (int _i = 0; _i < 2; ++_i) \
;         __builtin_amdgcn_global_load_lds((const unsigned*)((const char*)(gbase) + (voff)[_i]), (PG8_LAS unsigned*)(lds + (bufoff) + ldsw + _i * 8192), 16, 0, 0); } while (0)
; #define PG8_LDA(dst, b, h) do { _Pragma("unroll") for (int m = 0; m < 4; ++m) _Pragma("unroll") for (int k = 0; k < 2; ++k) dst[m][k] = *(const PG8_LAS bf16x8*)(lds + PG8_SA(b, h) + aoff + m * 2048 + k * 1024); } while (0)
; #define PG8_LDB(dst, b, h) do { _Pragma("unroll") for (int n = 0; n < 2; ++n) _Pragma("unroll") for (int k = 0; k < 2; ++k) dst[n][k] = *(const PG8_LAS bf16x8*)(lds + PG8_SB(b, h) + boff + n * 2048 + k * 1024); } while (0)
; #define PG8_MMA(ai, bj, At, Bt) do { __builtin_amdgcn_s_setprio(1); _Pragma("unroll") for (int m = 0; m < 4; ++m) _Pragma("unroll") for (int n = 0; n < 2; ++n) _Pragma("unroll") for (int k = 0; k < 2; ++k) \
;         acc[ai][bj][m][n] = __builtin_amdgcn_mfma_f32_16x16x32_bf16(Bt[n][k], At[m][k], acc[ai][bj][m][n], 0, 0, 0); __builtin_amdgcn_s_setprio(0); } while (0)
; #define PG8_WAIT_V(n) asm volatile("s_waitcnt vmcnt(" #n ")" ::: "memory")
; #define PG8_WAIT_L(n) asm volatile("s_waitcnt lgkmcnt(" #n ")" ::: "memory")
; #define PG8_BAR __builtin_amdgcn_s_barrier()
; #define PG8_SCHED __builtin_amdgcn_sched_barrier(0)
; template <class Epi, class Sched>
; __device__ __forceinline__ void gemm_phase(PG8_LAS unsigned char* lds, const int tid, const Gemm g, const Sched& S, const Epi& E) {
;     ...
;             const bool last = (t == nt - 2);
;             const char* a1 = cA + (size_t)(t + 1) * kstep;
;             const char* a2 = last ? nA : cA + (size_t)(t + 2) * kstep; const char* b2 = last ? nB : cB + (size_t)(t + 2) * kstep;
;             const char* a3 = a2 + kstep; const char* b3 = b2 + kstep;
;             if (last && has_next) S.a_ready(nxt);
;             PG8_LDB(B0, 0, 0); PG8_LDB(B1, 0, 1); PG8_SCHED; PG8_LDA(At, 0, 0); PG8_STAGE(PG8_SA(1, 1), a1 + hstepA, voffA);
;             PG8_WAIT_V(8); PG8_WAIT_L(0); PG8_BAR; PG8_MMA(0, 0, At, B0); PG8_MMA(0, 1, At, B1); PG8_BAR; PG8_SCHED;
;             PG8_LDA(At, 0, 1); PG8_STAGE(PG8_SB(0, 0), b2, voffB); PG8_STAGE(PG8_SB(0, 1), b2 + hstepB, voffB); PG8_STAGE(PG8_SA(0, 0), a2, voffA);
.LBB0_203:
	v_add_u32_e32 v142, s29, v150
	ds_read_b128 v[168:171], v142
	ds_read_b128 v[184:187], v142 offset:1024
	ds_read_b128 v[188:191], v142 offset:2048
	ds_read_b128 v[192:195], v142 offset:3072
	v_add_u32_e32 v142, s35, v150
	ds_read_b128 v[200:203], v142
	ds_read_b128 v[204:207], v142 offset:1024
	ds_read_b128 v[208:211], v142 offset:2048
	ds_read_b128 v[212:215], v142 offset:3072
	s_add_u32 s6, s2, 0x100
	s_addc_u32 s7, s3, 0
	s_cmp_eq_u32 vcc_lo, 2
	s_cselect_b32 s13, s19, s7
	s_cselect_b32 s12, s18, s6
	s_cselect_b32 s25, s21, s97
	s_cselect_b32 s24, s20, s36
	v_lshl_add_u64 v[142:143], s[2:3], 0, v[140:141]
	s_add_i32 m0, s44, 0xc000
	ds_read_b128 v[216:219], v167
	ds_read_b128 v[220:223], v167 offset:1024
	ds_read_b128 v[224:227], v167 offset:2048
	ds_read_b128 v[228:231], v167 offset:3072
	ds_read_b128 v[232:235], v167 offset:4096
	ds_read_b128 v[236:239], v167 offset:5120
	ds_read_b128 v[240:243], v167 offset:6144
	ds_read_b128 v[244:247], v167 offset:7168
	global_load_lds_dwordx4 v[142:143], off
	v_lshl_add_u64 v[142:143], s[2:3], 0, v[138:139]
	s_add_i32 m0, s44, 0xe000
	s_nop 0
	global_load_lds_dwordx4 v[142:143], off
	s_waitcnt vmcnt(8)
	s_waitcnt lgkmcnt(0)
	s_barrier
	s_waitcnt lgkmcnt(0)
	v_mfma_f32_16x16x32_bf16 v[126:129], v[168:171], v[216:219], v[126:129]
	v_mfma_f32_16x16x32_bf16 v[122:125], v[188:191], v[216:219], v[122:125]
	v_mfma_f32_16x16x32_bf16 v[118:121], v[168:171], v[224:227], v[118:121]
	v_mfma_f32_16x16x32_bf16 v[110:113], v[188:191], v[224:227], v[110:113]
	v_mfma_f32_16x16x32_bf16 v[102:105], v[168:171], v[232:235], v[102:105]
	v_mfma_f32_16x16x32_bf16 v[94:97], v[188:191], v[232:235], v[94:97]
	v_mfma_f32_16x16x32_bf16 v[86:89], v[168:171], v[240:243], v[86:89]
	v_mfma_f32_16x16x32_bf16 v[78:81], v[188:191], v[240:243], v[78:81]
	v_mfma_f32_16x16x32_bf16 v[126:129], v[184:187], v[220:223], v[126:129]
	v_mfma_f32_16x16x32_bf16 v[122:125], v[192:195], v[220:223], v[122:125]
	v_mfma_f32_16x16x32_bf16 v[118:121], v[184:187], v[228:231], v[118:121]
	v_mfma_f32_16x16x32_bf16 v[110:113], v[192:195], v[228:231], v[110:113]
	v_mfma_f32_16x16x32_bf16 v[102:105], v[184:187], v[236:239], v[102:105]
	v_mfma_f32_16x16x32_bf16 v[94:97], v[192:195], v[236:239], v[94:97]
	v_mfma_f32_16x16x32_bf16 v[86:89], v[184:187], v[244:247], v[86:89]
	v_mfma_f32_16x16x32_bf16 v[78:81], v[192:195], v[244:247], v[78:81]
	v_mfma_f32_16x16x32_bf16 v[114:117], v[200:203], v[216:219], v[114:117]
	v_mfma_f32_16x16x32_bf16 v[106:109], v[208:211], v[216:219], v[106:109]
	v_mfma_f32_16x16x32_bf16 v[98:101], v[200:203], v[224:227], v[98:101]
	v_mfma_f32_16x16x32_bf16 v[90:93], v[208:211], v[224:227], v[90:93]
	v_mfma_f32_16x16x32_bf16 v[82:85], v[200:203], v[232:235], v[82:85]
	v_mfma_f32_16x16x32_bf16 v[74:77], v[208:211], v[232:235], v[74:77]
	v_mfma_f32_16x16x32_bf16 v[70:73], v[200:203], v[240:243], v[70:73]
	v_mfma_f32_16x16x32_bf16 v[66:69], v[208:211], v[240:243], v[66:69]
	v_mfma_f32_16x16x32_bf16 v[114:117], v[204:207], v[220:223], v[114:117]
	v_mfma_f32_16x16x32_bf16 v[106:109], v[212:215], v[220:223], v[106:109]
	v_mfma_f32_16x16x32_bf16 v[98:101], v[204:207], v[228:231], v[98:101]
	v_mfma_f32_16x16x32_bf16 v[90:93], v[212:215], v[228:231], v[90:93]
	v_mfma_f32_16x16x32_bf16 v[82:85], v[204:207], v[236:239], v[82:85]
	v_mfma_f32_16x16x32_bf16 v[74:77], v[212:215], v[236:239], v[74:77]
	v_mfma_f32_16x16x32_bf16 v[70:73], v[204:207], v[244:247], v[70:73]
	v_mfma_f32_16x16x32_bf16 v[66:69], v[212:215], v[244:247], v[66:69]
	s_barrier
	s_mov_b32 m0, s31
	v_lshl_add_u64 v[142:143], s[24:25], 0, v[132:133]
	s_add_u32 s2, s24, 0x18000
	ds_read_b128 v[216:219], v167 offset:16384
	ds_read_b128 v[220:223], v167 offset:17408
	ds_read_b128 v[224:227], v167 offset:18432
	ds_read_b128 v[228:231], v167 offset:19456
	ds_read_b128 v[232:235], v167 offset:20480
	ds_read_b128 v[236:239], v167 offset:21504
	ds_read_b128 v[240:243], v167 offset:22528
	ds_read_b128 v[244:247], v167 offset:23552
	global_load_lds_dwordx4 v[142:143], off
	v_lshl_add_u64 v[196:197], s[24:25], 0, v[136:137]
	s_mov_b32 m0, s34
	s_addc_u32 s3, s25, 0
	global_load_lds_dwordx4 v[196:197], off
	v_lshl_add_u64 v[248:249], s[2:3], 0, v[132:133]
	s_mov_b32 m0, s40
	v_lshl_add_u64 v[250:251], s[12:13], 0, v[134:135]
	global_load_lds_dwordx4 v[248:249], off
	v_lshl_add_u64 v[248:249], s[2:3], 0, v[136:137]
	s_mov_b32 m0, s41
	s_nop 0
	global_load_lds_dwordx4 v[248:249], off
	v_lshl_add_u64 v[248:249], s[12:13], 0, v[130:131]
	s_mov_b32 m0, s44
	s_nop 0
	global_load_lds_dwordx4 v[248:249], off
	s_mov_b32 m0, s45
	s_nop 0
	global_load_lds_dwordx4 v[250:251], off
	s_waitcnt vmcnt(8)
	s_waitcnt lgkmcnt(0)
	s_barrier
; #define PG8_STAGE(bufoff, gbase, voff) do { _Pragma("unroll") for (int _i = 0; _i < 2; ++_i) \
;         __builtin_amdgcn_global_load_lds((const unsigned*)((const char*)(gbase) + (voff)[_i]), (PG8_LAS unsigned*)(lds + (bufoff) + ldsw + _i * 8192), 16, 0, 0); } while (0)
; #define PG8_LDA(dst, b, h) do { _Pragma("unroll") for (int m = 0; m < 4; ++m) _Pragma("unroll") for (int k = 0; k < 2; ++k) dst[m][k] = *(const PG8_LAS bf16x8*)(lds + PG8_SA(b, h) + aoff + m * 2048 + k * 1024); } while (0)
; #define PG8_LDB(dst, b, h) do { _Pragma("unroll") for (int n = 0; n < 2; ++n) _Pragma("unroll") for (int k = 0; k < 2; ++k) dst[n][k] = *(const PG8_LAS bf16x8*)(lds + PG8_SB(b, h) + boff + n * 2048 + k * 1024); } while (0)
; #define PG8_MMA(ai, bj, At, Bt) do { __builtin_amdgcn_s_setprio(1); _Pragma("unroll") for (int m = 0; m < 4; ++m) _Pragma("unroll") for (int n = 0; n < 2; ++n) _Pragma("unroll") for (int k = 0; k < 2; ++k) \
;         acc[ai][bj][m][n] = __builtin_amdgcn_mfma_f32_16x16x32_bf16(Bt[n][k], At[m][k], acc[ai][bj][m][n], 0, 0, 0); __builtin_amdgcn_s_setprio(0); } while (0)
; #define PG8_WAIT_V(n) asm volatile("s_waitcnt vmcnt(" #n ")" ::: "memory")
; #define PG8_WAIT_L(n) asm volatile("s_waitcnt lgkmcnt(" #n ")" ::: "memory")
; #define PG8_BAR __builtin_amdgcn_s_barrier()
; #define PG8_SCHED __builtin_amdgcn_sched_barrier(0)
; template <class Epi, class Sched>
; __device__ __forceinline__ void gemm_phase(PG8_LAS unsigned char* lds, const int tid, const Gemm g, const Sched& S, const Epi& E) {
;     ...
;             PG8_WAIT_V(8); PG8_WAIT_L(0); PG8_BAR; PG8_MMA(1, 0, At, B0); PG8_MMA(1, 1, At, B1); PG8_BAR; PG8_SCHED;
;             PG8_LDB(B0, 1, 0); PG8_LDB(B1, 1, 1); PG8_SCHED; PG8_LDA(At, 1, 0); PG8_STAGE(PG8_SA(0, 1), a2 + hstepA, voffA);
;             PG8_WAIT_V(8); PG8_WAIT_L(0); PG8_BAR; PG8_MMA(0, 0, At, B0); PG8_MMA(0, 1, At, B1); PG8_BAR; PG8_SCHED;
	s_waitcnt lgkmcnt(0)
	v_mfma_f32_16x16x32_bf16 v[62:65], v[168:171], v[216:219], v[62:65]
	v_mfma_f32_16x16x32_bf16 v[58:61], v[188:191], v[216:219], v[58:61]
	v_mfma_f32_16x16x32_bf16 v[54:57], v[168:171], v[224:227], v[54:57]
	v_mfma_f32_16x16x32_bf16 v[46:49], v[188:191], v[224:227], v[46:49]
	v_mfma_f32_16x16x32_bf16 v[38:41], v[168:171], v[232:235], v[38:41]
	v_mfma_f32_16x16x32_bf16 v[30:33], v[188:191], v[232:235], v[30:33]
	v_mfma_f32_16x16x32_bf16 v[22:25], v[168:171], v[240:243], v[22:25]
	v_mfma_f32_16x16x32_bf16 v[14:17], v[188:191], v[240:243], v[14:17]
	v_mfma_f32_16x16x32_bf16 v[62:65], v[184:187], v[220:223], v[62:65]
	v_mfma_f32_16x16x32_bf16 v[58:61], v[192:195], v[220:223], v[58:61]
	v_mfma_f32_16x16x32_bf16 v[54:57], v[184:187], v[228:231], v[54:57]
	v_mfma_f32_16x16x32_bf16 v[46:49], v[192:195], v[228:231], v[46:49]
	v_mfma_f32_16x16x32_bf16 v[38:41], v[184:187], v[236:239], v[38:41]
	v_mfma_f32_16x16x32_bf16 v[30:33], v[192:195], v[236:239], v[30:33]
	v_mfma_f32_16x16x32_bf16 v[22:25], v[184:187], v[244:247], v[22:25]
	v_mfma_f32_16x16x32_bf16 v[14:17], v[192:195], v[244:247], v[14:17]
	v_mfma_f32_16x16x32_bf16 v[50:53], v[200:203], v[216:219], v[50:53]
	v_mfma_f32_16x16x32_bf16 v[42:45], v[208:211], v[216:219], v[42:45]
	v_mfma_f32_16x16x32_bf16 v[34:37], v[200:203], v[224:227], v[34:37]
	v_mfma_f32_16x16x32_bf16 v[26:29], v[208:211], v[224:227], v[26:29]
	v_mfma_f32_16x16x32_bf16 v[18:21], v[200:203], v[232:235], v[18:21]
	v_mfma_f32_16x16x32_bf16 v[10:13], v[208:211], v[232:235], v[10:13]
	v_mfma_f32_16x16x32_bf16 v[6:9], v[200:203], v[240:243], v[6:9]
	v_mfma_f32_16x16x32_bf16 v[2:5], v[208:211], v[240:243], v[2:5]
	v_mfma_f32_16x16x32_bf16 v[50:53], v[204:207], v[220:223], v[50:53]
	v_mfma_f32_16x16x32_bf16 v[42:45], v[212:215], v[220:223], v[42:45]
	v_mfma_f32_16x16x32_bf16 v[34:37], v[204:207], v[228:231], v[34:37]
	v_mfma_f32_16x16x32_bf16 v[26:29], v[212:215], v[228:231], v[26:29]
	v_mfma_f32_16x16x32_bf16 v[18:21], v[204:207], v[236:239], v[18:21]
	v_mfma_f32_16x16x32_bf16 v[10:13], v[212:215], v[236:239], v[10:13]
	v_mfma_f32_16x16x32_bf16 v[6:9], v[204:207], v[244:247], v[6:9]
	v_mfma_f32_16x16x32_bf16 v[2:5], v[212:215], v[244:247], v[2:5]
	s_barrier
	v_add_u32_e32 v174, s58, v150
	ds_read_b128 v[168:171], v174
	ds_read_b128 v[184:187], v174 offset:1024
	ds_read_b128 v[188:191], v174 offset:2048
	ds_read_b128 v[192:195], v174 offset:3072
	v_add_u32_e32 v174, s81, v150
	ds_read_b128 v[200:203], v174
	ds_read_b128 v[204:207], v174 offset:1024
	ds_read_b128 v[208:211], v174 offset:2048
	ds_read_b128 v[212:215], v174 offset:3072
	s_add_u32 s2, s12, 0x18000
	s_addc_u32 s3, s13, 0
	s_mov_b32 m0, s48
	v_lshl_add_u64 v[252:253], s[2:3], 0, v[130:131]
	ds_read_b128 v[216:219], v167 offset:32768
	ds_read_b128 v[220:223], v167 offset:33792
	ds_read_b128 v[224:227], v167 offset:34816
	ds_read_b128 v[228:231], v167 offset:35840
	ds_read_b128 v[232:235], v167 offset:36864
	ds_read_b128 v[236:239], v167 offset:37888
	ds_read_b128 v[240:243], v167 offset:38912
	ds_read_b128 v[244:247], v167 offset:39936
	global_load_lds_dwordx4 v[252:253], off
	v_lshl_add_u64 v[252:253], s[2:3], 0, v[134:135]
	s_mov_b32 m0, s49
	s_nop 0
	global_load_lds_dwordx4 v[252:253], off
	s_waitcnt vmcnt(8)
	s_waitcnt lgkmcnt(0)
	s_barrier
	s_waitcnt lgkmcnt(0)
	v_mfma_f32_16x16x32_bf16 v[126:129], v[168:171], v[216:219], v[126:129]
	v_mfma_f32_16x16x32_bf16 v[122:125], v[188:191], v[216:219], v[122:125]
	v_mfma_f32_16x16x32_bf16 v[118:121], v[168:171], v[224:227], v[118:121]
	v_mfma_f32_16x16x32_bf16 v[110:113], v[188:191], v[224:227], v[110:113]
	v_mfma_f32_16x16x32_bf16 v[102:105], v[168:171], v[232:235], v[102:105]
	v_mfma_f32_16x16x32_bf16 v[94:97], v[188:191], v[232:235], v[94:97]
	v_mfma_f32_16x16x32_bf16 v[86:89], v[168:171], v[240:243], v[86:89]
	v_mfma_f32_16x16x32_bf16 v[78:81], v[188:191], v[240:243], v[78:81]
	v_mfma_f32_16x16x32_bf16 v[126:129], v[184:187], v[220:223], v[126:129]
	v_mfma_f32_16x16x32_bf16 v[122:125], v[192:195], v[220:223], v[122:125]
	v_mfma_f32_16x16x32_bf16 v[118:121], v[184:187], v[228:231], v[118:121]
	v_mfma_f32_16x16x32_bf16 v[110:113], v[192:195], v[228:231], v[110:113]
	v_mfma_f32_16x16x32_bf16 v[102:105], v[184:187], v[236:239], v[102:105]
	v_mfma_f32_16x16x32_bf16 v[94:97], v[192:195], v[236:239], v[94:97]
	v_mfma_f32_16x16x32_bf16 v[86:89], v[184:187], v[244:247], v[86:89]
	v_mfma_f32_16x16x32_bf16 v[78:81], v[192:195], v[244:247], v[78:81]
	v_mfma_f32_16x16x32_bf16 v[114:117], v[200:203], v[216:219], v[114:117]
	v_mfma_f32_16x16x32_bf16 v[106:109], v[208:211], v[216:219], v[106:109]
	v_mfma_f32_16x16x32_bf16 v[98:101], v[200:203], v[224:227], v[98:101]
	v_mfma_f32_16x16x32_bf16 v[90:93], v[208:211], v[224:227], v[90:93]
	v_mfma_f32_16x16x32_bf16 v[82:85], v[200:203], v[232:235], v[82:85]
	v_mfma_f32_16x16x32_bf16 v[74:77], v[208:211], v[232:235], v[74:77]
	v_mfma_f32_16x16x32_bf16 v[70:73], v[200:203], v[240:243], v[70:73]
	v_mfma_f32_16x16x32_bf16 v[66:69], v[208:211], v[240:243], v[66:69]
	v_mfma_f32_16x16x32_bf16 v[114:117], v[204:207], v[220:223], v[114:117]
	v_mfma_f32_16x16x32_bf16 v[106:109], v[212:215], v[220:223], v[106:109]
	v_mfma_f32_16x16x32_bf16 v[98:101], v[204:207], v[228:231], v[98:101]
	v_mfma_f32_16x16x32_bf16 v[90:93], v[212:215], v[228:231], v[90:93]
	v_mfma_f32_16x16x32_bf16 v[82:85], v[204:207], v[236:239], v[82:85]
	v_mfma_f32_16x16x32_bf16 v[74:77], v[212:215], v[236:239], v[74:77]
	v_mfma_f32_16x16x32_bf16 v[70:73], v[204:207], v[244:247], v[70:73]
	v_mfma_f32_16x16x32_bf16 v[66:69], v[212:215], v[244:247], v[66:69]
	s_barrier
; #define PG8_STAGE(bufoff, gbase, voff) do { _Pragma("unroll") for (int _i = 0; _i < 2; ++_i) \
;         __builtin_amdgcn_global_load_lds((const unsigned*)((const char*)(gbase) + (voff)[_i]), (PG8_LAS unsigned*)(lds + (bufoff) + ldsw + _i * 8192), 16, 0, 0); } while (0)
; #define PG8_LDA(dst, b, h) do { _Pragma("unroll") for (int m = 0; m < 4; ++m) _Pragma("unroll") for (int k = 0; k < 2; ++k) dst[m][k] = *(const PG8_LAS bf16x8*)(lds + PG8_SA(b, h) + aoff + m * 2048 + k * 1024); } while (0)
; #define PG8_MMA(ai, bj, At, Bt) do { __builtin_amdgcn_s_setprio(1); _Pragma("unroll") for (int m = 0; m < 4; ++m) _Pragma("unroll") for (int n = 0; n < 2; ++n) _Pragma("unroll") for (int k = 0; k < 2; ++k) \
;         acc[ai][bj][m][n] = __builtin_amdgcn_mfma_f32_16x16x32_bf16(Bt[n][k], At[m][k], acc[ai][bj][m][n], 0, 0, 0); __builtin_amdgcn_s_setprio(0); } while (0)
; #define PG8_WAIT_V(n) asm volatile("s_waitcnt vmcnt(" #n ")" ::: "memory")
; #define PG8_WAIT_L(n) asm volatile("s_waitcnt lgkmcnt(" #n ")" ::: "memory")
; #define PG8_BAR __builtin_amdgcn_s_barrier()
; #define PG8_SCHED __builtin_amdgcn_sched_barrier(0)
; template <class Epi, class Sched>
; __device__ __forceinline__ void gemm_phase(PG8_LAS unsigned char* lds, const int tid, const Gemm g, const Sched& S, const Epi& E) {
;     ...
;             PG8_LDA(At, 1, 1); PG8_STAGE(PG8_SB(1, 0), b3, voffB); PG8_STAGE(PG8_SB(1, 1), b3 + hstepB, voffB); PG8_STAGE(PG8_SA(1, 0), a3, voffA);
;             PG8_WAIT_V(8); PG8_WAIT_L(0); PG8_BAR; PG8_MMA(1, 0, At, B0); PG8_MMA(1, 1, At, B1); PG8_BAR; PG8_SCHED;
;         }
;         if constexpr (ALIGN_EPI) { if (wr == 0) PG8_BAR; }
	s_mov_b32 m0, s59
	v_lshl_add_u64 v[142:143], v[142:143], 0, s[54:55]
	s_add_u32 s2, s24, 0x18080
	ds_read_b128 v[216:219], v167 offset:49152
	ds_read_b128 v[220:223], v167 offset:50176
	ds_read_b128 v[224:227], v167 offset:51200
	ds_read_b128 v[228:231], v167 offset:52224
	ds_read_b128 v[232:235], v167 offset:53248
	ds_read_b128 v[236:239], v167 offset:54272
	ds_read_b128 v[240:243], v167 offset:55296
	ds_read_b128 v[244:247], v167 offset:56320
	global_load_lds_dwordx4 v[142:143], off
	v_lshl_add_u64 v[142:143], v[196:197], 0, s[54:55]
	s_mov_b32 m0, s72
	s_addc_u32 s3, s25, 0
	global_load_lds_dwordx4 v[142:143], off
	v_lshl_add_u64 v[142:143], s[2:3], 0, v[132:133]
	s_mov_b32 m0, s82
	s_nop 0
	global_load_lds_dwordx4 v[142:143], off
	v_lshl_add_u64 v[142:143], s[2:3], 0, v[136:137]
	s_mov_b32 m0, s83
	s_nop 0
	global_load_lds_dwordx4 v[142:143], off
	v_lshl_add_u64 v[142:143], v[248:249], 0, s[54:55]
	s_mov_b32 m0, s73
	s_nop 0
	global_load_lds_dwordx4 v[142:143], off
	v_lshl_add_u64 v[142:143], v[250:251], 0, s[54:55]
	s_mov_b32 m0, s80
	s_nop 0
	global_load_lds_dwordx4 v[142:143], off
	s_waitcnt vmcnt(8)
	s_waitcnt lgkmcnt(0)
	s_barrier
	s_waitcnt lgkmcnt(0)
	v_mfma_f32_16x16x32_bf16 v[62:65], v[168:171], v[216:219], v[62:65]
	v_mfma_f32_16x16x32_bf16 v[58:61], v[188:191], v[216:219], v[58:61]
	v_mfma_f32_16x16x32_bf16 v[54:57], v[168:171], v[224:227], v[54:57]
	v_mfma_f32_16x16x32_bf16 v[46:49], v[188:191], v[224:227], v[46:49]
	v_mfma_f32_16x16x32_bf16 v[38:41], v[168:171], v[232:235], v[38:41]
	v_mfma_f32_16x16x32_bf16 v[30:33], v[188:191], v[232:235], v[30:33]
	v_mfma_f32_16x16x32_bf16 v[22:25], v[168:171], v[240:243], v[22:25]
	v_mfma_f32_16x16x32_bf16 v[14:17], v[188:191], v[240:243], v[14:17]
	v_mfma_f32_16x16x32_bf16 v[62:65], v[184:187], v[220:223], v[62:65]
	v_mfma_f32_16x16x32_bf16 v[58:61], v[192:195], v[220:223], v[58:61]
	v_mfma_f32_16x16x32_bf16 v[54:57], v[184:187], v[228:231], v[54:57]
	v_mfma_f32_16x16x32_bf16 v[46:49], v[192:195], v[228:231], v[46:49]
	v_mfma_f32_16x16x32_bf16 v[38:41], v[184:187], v[236:239], v[38:41]
	v_mfma_f32_16x16x32_bf16 v[30:33], v[192:195], v[236:239], v[30:33]
	v_mfma_f32_16x16x32_bf16 v[22:25], v[184:187], v[244:247], v[22:25]
	v_mfma_f32_16x16x32_bf16 v[14:17], v[192:195], v[244:247], v[14:17]
	v_mfma_f32_16x16x32_bf16 v[50:53], v[200:203], v[216:219], v[50:53]
	v_mfma_f32_16x16x32_bf16 v[42:45], v[208:211], v[216:219], v[42:45]
	v_mfma_f32_16x16x32_bf16 v[34:37], v[200:203], v[224:227], v[34:37]
	v_mfma_f32_16x16x32_bf16 v[26:29], v[208:211], v[224:227], v[26:29]
	v_mfma_f32_16x16x32_bf16 v[18:21], v[200:203], v[232:235], v[18:21]
	v_mfma_f32_16x16x32_bf16 v[10:13], v[208:211], v[232:235], v[10:13]
	v_mfma_f32_16x16x32_bf16 v[6:9], v[200:203], v[240:243], v[6:9]
	v_mfma_f32_16x16x32_bf16 v[2:5], v[208:211], v[240:243], v[2:5]
	v_mfma_f32_16x16x32_bf16 v[50:53], v[204:207], v[220:223], v[50:53]
	v_mfma_f32_16x16x32_bf16 v[42:45], v[212:215], v[220:223], v[42:45]
	v_mfma_f32_16x16x32_bf16 v[34:37], v[204:207], v[228:231], v[34:37]
	v_mfma_f32_16x16x32_bf16 v[26:29], v[212:215], v[228:231], v[26:29]
	v_mfma_f32_16x16x32_bf16 v[18:21], v[204:207], v[236:239], v[18:21]
	v_mfma_f32_16x16x32_bf16 v[10:13], v[212:215], v[236:239], v[10:13]
	v_mfma_f32_16x16x32_bf16 v[6:9], v[204:207], v[244:247], v[6:9]
	v_mfma_f32_16x16x32_bf16 v[2:5], v[212:215], v[244:247], v[2:5]
	s_barrier
	s_add_i32 vcc_lo, vcc_lo, 2
	s_add_u32 s36, s36, 0x100
	s_addc_u32 s97, s97, 0
	s_cmp_gt_u32 vcc_lo, 3
	s_mov_b64 s[2:3], s[6:7]
	s_cbranch_scc0 .LBB0_203
	s_and_b64 vcc, exec, s[14:15]
	s_cbranch_vccz .LBB0_206
	s_barrier

; #define PG8_STAGE(bufoff, gbase, voff) do { _Pragma("unroll") for (int _i = 0; _i < 2; ++_i) \
;         __builtin_amdgcn_global_load_lds((const unsigned*)((const char*)(gbase) + (voff)[_i]), (PG8_LAS unsigned*)(lds + (bufoff) + ldsw + _i * 8192), 16, 0, 0); } while (0)
; #define PG8_LDA(dst, b, h) do { _Pragma("unroll") for (int m = 0; m < 4; ++m) _Pragma("unroll") for (int k = 0; k < 2; ++k) dst[m][k] = *(const PG8_LAS bf16x8*)(lds + PG8_SA(b, h) + aoff + m * 2048 + k * 1024); } while (0)
; #define PG8_LDB(dst, b, h) do { _Pragma("unroll") for (int n = 0; n < 2; ++n) _Pragma("unroll") for (int k = 0; k < 2; ++k) dst[n][k] = *(const PG8_LAS bf16x8*)(lds + PG8_SB(b, h) + boff + n * 2048 + k * 1024); } while (0)
; #define PG8_MMA(ai, bj, At, Bt) do { __builtin_amdgcn_s_setprio(1); _Pragma("unroll") for (int m = 0; m < 4; ++m) _Pragma("unroll") for (int n = 0; n < 2; ++n) _Pragma("unroll") for (int k = 0; k < 2; ++k) \
;         acc[ai][bj][m][n] = __builtin_amdgcn_mfma_f32_16x16x32_bf16(Bt[n][k], At[m][k], acc[ai][bj][m][n], 0, 0, 0); __builtin_amdgcn_s_setprio(0); } while (0)
; #define PG8_WAIT_V(n) asm volatile("s_waitcnt vmcnt(" #n ")" ::: "memory")
; #define PG8_WAIT_L(n) asm volatile("s_waitcnt lgkmcnt(" #n ")" ::: "memory")
; #define PG8_BAR __builtin_amdgcn_s_barrier()
; #define PG8_SCHED __builtin_amdgcn_sched_barrier(0)
; template <class Epi, class Sched>
; __device__ __forceinline__ void gemm_phase(PG8_LAS unsigned char* lds, const int tid, const Gemm g, const Sched& S, const Epi& E) {
;     ...
;             const bool last = (t == nt - 2);
;             const char* a1 = cA + (size_t)(t + 1) * kstep;
;             const char* a2 = last ? nA : cA + (size_t)(t + 2) * kstep; const char* b2 = last ? nB : cB + (size_t)(t + 2) * kstep;
;             const char* a3 = a2 + kstep; const char* b3 = b2 + kstep;
;             if (last && has_next) S.a_ready(nxt);
;             PG8_LDB(B0, 0, 0); PG8_LDB(B1, 0, 1); PG8_SCHED; PG8_LDA(At, 0, 0); PG8_STAGE(PG8_SA(1, 1), a1 + hstepA, voffA);
;             PG8_WAIT_V(8); PG8_WAIT_L(0); PG8_BAR; PG8_MMA(0, 0, At, B0); PG8_MMA(0, 1, At, B1); PG8_BAR; PG8_SCHED;
;             PG8_LDA(At, 0, 1); PG8_STAGE(PG8_SB(0, 0), b2, voffB); PG8_STAGE(PG8_SB(0, 1), b2 + hstepB, voffB); PG8_STAGE(PG8_SA(0, 0), a2, voffA);
.LBB0_255:
	v_add_u32_e32 v142, s21, v165
	ds_read_b128 v[184:187], v142
	ds_read_b128 v[188:191], v142 offset:1024
	ds_read_b128 v[192:195], v142 offset:2048
	ds_read_b128 v[200:203], v142 offset:3072
	v_add_u32_e32 v142, s41, v165
	ds_read_b128 v[204:207], v142
	ds_read_b128 v[208:211], v142 offset:1024
	ds_read_b128 v[212:215], v142 offset:2048
	ds_read_b128 v[216:219], v142 offset:3072
	s_add_u32 s6, s2, 0x100
	s_addc_u32 s7, s3, 0
	s_cmp_eq_u32 s96, 4
	s_cselect_b32 s13, s25, s7
	s_cselect_b32 s12, s24, s6
	s_cselect_b32 s35, s19, s95
	s_cselect_b32 s34, s36, s93
	v_lshl_add_u64 v[142:143], s[2:3], 0, v[140:141]
	s_add_i32 m0, s45, 0xc000
	ds_read_b128 v[220:223], v170
	ds_read_b128 v[224:227], v170 offset:1024
	ds_read_b128 v[228:231], v170 offset:2048
	ds_read_b128 v[232:235], v170 offset:3072
	ds_read_b128 v[236:239], v170 offset:4096
	ds_read_b128 v[240:243], v170 offset:5120
	ds_read_b128 v[244:247], v170 offset:6144
	ds_read_b128 v[248:251], v170 offset:7168
	global_load_lds_dwordx4 v[142:143], off
	v_lshl_add_u64 v[142:143], s[2:3], 0, v[138:139]
	s_add_i32 m0, s45, 0xe000
	s_nop 0
	global_load_lds_dwordx4 v[142:143], off
	s_waitcnt vmcnt(8)
	s_waitcnt lgkmcnt(0)
	s_barrier
	s_waitcnt lgkmcnt(0)
	v_mfma_f32_16x16x32_bf16 v[126:129], v[184:187], v[220:223], v[126:129]
	v_mfma_f32_16x16x32_bf16 v[122:125], v[192:195], v[220:223], v[122:125]
	v_mfma_f32_16x16x32_bf16 v[118:121], v[184:187], v[228:231], v[118:121]
	v_mfma_f32_16x16x32_bf16 v[110:113], v[192:195], v[228:231], v[110:113]
	v_mfma_f32_16x16x32_bf16 v[102:105], v[184:187], v[236:239], v[102:105]
	v_mfma_f32_16x16x32_bf16 v[94:97], v[192:195], v[236:239], v[94:97]
	v_mfma_f32_16x16x32_bf16 v[86:89], v[184:187], v[244:247], v[86:89]
	v_mfma_f32_16x16x32_bf16 v[78:81], v[192:195], v[244:247], v[78:81]
	v_mfma_f32_16x16x32_bf16 v[126:129], v[188:191], v[224:227], v[126:129]
	v_mfma_f32_16x16x32_bf16 v[122:125], v[200:203], v[224:227], v[122:125]
	v_mfma_f32_16x16x32_bf16 v[118:121], v[188:191], v[232:235], v[118:121]
	v_mfma_f32_16x16x32_bf16 v[110:113], v[200:203], v[232:235], v[110:113]
	v_mfma_f32_16x16x32_bf16 v[102:105], v[188:191], v[240:243], v[102:105]
	v_mfma_f32_16x16x32_bf16 v[94:97], v[200:203], v[240:243], v[94:97]
	v_mfma_f32_16x16x32_bf16 v[86:89], v[188:191], v[248:251], v[86:89]
	v_mfma_f32_16x16x32_bf16 v[78:81], v[200:203], v[248:251], v[78:81]
	v_mfma_f32_16x16x32_bf16 v[114:117], v[204:207], v[220:223], v[114:117]
	v_mfma_f32_16x16x32_bf16 v[106:109], v[212:215], v[220:223], v[106:109]
	v_mfma_f32_16x16x32_bf16 v[98:101], v[204:207], v[228:231], v[98:101]
	v_mfma_f32_16x16x32_bf16 v[90:93], v[212:215], v[228:231], v[90:93]
	v_mfma_f32_16x16x32_bf16 v[82:85], v[204:207], v[236:239], v[82:85]
	v_mfma_f32_16x16x32_bf16 v[74:77], v[212:215], v[236:239], v[74:77]
	v_mfma_f32_16x16x32_bf16 v[70:73], v[204:207], v[244:247], v[70:73]
	v_mfma_f32_16x16x32_bf16 v[66:69], v[212:215], v[244:247], v[66:69]
	v_mfma_f32_16x16x32_bf16 v[114:117], v[208:211], v[224:227], v[114:117]
	v_mfma_f32_16x16x32_bf16 v[106:109], v[216:219], v[224:227], v[106:109]
	v_mfma_f32_16x16x32_bf16 v[98:101], v[208:211], v[232:235], v[98:101]
	v_mfma_f32_16x16x32_bf16 v[90:93], v[216:219], v[232:235], v[90:93]
	v_mfma_f32_16x16x32_bf16 v[82:85], v[208:211], v[240:243], v[82:85]
	v_mfma_f32_16x16x32_bf16 v[74:77], v[216:219], v[240:243], v[74:77]
	v_mfma_f32_16x16x32_bf16 v[70:73], v[208:211], v[248:251], v[70:73]
	v_mfma_f32_16x16x32_bf16 v[66:69], v[216:219], v[248:251], v[66:69]
	s_barrier
	s_mov_b32 m0, s39
	v_lshl_add_u64 v[142:143], s[34:35], 0, v[132:133]
	s_add_u32 s2, s34, 0x20000
	ds_read_b128 v[220:223], v170 offset:16384
	ds_read_b128 v[224:227], v170 offset:17408
	ds_read_b128 v[228:231], v170 offset:18432
	ds_read_b128 v[232:235], v170 offset:19456
	ds_read_b128 v[236:239], v170 offset:20480
	ds_read_b128 v[240:243], v170 offset:21504
	ds_read_b128 v[244:247], v170 offset:22528
	ds_read_b128 v[248:251], v170 offset:23552
	global_load_lds_dwordx4 v[142:143], off
	v_lshl_add_u64 v[168:169], s[34:35], 0, v[136:137]
	s_mov_b32 m0, s40
	s_addc_u32 s3, s35, 0
	global_load_lds_dwordx4 v[168:169], off
	v_lshl_add_u64 v[196:197], s[2:3], 0, v[132:133]
	s_mov_b32 m0, s42
	v_lshl_add_u64 v[252:253], s[12:13], 0, v[134:135]
	global_load_lds_dwordx4 v[196:197], off
	v_lshl_add_u64 v[196:197], s[2:3], 0, v[136:137]
	s_mov_b32 m0, s44
	s_nop 0
	global_load_lds_dwordx4 v[196:197], off
	v_lshl_add_u64 v[196:197], s[12:13], 0, v[130:131]
	s_mov_b32 m0, s45
	s_nop 0
	global_load_lds_dwordx4 v[196:197], off
	s_mov_b32 m0, s48
	s_nop 0
	global_load_lds_dwordx4 v[252:253], off
	s_waitcnt vmcnt(8)
	s_waitcnt lgkmcnt(0)
	s_barrier
; #define PG8_STAGE(bufoff, gbase, voff) do { _Pragma("unroll") for (int _i = 0; _i < 2; ++_i) \
;         __builtin_amdgcn_global_load_lds((const unsigned*)((const char*)(gbase) + (voff)[_i]), (PG8_LAS unsigned*)(lds + (bufoff) + ldsw + _i * 8192), 16, 0, 0); } while (0)
; #define PG8_LDA(dst, b, h) do { _Pragma("unroll") for (int m = 0; m < 4; ++m) _Pragma("unroll") for (int k = 0; k < 2; ++k) dst[m][k] = *(const PG8_LAS bf16x8*)(lds + PG8_SA(b, h) + aoff + m * 2048 + k * 1024); } while (0)
; #define PG8_LDB(dst, b, h) do { _Pragma("unroll") for (int n = 0; n < 2; ++n) _Pragma("unroll") for (int k = 0; k < 2; ++k) dst[n][k] = *(const PG8_LAS bf16x8*)(lds + PG8_SB(b, h) + boff + n * 2048 + k * 1024); } while (0)
; #define PG8_MMA(ai, bj, At, Bt) do { __builtin_amdgcn_s_setprio(1); _Pragma("unroll") for (int m = 0; m < 4; ++m) _Pragma("unroll") for (int n = 0; n < 2; ++n) _Pragma("unroll") for (int k = 0; k < 2; ++k) \
;         acc[ai][bj][m][n] = __builtin_amdgcn_mfma_f32_16x16x32_bf16(Bt[n][k], At[m][k], acc[ai][bj][m][n], 0, 0, 0); __builtin_amdgcn_s_setprio(0); } while (0)
; #define PG8_WAIT_V(n) asm volatile("s_waitcnt vmcnt(" #n ")" ::: "memory")
; #define PG8_WAIT_L(n) asm volatile("s_waitcnt lgkmcnt(" #n ")" ::: "memory")
; #define PG8_BAR __builtin_amdgcn_s_barrier()
; #define PG8_SCHED __builtin_amdgcn_sched_barrier(0)
; template <class Epi, class Sched>
; __device__ __forceinline__ void gemm_phase(PG8_LAS unsigned char* lds, const int tid, const Gemm g, const Sched& S, const Epi& E) {
;     ...
;             PG8_WAIT_V(8); PG8_WAIT_L(0); PG8_BAR; PG8_MMA(1, 0, At, B0); PG8_MMA(1, 1, At, B1); PG8_BAR; PG8_SCHED;
;             PG8_LDB(B0, 1, 0); PG8_LDB(B1, 1, 1); PG8_SCHED; PG8_LDA(At, 1, 0); PG8_STAGE(PG8_SA(0, 1), a2 + hstepA, voffA);
;             PG8_WAIT_V(8); PG8_WAIT_L(0); PG8_BAR; PG8_MMA(0, 0, At, B0); PG8_MMA(0, 1, At, B1); PG8_BAR; PG8_SCHED;
	s_waitcnt lgkmcnt(0)
	v_mfma_f32_16x16x32_bf16 v[62:65], v[184:187], v[220:223], v[62:65]
	v_mfma_f32_16x16x32_bf16 v[58:61], v[192:195], v[220:223], v[58:61]
	v_mfma_f32_16x16x32_bf16 v[54:57], v[184:187], v[228:231], v[54:57]
	v_mfma_f32_16x16x32_bf16 v[46:49], v[192:195], v[228:231], v[46:49]
	v_mfma_f32_16x16x32_bf16 v[38:41], v[184:187], v[236:239], v[38:41]
	v_mfma_f32_16x16x32_bf16 v[30:33], v[192:195], v[236:239], v[30:33]
	v_mfma_f32_16x16x32_bf16 v[22:25], v[184:187], v[244:247], v[22:25]
	v_mfma_f32_16x16x32_bf16 v[14:17], v[192:195], v[244:247], v[14:17]
	v_mfma_f32_16x16x32_bf16 v[62:65], v[188:191], v[224:227], v[62:65]
	v_mfma_f32_16x16x32_bf16 v[58:61], v[200:203], v[224:227], v[58:61]
	v_mfma_f32_16x16x32_bf16 v[54:57], v[188:191], v[232:235], v[54:57]
	v_mfma_f32_16x16x32_bf16 v[46:49], v[200:203], v[232:235], v[46:49]
	v_mfma_f32_16x16x32_bf16 v[38:41], v[188:191], v[240:243], v[38:41]
	v_mfma_f32_16x16x32_bf16 v[30:33], v[200:203], v[240:243], v[30:33]
	v_mfma_f32_16x16x32_bf16 v[22:25], v[188:191], v[248:251], v[22:25]
	v_mfma_f32_16x16x32_bf16 v[14:17], v[200:203], v[248:251], v[14:17]
	v_mfma_f32_16x16x32_bf16 v[50:53], v[204:207], v[220:223], v[50:53]
	v_mfma_f32_16x16x32_bf16 v[42:45], v[212:215], v[220:223], v[42:45]
	v_mfma_f32_16x16x32_bf16 v[34:37], v[204:207], v[228:231], v[34:37]
	v_mfma_f32_16x16x32_bf16 v[26:29], v[212:215], v[228:231], v[26:29]
	v_mfma_f32_16x16x32_bf16 v[18:21], v[204:207], v[236:239], v[18:21]
	v_mfma_f32_16x16x32_bf16 v[10:13], v[212:215], v[236:239], v[10:13]
	v_mfma_f32_16x16x32_bf16 v[6:9], v[204:207], v[244:247], v[6:9]
	v_mfma_f32_16x16x32_bf16 v[2:5], v[212:215], v[244:247], v[2:5]
	v_mfma_f32_16x16x32_bf16 v[50:53], v[208:211], v[224:227], v[50:53]
	v_mfma_f32_16x16x32_bf16 v[42:45], v[216:219], v[224:227], v[42:45]
	v_mfma_f32_16x16x32_bf16 v[34:37], v[208:211], v[232:235], v[34:37]
	v_mfma_f32_16x16x32_bf16 v[26:29], v[216:219], v[232:235], v[26:29]
	v_mfma_f32_16x16x32_bf16 v[18:21], v[208:211], v[240:243], v[18:21]
	v_mfma_f32_16x16x32_bf16 v[10:13], v[216:219], v[240:243], v[10:13]
	v_mfma_f32_16x16x32_bf16 v[6:9], v[208:211], v[248:251], v[6:9]
	v_mfma_f32_16x16x32_bf16 v[2:5], v[216:219], v[248:251], v[2:5]
	s_barrier
	v_add_u32_e32 v171, s59, v165
	ds_read_b128 v[184:187], v171
	ds_read_b128 v[188:191], v171 offset:1024
	ds_read_b128 v[192:195], v171 offset:2048
	ds_read_b128 v[200:203], v171 offset:3072
	v_add_u32_e32 v171, s82, v165
	ds_read_b128 v[204:207], v171
	ds_read_b128 v[208:211], v171 offset:1024
	ds_read_b128 v[212:215], v171 offset:2048
	ds_read_b128 v[216:219], v171 offset:3072
	s_add_u32 s2, s12, 0x50000
	s_addc_u32 s3, s13, 0
	s_mov_b32 m0, s49
	v_lshl_add_u64 v[174:175], s[2:3], 0, v[130:131]
	ds_read_b128 v[220:223], v170 offset:32768
	ds_read_b128 v[224:227], v170 offset:33792
	ds_read_b128 v[228:231], v170 offset:34816
	ds_read_b128 v[232:235], v170 offset:35840
	ds_read_b128 v[236:239], v170 offset:36864
	ds_read_b128 v[240:243], v170 offset:37888
	ds_read_b128 v[244:247], v170 offset:38912
	ds_read_b128 v[248:251], v170 offset:39936
	global_load_lds_dwordx4 v[174:175], off
	v_lshl_add_u64 v[174:175], s[2:3], 0, v[134:135]
	s_mov_b32 m0, s58
	s_nop 0
	global_load_lds_dwordx4 v[174:175], off
	s_waitcnt vmcnt(8)
	s_waitcnt lgkmcnt(0)
	s_barrier
	s_waitcnt lgkmcnt(0)
	v_mfma_f32_16x16x32_bf16 v[126:129], v[184:187], v[220:223], v[126:129]
	v_mfma_f32_16x16x32_bf16 v[122:125], v[192:195], v[220:223], v[122:125]
	v_mfma_f32_16x16x32_bf16 v[118:121], v[184:187], v[228:231], v[118:121]
	v_mfma_f32_16x16x32_bf16 v[110:113], v[192:195], v[228:231], v[110:113]
	v_mfma_f32_16x16x32_bf16 v[102:105], v[184:187], v[236:239], v[102:105]
	v_mfma_f32_16x16x32_bf16 v[94:97], v[192:195], v[236:239], v[94:97]
	v_mfma_f32_16x16x32_bf16 v[86:89], v[184:187], v[244:247], v[86:89]
	v_mfma_f32_16x16x32_bf16 v[78:81], v[192:195], v[244:247], v[78:81]
	v_mfma_f32_16x16x32_bf16 v[126:129], v[188:191], v[224:227], v[126:129]
	v_mfma_f32_16x16x32_bf16 v[122:125], v[200:203], v[224:227], v[122:125]
	v_mfma_f32_16x16x32_bf16 v[118:121], v[188:191], v[232:235], v[118:121]
	v_mfma_f32_16x16x32_bf16 v[110:113], v[200:203], v[232:235], v[110:113]
	v_mfma_f32_16x16x32_bf16 v[102:105], v[188:191], v[240:243], v[102:105]
	v_mfma_f32_16x16x32_bf16 v[94:97], v[200:203], v[240:243], v[94:97]
	v_mfma_f32_16x16x32_bf16 v[86:89], v[188:191], v[248:251], v[86:89]
	v_mfma_f32_16x16x32_bf16 v[78:81], v[200:203], v[248:251], v[78:81]
	v_mfma_f32_16x16x32_bf16 v[114:117], v[204:207], v[220:223], v[114:117]
	v_mfma_f32_16x16x32_bf16 v[106:109], v[212:215], v[220:223], v[106:109]
	v_mfma_f32_16x16x32_bf16 v[98:101], v[204:207], v[228:231], v[98:101]
	v_mfma_f32_16x16x32_bf16 v[90:93], v[212:215], v[228:231], v[90:93]
	v_mfma_f32_16x16x32_bf16 v[82:85], v[204:207], v[236:239], v[82:85]
	v_mfma_f32_16x16x32_bf16 v[74:77], v[212:215], v[236:239], v[74:77]
	v_mfma_f32_16x16x32_bf16 v[70:73], v[204:207], v[244:247], v[70:73]
	v_mfma_f32_16x16x32_bf16 v[66:69], v[212:215], v[244:247], v[66:69]
	v_mfma_f32_16x16x32_bf16 v[114:117], v[208:211], v[224:227], v[114:117]
	v_mfma_f32_16x16x32_bf16 v[106:109], v[216:219], v[224:227], v[106:109]
	v_mfma_f32_16x16x32_bf16 v[98:101], v[208:211], v[232:235], v[98:101]
	v_mfma_f32_16x16x32_bf16 v[90:93], v[216:219], v[232:235], v[90:93]
	v_mfma_f32_16x16x32_bf16 v[82:85], v[208:211], v[240:243], v[82:85]
	v_mfma_f32_16x16x32_bf16 v[74:77], v[216:219], v[240:243], v[74:77]
	v_mfma_f32_16x16x32_bf16 v[70:73], v[208:211], v[248:251], v[70:73]
	v_mfma_f32_16x16x32_bf16 v[66:69], v[216:219], v[248:251], v[66:69]
	s_barrier
; #define PG8_STAGE(bufoff, gbase, voff) do { _Pragma("unroll") for (int _i = 0; _i < 2; ++_i) \
;         __builtin_amdgcn_global_load_lds((const unsigned*)((const char*)(gbase) + (voff)[_i]), (PG8_LAS unsigned*)(lds + (bufoff) + ldsw + _i * 8192), 16, 0, 0); } while (0)
; #define PG8_LDA(dst, b, h) do { _Pragma("unroll") for (int m = 0; m < 4; ++m) _Pragma("unroll") for (int k = 0; k < 2; ++k) dst[m][k] = *(const PG8_LAS bf16x8*)(lds + PG8_SA(b, h) + aoff + m * 2048 + k * 1024); } while (0)
; #define PG8_MMA(ai, bj, At, Bt) do { __builtin_amdgcn_s_setprio(1); _Pragma("unroll") for (int m = 0; m < 4; ++m) _Pragma("unroll") for (int n = 0; n < 2; ++n) _Pragma("unroll") for (int k = 0; k < 2; ++k) \
;         acc[ai][bj][m][n] = __builtin_amdgcn_mfma_f32_16x16x32_bf16(Bt[n][k], At[m][k], acc[ai][bj][m][n], 0, 0, 0); __builtin_amdgcn_s_setprio(0); } while (0)
; #define PG8_WAIT_V(n) asm volatile("s_waitcnt vmcnt(" #n ")" ::: "memory")
; #define PG8_WAIT_L(n) asm volatile("s_waitcnt lgkmcnt(" #n ")" ::: "memory")
; #define PG8_BAR __builtin_amdgcn_s_barrier()
; #define PG8_SCHED __builtin_amdgcn_sched_barrier(0)
; template <class Epi, class Sched>
; __device__ __forceinline__ void gemm_phase(PG8_LAS unsigned char* lds, const int tid, const Gemm g, const Sched& S, const Epi& E) {
;     ...
;             PG8_LDA(At, 1, 1); PG8_STAGE(PG8_SB(1, 0), b3, voffB); PG8_STAGE(PG8_SB(1, 1), b3 + hstepB, voffB); PG8_STAGE(PG8_SA(1, 0), a3, voffA);
;             PG8_WAIT_V(8); PG8_WAIT_L(0); PG8_BAR; PG8_MMA(1, 0, At, B0); PG8_MMA(1, 1, At, B1); PG8_BAR; PG8_SCHED;
;         }
;         if constexpr (ALIGN_EPI) { if (wr == 0) PG8_BAR; }
	s_mov_b32 m0, s72
	v_lshl_add_u64 v[142:143], v[142:143], 0, s[54:55]
	s_add_u32 s2, s34, 0x20080
	ds_read_b128 v[220:223], v170 offset:49152
	ds_read_b128 v[224:227], v170 offset:50176
	ds_read_b128 v[228:231], v170 offset:51200
	ds_read_b128 v[232:235], v170 offset:52224
	ds_read_b128 v[236:239], v170 offset:53248
	ds_read_b128 v[240:243], v170 offset:54272
	ds_read_b128 v[244:247], v170 offset:55296
	ds_read_b128 v[248:251], v170 offset:56320
	global_load_lds_dwordx4 v[142:143], off
	v_lshl_add_u64 v[142:143], v[168:169], 0, s[54:55]
	s_mov_b32 m0, s73
	s_addc_u32 s3, s35, 0
	global_load_lds_dwordx4 v[142:143], off
	v_lshl_add_u64 v[142:143], s[2:3], 0, v[132:133]
	s_mov_b32 m0, s83
	s_nop 0
	global_load_lds_dwordx4 v[142:143], off
	v_lshl_add_u64 v[142:143], s[2:3], 0, v[136:137]
	s_mov_b32 m0, s84
	s_nop 0
	global_load_lds_dwordx4 v[142:143], off
	v_lshl_add_u64 v[142:143], v[196:197], 0, s[54:55]
	s_mov_b32 m0, s80
	s_nop 0
	global_load_lds_dwordx4 v[142:143], off
	v_lshl_add_u64 v[142:143], v[252:253], 0, s[54:55]
	s_mov_b32 m0, s81
	s_nop 0
	global_load_lds_dwordx4 v[142:143], off
	s_waitcnt vmcnt(8)
	s_waitcnt lgkmcnt(0)
	s_barrier
	s_waitcnt lgkmcnt(0)
	v_mfma_f32_16x16x32_bf16 v[62:65], v[184:187], v[220:223], v[62:65]
	v_mfma_f32_16x16x32_bf16 v[58:61], v[192:195], v[220:223], v[58:61]
	v_mfma_f32_16x16x32_bf16 v[54:57], v[184:187], v[228:231], v[54:57]
	v_mfma_f32_16x16x32_bf16 v[46:49], v[192:195], v[228:231], v[46:49]
	v_mfma_f32_16x16x32_bf16 v[38:41], v[184:187], v[236:239], v[38:41]
	v_mfma_f32_16x16x32_bf16 v[30:33], v[192:195], v[236:239], v[30:33]
	v_mfma_f32_16x16x32_bf16 v[22:25], v[184:187], v[244:247], v[22:25]
	v_mfma_f32_16x16x32_bf16 v[14:17], v[192:195], v[244:247], v[14:17]
	v_mfma_f32_16x16x32_bf16 v[62:65], v[188:191], v[224:227], v[62:65]
	v_mfma_f32_16x16x32_bf16 v[58:61], v[200:203], v[224:227], v[58:61]
	v_mfma_f32_16x16x32_bf16 v[54:57], v[188:191], v[232:235], v[54:57]
	v_mfma_f32_16x16x32_bf16 v[46:49], v[200:203], v[232:235], v[46:49]
	v_mfma_f32_16x16x32_bf16 v[38:41], v[188:191], v[240:243], v[38:41]
	v_mfma_f32_16x16x32_bf16 v[30:33], v[200:203], v[240:243], v[30:33]
	v_mfma_f32_16x16x32_bf16 v[22:25], v[188:191], v[248:251], v[22:25]
	v_mfma_f32_16x16x32_bf16 v[14:17], v[200:203], v[248:251], v[14:17]
	v_mfma_f32_16x16x32_bf16 v[50:53], v[204:207], v[220:223], v[50:53]
	v_mfma_f32_16x16x32_bf16 v[42:45], v[212:215], v[220:223], v[42:45]
	v_mfma_f32_16x16x32_bf16 v[34:37], v[204:207], v[228:231], v[34:37]
	v_mfma_f32_16x16x32_bf16 v[26:29], v[212:215], v[228:231], v[26:29]
	v_mfma_f32_16x16x32_bf16 v[18:21], v[204:207], v[236:239], v[18:21]
	v_mfma_f32_16x16x32_bf16 v[10:13], v[212:215], v[236:239], v[10:13]
	v_mfma_f32_16x16x32_bf16 v[6:9], v[204:207], v[244:247], v[6:9]
	v_mfma_f32_16x16x32_bf16 v[2:5], v[212:215], v[244:247], v[2:5]
	v_mfma_f32_16x16x32_bf16 v[50:53], v[208:211], v[224:227], v[50:53]
	v_mfma_f32_16x16x32_bf16 v[42:45], v[216:219], v[224:227], v[42:45]
	v_mfma_f32_16x16x32_bf16 v[34:37], v[208:211], v[232:235], v[34:37]
	v_mfma_f32_16x16x32_bf16 v[26:29], v[216:219], v[232:235], v[26:29]
	v_mfma_f32_16x16x32_bf16 v[18:21], v[208:211], v[240:243], v[18:21]
	v_mfma_f32_16x16x32_bf16 v[10:13], v[216:219], v[240:243], v[10:13]
	v_mfma_f32_16x16x32_bf16 v[6:9], v[208:211], v[248:251], v[6:9]
	v_mfma_f32_16x16x32_bf16 v[2:5], v[216:219], v[248:251], v[2:5]
	s_barrier
	s_add_i32 s96, s96, 2
	s_add_u32 s93, s93, 0x100
	s_addc_u32 s95, s95, 0
	s_cmp_gt_u32 s96, 5
	s_mov_b64 s[2:3], s[6:7]
	s_cbranch_scc0 .LBB0_255
	s_and_b64 vcc, exec, s[14:15]
	s_cbranch_vccz .LBB0_258
	s_barrier

; #define PG8_STAGE(bufoff, gbase, voff) do { _Pragma("unroll") for (int _i = 0; _i < 2; ++_i) \
;         __builtin_amdgcn_global_load_lds((const unsigned*)((const char*)(gbase) + (voff)[_i]), (PG8_LAS unsigned*)(lds + (bufoff) + ldsw + _i * 8192), 16, 0, 0); } while (0)
; #define PG8_LDA(dst, b, h) do { _Pragma("unroll") for (int m = 0; m < 4; ++m) _Pragma("unroll") for (int k = 0; k < 2; ++k) dst[m][k] = *(const PG8_LAS bf16x8*)(lds + PG8_SA(b, h) + aoff + m * 2048 + k * 1024); } while (0)
; #define PG8_LDB(dst, b, h) do { _Pragma("unroll") for (int n = 0; n < 2; ++n) _Pragma("unroll") for (int k = 0; k < 2; ++k) dst[n][k] = *(const PG8_LAS bf16x8*)(lds + PG8_SB(b, h) + boff + n * 2048 + k * 1024); } while (0)
; #define PG8_MMA(ai, bj, At, Bt) do { __builtin_amdgcn_s_setprio(1); _Pragma("unroll") for (int m = 0; m < 4; ++m) _Pragma("unroll") for (int n = 0; n < 2; ++n) _Pragma("unroll") for (int k = 0; k < 2; ++k) \
;         acc[ai][bj][m][n] = __builtin_amdgcn_mfma_f32_16x16x32_bf16(Bt[n][k], At[m][k], acc[ai][bj][m][n], 0, 0, 0); __builtin_amdgcn_s_setprio(0); } while (0)
; #define PG8_WAIT_V(n) asm volatile("s_waitcnt vmcnt(" #n ")" ::: "memory")
; #define PG8_WAIT_L(n) asm volatile("s_waitcnt lgkmcnt(" #n ")" ::: "memory")
; template <class Epi, class Sched>
; __device__ __forceinline__ void gemm_phase(PG8_LAS unsigned char* lds, const int tid, const Gemm g, const Sched& S, const Epi& E) {
;     ...
;         const char* nA = has_next ? (const char*)g.A + (size_t)nxt.pm * tstepA : cA; const char* nB = has_next ? (const char*)g.Bt + (size_t)nxt.pn * tstepB : cB;
;         for (int t = 0; t < nt; t += 2) {
;             const bool last = (t == nt - 2);
;             const char* a1 = cA + (size_t)(t + 1) * kstep;
;             const char* a2 = last ? nA : cA + (size_t)(t + 2) * kstep; const char* b2 = last ? nB : cB + (size_t)(t + 2) * kstep;
;             const char* a3 = a2 + kstep; const char* b3 = b2 + kstep;
;             if (last && has_next) S.a_ready(nxt);
;             PG8_LDB(B0, 0, 0); PG8_LDB(B1, 0, 1); PG8_SCHED; PG8_LDA(At, 0, 0); PG8_STAGE(PG8_SA(1, 1), a1 + hstepA, voffA);
;             PG8_WAIT_V(8); PG8_WAIT_L(0); PG8_BAR; PG8_MMA(0, 0, At, B0); PG8_MMA(0, 1, At, B1); PG8_BAR; PG8_SCHED;
;             PG8_LDA(At, 0, 1); PG8_STAGE(PG8_SB(0, 0), b2, voffB); PG8_STAGE(PG8_SB(0, 1), b2 + hstepB, voffB); PG8_STAGE(PG8_SA(0, 0), a2, voffA);
.LBB0_307:
	s_add_u32 s35, s40, s34
	s_addc_u32 s62, s41, 0
	s_add_u32 s48, s35, 0x100
	s_addc_u32 s49, s62, 0
	s_and_b64 s[44:45], s[6:7], exec
	s_cselect_b32 s45, s21, s49
	s_cselect_b32 s44, s20, s48
	s_add_u32 s34, s26, s34
	s_addc_u32 s48, s27, 0
	s_add_u32 s34, s34, 0x100
	s_addc_u32 s48, s48, 0
	s_and_b64 s[6:7], s[6:7], exec
	v_add_u32_e32 v142, s19, v1
	s_cselect_b32 s49, s15, s48
	s_cselect_b32 s48, s36, s34
	s_add_u32 s80, s35, 0x50080
	ds_read_b128 v[138:141], v142
	ds_read_b128 v[168:171], v142 offset:1024
	ds_read_b128 v[184:187], v142 offset:2048
	ds_read_b128 v[188:191], v142 offset:3072
	v_add_u32_e32 v142, s39, v1
	s_addc_u32 s81, s62, 0
	s_add_i32 m0, s59, 0xc000
	s_add_i32 s62, s59, 0xe000
	ds_read_b128 v[192:195], v142
	ds_read_b128 v[200:203], v142 offset:1024
	ds_read_b128 v[204:207], v142 offset:2048
	ds_read_b128 v[208:211], v142 offset:3072
	s_add_u32 s72, s48, 0x10000
	s_addc_u32 s73, s49, 0
	s_add_u32 s34, s44, 0x50000
	s_addc_u32 s35, s45, 0
	s_add_u32 s6, s48, 0x10080
	s_addc_u32 s7, s49, 0
	v_lshl_add_u64 v[142:143], s[80:81], 0, v[130:131]
	ds_read_b128 v[212:215], v167
	ds_read_b128 v[216:219], v167 offset:1024
	ds_read_b128 v[220:223], v167 offset:2048
	ds_read_b128 v[224:227], v167 offset:3072
	ds_read_b128 v[228:231], v167 offset:4096
	ds_read_b128 v[232:235], v167 offset:5120
	ds_read_b128 v[236:239], v167 offset:6144
	ds_read_b128 v[240:243], v167 offset:7168
	global_load_lds_dwordx4 v[142:143], off
	v_lshl_add_u64 v[142:143], s[80:81], 0, v[134:135]
	s_mov_b32 m0, s62
	s_nop 0
	global_load_lds_dwordx4 v[142:143], off
	s_waitcnt vmcnt(8)
	s_waitcnt lgkmcnt(0)
	s_barrier
	s_waitcnt lgkmcnt(0)
	v_mfma_f32_16x16x32_bf16 v[126:129], v[138:141], v[212:215], v[126:129]
	v_mfma_f32_16x16x32_bf16 v[122:125], v[184:187], v[212:215], v[122:125]
	v_mfma_f32_16x16x32_bf16 v[114:117], v[138:141], v[220:223], v[114:117]
	v_mfma_f32_16x16x32_bf16 v[106:109], v[184:187], v[220:223], v[106:109]
	v_mfma_f32_16x16x32_bf16 v[102:105], v[138:141], v[228:231], v[102:105]
	v_mfma_f32_16x16x32_bf16 v[94:97], v[184:187], v[228:231], v[94:97]
	v_mfma_f32_16x16x32_bf16 v[86:89], v[138:141], v[236:239], v[86:89]
	v_mfma_f32_16x16x32_bf16 v[78:81], v[184:187], v[236:239], v[78:81]
	v_mfma_f32_16x16x32_bf16 v[126:129], v[168:171], v[216:219], v[126:129]
	v_mfma_f32_16x16x32_bf16 v[122:125], v[188:191], v[216:219], v[122:125]
	v_mfma_f32_16x16x32_bf16 v[114:117], v[168:171], v[224:227], v[114:117]
	v_mfma_f32_16x16x32_bf16 v[106:109], v[188:191], v[224:227], v[106:109]
	v_mfma_f32_16x16x32_bf16 v[102:105], v[168:171], v[232:235], v[102:105]
	v_mfma_f32_16x16x32_bf16 v[94:97], v[188:191], v[232:235], v[94:97]
	v_mfma_f32_16x16x32_bf16 v[86:89], v[168:171], v[240:243], v[86:89]
	v_mfma_f32_16x16x32_bf16 v[78:81], v[188:191], v[240:243], v[78:81]
	v_mfma_f32_16x16x32_bf16 v[118:121], v[192:195], v[212:215], v[118:121]
	v_mfma_f32_16x16x32_bf16 v[110:113], v[204:207], v[212:215], v[110:113]
	v_mfma_f32_16x16x32_bf16 v[98:101], v[192:195], v[220:223], v[98:101]
	v_mfma_f32_16x16x32_bf16 v[90:93], v[204:207], v[220:223], v[90:93]
	v_mfma_f32_16x16x32_bf16 v[82:85], v[192:195], v[228:231], v[82:85]
	v_mfma_f32_16x16x32_bf16 v[74:77], v[204:207], v[228:231], v[74:77]
	v_mfma_f32_16x16x32_bf16 v[70:73], v[192:195], v[236:239], v[70:73]
	v_mfma_f32_16x16x32_bf16 v[66:69], v[204:207], v[236:239], v[66:69]
	v_mfma_f32_16x16x32_bf16 v[118:121], v[200:203], v[216:219], v[118:121]
	v_mfma_f32_16x16x32_bf16 v[110:113], v[208:211], v[216:219], v[110:113]
	v_mfma_f32_16x16x32_bf16 v[98:101], v[200:203], v[224:227], v[98:101]
	v_mfma_f32_16x16x32_bf16 v[90:93], v[208:211], v[224:227], v[90:93]
	v_mfma_f32_16x16x32_bf16 v[82:85], v[200:203], v[232:235], v[82:85]
	v_mfma_f32_16x16x32_bf16 v[74:77], v[208:211], v[232:235], v[74:77]
	v_mfma_f32_16x16x32_bf16 v[70:73], v[200:203], v[240:243], v[70:73]
	v_mfma_f32_16x16x32_bf16 v[66:69], v[208:211], v[240:243], v[66:69]
	s_barrier
	s_mov_b32 m0, s29
	v_lshl_add_u64 v[142:143], s[48:49], 0, v[132:133]
	ds_read_b128 v[212:215], v167 offset:16384
	ds_read_b128 v[216:219], v167 offset:17408
	ds_read_b128 v[220:223], v167 offset:18432
	ds_read_b128 v[224:227], v167 offset:19456
	ds_read_b128 v[228:231], v167 offset:20480
	ds_read_b128 v[232:235], v167 offset:21504
	ds_read_b128 v[236:239], v167 offset:22528
	ds_read_b128 v[240:243], v167 offset:23552
	global_load_lds_dwordx4 v[142:143], off
	v_lshl_add_u64 v[174:175], s[48:49], 0, v[136:137]
	s_mov_b32 m0, s31
	v_lshl_add_u64 v[196:197], s[72:73], 0, v[132:133]
	global_load_lds_dwordx4 v[174:175], off
	s_mov_b32 m0, s42
	v_lshl_add_u64 v[244:245], s[44:45], 0, v[134:135]
	global_load_lds_dwordx4 v[196:197], off
	v_lshl_add_u64 v[196:197], s[72:73], 0, v[136:137]
	s_mov_b32 m0, s58
	s_nop 0
	global_load_lds_dwordx4 v[196:197], off
	v_lshl_add_u64 v[196:197], s[44:45], 0, v[130:131]
	s_mov_b32 m0, s59
	s_nop 0
	global_load_lds_dwordx4 v[196:197], off
	s_mov_b32 m0, s82
	s_nop 0
	global_load_lds_dwordx4 v[244:245], off
	s_waitcnt vmcnt(8)
	s_waitcnt lgkmcnt(0)
	s_barrier
; #define PG8_STAGE(bufoff, gbase, voff) do { _Pragma("unroll") for (int _i = 0; _i < 2; ++_i) \
;         __builtin_amdgcn_global_load_lds((const unsigned*)((const char*)(gbase) + (voff)[_i]), (PG8_LAS unsigned*)(lds + (bufoff) + ldsw + _i * 8192), 16, 0, 0); } while (0)
; #define PG8_LDA(dst, b, h) do { _Pragma("unroll") for (int m = 0; m < 4; ++m) _Pragma("unroll") for (int k = 0; k < 2; ++k) dst[m][k] = *(const PG8_LAS bf16x8*)(lds + PG8_SA(b, h) + aoff + m * 2048 + k * 1024); } while (0)
; #define PG8_LDB(dst, b, h) do { _Pragma("unroll") for (int n = 0; n < 2; ++n) _Pragma("unroll") for (int k = 0; k < 2; ++k) dst[n][k] = *(const PG8_LAS bf16x8*)(lds + PG8_SB(b, h) + boff + n * 2048 + k * 1024); } while (0)
; #define PG8_MMA(ai, bj, At, Bt) do { __builtin_amdgcn_s_setprio(1); _Pragma("unroll") for (int m = 0; m < 4; ++m) _Pragma("unroll") for (int n = 0; n < 2; ++n) _Pragma("unroll") for (int k = 0; k < 2; ++k) \
;         acc[ai][bj][m][n] = __builtin_amdgcn_mfma_f32_16x16x32_bf16(Bt[n][k], At[m][k], acc[ai][bj][m][n], 0, 0, 0); __builtin_amdgcn_s_setprio(0); } while (0)
; #define PG8_WAIT_V(n) asm volatile("s_waitcnt vmcnt(" #n ")" ::: "memory")
; #define PG8_WAIT_L(n) asm volatile("s_waitcnt lgkmcnt(" #n ")" ::: "memory")
; #define PG8_BAR __builtin_amdgcn_s_barrier()
; #define PG8_SCHED __builtin_amdgcn_sched_barrier(0)
; template <class Epi, class Sched>
; __device__ __forceinline__ void gemm_phase(PG8_LAS unsigned char* lds, const int tid, const Gemm g, const Sched& S, const Epi& E) {
;     ...
;             PG8_WAIT_V(8); PG8_WAIT_L(0); PG8_BAR; PG8_MMA(1, 0, At, B0); PG8_MMA(1, 1, At, B1); PG8_BAR; PG8_SCHED;
;             PG8_LDB(B0, 1, 0); PG8_LDB(B1, 1, 1); PG8_SCHED; PG8_LDA(At, 1, 0); PG8_STAGE(PG8_SA(0, 1), a2 + hstepA, voffA);
;             PG8_WAIT_V(8); PG8_WAIT_L(0); PG8_BAR; PG8_MMA(0, 0, At, B0); PG8_MMA(0, 1, At, B1); PG8_BAR; PG8_SCHED;
	s_waitcnt lgkmcnt(0)
	v_mfma_f32_16x16x32_bf16 v[62:65], v[138:141], v[212:215], v[62:65]
	v_mfma_f32_16x16x32_bf16 v[58:61], v[184:187], v[212:215], v[58:61]
	v_mfma_f32_16x16x32_bf16 v[54:57], v[138:141], v[220:223], v[54:57]
	v_mfma_f32_16x16x32_bf16 v[46:49], v[184:187], v[220:223], v[46:49]
	v_mfma_f32_16x16x32_bf16 v[38:41], v[138:141], v[228:231], v[38:41]
	v_mfma_f32_16x16x32_bf16 v[30:33], v[184:187], v[228:231], v[30:33]
	v_mfma_f32_16x16x32_bf16 v[22:25], v[138:141], v[236:239], v[22:25]
	v_mfma_f32_16x16x32_bf16 v[14:17], v[184:187], v[236:239], v[14:17]
	v_mfma_f32_16x16x32_bf16 v[62:65], v[168:171], v[216:219], v[62:65]
	v_mfma_f32_16x16x32_bf16 v[58:61], v[188:191], v[216:219], v[58:61]
	v_mfma_f32_16x16x32_bf16 v[54:57], v[168:171], v[224:227], v[54:57]
	v_mfma_f32_16x16x32_bf16 v[46:49], v[188:191], v[224:227], v[46:49]
	v_mfma_f32_16x16x32_bf16 v[38:41], v[168:171], v[232:235], v[38:41]
	v_mfma_f32_16x16x32_bf16 v[30:33], v[188:191], v[232:235], v[30:33]
	v_mfma_f32_16x16x32_bf16 v[22:25], v[168:171], v[240:243], v[22:25]
	v_mfma_f32_16x16x32_bf16 v[14:17], v[188:191], v[240:243], v[14:17]
	v_mfma_f32_16x16x32_bf16 v[50:53], v[192:195], v[212:215], v[50:53]
	v_mfma_f32_16x16x32_bf16 v[42:45], v[204:207], v[212:215], v[42:45]
	v_mfma_f32_16x16x32_bf16 v[34:37], v[192:195], v[220:223], v[34:37]
	v_mfma_f32_16x16x32_bf16 v[26:29], v[204:207], v[220:223], v[26:29]
	v_mfma_f32_16x16x32_bf16 v[18:21], v[192:195], v[228:231], v[18:21]
	v_mfma_f32_16x16x32_bf16 v[10:13], v[204:207], v[228:231], v[10:13]
	v_mfma_f32_16x16x32_bf16 v[6:9], v[192:195], v[236:239], v[6:9]
	v_mfma_f32_16x16x32_bf16 v[2:5], v[204:207], v[236:239], v[2:5]
	v_mfma_f32_16x16x32_bf16 v[50:53], v[200:203], v[216:219], v[50:53]
	v_mfma_f32_16x16x32_bf16 v[42:45], v[208:211], v[216:219], v[42:45]
	v_mfma_f32_16x16x32_bf16 v[34:37], v[200:203], v[224:227], v[34:37]
	v_mfma_f32_16x16x32_bf16 v[26:29], v[208:211], v[224:227], v[26:29]
	v_mfma_f32_16x16x32_bf16 v[18:21], v[200:203], v[232:235], v[18:21]
	v_mfma_f32_16x16x32_bf16 v[10:13], v[208:211], v[232:235], v[10:13]
	v_mfma_f32_16x16x32_bf16 v[6:9], v[200:203], v[240:243], v[6:9]
	v_mfma_f32_16x16x32_bf16 v[2:5], v[208:211], v[240:243], v[2:5]
	s_barrier
	v_add_u32_e32 v183, s85, v1
	ds_read_b128 v[138:141], v183
	ds_read_b128 v[168:171], v183 offset:1024
	ds_read_b128 v[184:187], v183 offset:2048
	ds_read_b128 v[188:191], v183 offset:3072
	v_add_u32_e32 v183, s95, v1
	ds_read_b128 v[192:195], v183
	ds_read_b128 v[200:203], v183 offset:1024
	ds_read_b128 v[204:207], v183 offset:2048
	ds_read_b128 v[208:211], v183 offset:3072
	s_mov_b32 m0, s83
	v_lshl_add_u64 v[246:247], s[34:35], 0, v[130:131]
	ds_read_b128 v[212:215], v167 offset:32768
	ds_read_b128 v[216:219], v167 offset:33792
	ds_read_b128 v[220:223], v167 offset:34816
	ds_read_b128 v[224:227], v167 offset:35840
	ds_read_b128 v[228:231], v167 offset:36864
	ds_read_b128 v[232:235], v167 offset:37888
	ds_read_b128 v[236:239], v167 offset:38912
	ds_read_b128 v[240:243], v167 offset:39936
	global_load_lds_dwordx4 v[246:247], off
	v_lshl_add_u64 v[246:247], s[34:35], 0, v[134:135]
	s_mov_b32 m0, s84
	s_nop 0
	global_load_lds_dwordx4 v[246:247], off
	s_waitcnt vmcnt(8)
	s_waitcnt lgkmcnt(0)
	s_barrier
	s_waitcnt lgkmcnt(0)
	v_mfma_f32_16x16x32_bf16 v[126:129], v[138:141], v[212:215], v[126:129]
	v_mfma_f32_16x16x32_bf16 v[122:125], v[184:187], v[212:215], v[122:125]
	v_mfma_f32_16x16x32_bf16 v[114:117], v[138:141], v[220:223], v[114:117]
	v_mfma_f32_16x16x32_bf16 v[106:109], v[184:187], v[220:223], v[106:109]
	v_mfma_f32_16x16x32_bf16 v[102:105], v[138:141], v[228:231], v[102:105]
	v_mfma_f32_16x16x32_bf16 v[94:97], v[184:187], v[228:231], v[94:97]
	v_mfma_f32_16x16x32_bf16 v[86:89], v[138:141], v[236:239], v[86:89]
	v_mfma_f32_16x16x32_bf16 v[78:81], v[184:187], v[236:239], v[78:81]
	v_mfma_f32_16x16x32_bf16 v[126:129], v[168:171], v[216:219], v[126:129]
	v_mfma_f32_16x16x32_bf16 v[122:125], v[188:191], v[216:219], v[122:125]
	v_mfma_f32_16x16x32_bf16 v[114:117], v[168:171], v[224:227], v[114:117]
	v_mfma_f32_16x16x32_bf16 v[106:109], v[188:191], v[224:227], v[106:109]
	v_mfma_f32_16x16x32_bf16 v[102:105], v[168:171], v[232:235], v[102:105]
	v_mfma_f32_16x16x32_bf16 v[94:97], v[188:191], v[232:235], v[94:97]
	v_mfma_f32_16x16x32_bf16 v[86:89], v[168:171], v[240:243], v[86:89]
	v_mfma_f32_16x16x32_bf16 v[78:81], v[188:191], v[240:243], v[78:81]
	v_mfma_f32_16x16x32_bf16 v[118:121], v[192:195], v[212:215], v[118:121]
	v_mfma_f32_16x16x32_bf16 v[110:113], v[204:207], v[212:215], v[110:113]
	v_mfma_f32_16x16x32_bf16 v[98:101], v[192:195], v[220:223], v[98:101]
	v_mfma_f32_16x16x32_bf16 v[90:93], v[204:207], v[220:223], v[90:93]
	v_mfma_f32_16x16x32_bf16 v[82:85], v[192:195], v[228:231], v[82:85]
	v_mfma_f32_16x16x32_bf16 v[74:77], v[204:207], v[228:231], v[74:77]
	v_mfma_f32_16x16x32_bf16 v[70:73], v[192:195], v[236:239], v[70:73]
	v_mfma_f32_16x16x32_bf16 v[66:69], v[204:207], v[236:239], v[66:69]
	v_mfma_f32_16x16x32_bf16 v[118:121], v[200:203], v[216:219], v[118:121]
	v_mfma_f32_16x16x32_bf16 v[110:113], v[208:211], v[216:219], v[110:113]
	v_mfma_f32_16x16x32_bf16 v[98:101], v[200:203], v[224:227], v[98:101]
	v_mfma_f32_16x16x32_bf16 v[90:93], v[208:211], v[224:227], v[90:93]
	v_mfma_f32_16x16x32_bf16 v[82:85], v[200:203], v[232:235], v[82:85]
	v_mfma_f32_16x16x32_bf16 v[74:77], v[208:211], v[232:235], v[74:77]
	v_mfma_f32_16x16x32_bf16 v[70:73], v[200:203], v[240:243], v[70:73]
	v_mfma_f32_16x16x32_bf16 v[66:69], v[208:211], v[240:243], v[66:69]
	s_barrier
; #define PG8_STAGE(bufoff, gbase, voff) do { _Pragma("unroll") for (int _i = 0; _i < 2; ++_i) \
;         __builtin_amdgcn_global_load_lds((const unsigned*)((const char*)(gbase) + (voff)[_i]), (PG8_LAS unsigned*)(lds + (bufoff) + ldsw + _i * 8192), 16, 0, 0); } while (0)
; #define PG8_LDA(dst, b, h) do { _Pragma("unroll") for (int m = 0; m < 4; ++m) _Pragma("unroll") for (int k = 0; k < 2; ++k) dst[m][k] = *(const PG8_LAS bf16x8*)(lds + PG8_SA(b, h) + aoff + m * 2048 + k * 1024); } while (0)
; #define PG8_MMA(ai, bj, At, Bt) do { __builtin_amdgcn_s_setprio(1); _Pragma("unroll") for (int m = 0; m < 4; ++m) _Pragma("unroll") for (int n = 0; n < 2; ++n) _Pragma("unroll") for (int k = 0; k < 2; ++k) \
;         acc[ai][bj][m][n] = __builtin_amdgcn_mfma_f32_16x16x32_bf16(Bt[n][k], At[m][k], acc[ai][bj][m][n], 0, 0, 0); __builtin_amdgcn_s_setprio(0); } while (0)
; #define PG8_WAIT_V(n) asm volatile("s_waitcnt vmcnt(" #n ")" ::: "memory")
; #define PG8_WAIT_L(n) asm volatile("s_waitcnt lgkmcnt(" #n ")" ::: "memory")
; #define PG8_BAR __builtin_amdgcn_s_barrier()
; #define PG8_SCHED __builtin_amdgcn_sched_barrier(0)
; template <class Epi, class Sched>
; __device__ __forceinline__ void gemm_phase(PG8_LAS unsigned char* lds, const int tid, const Gemm g, const Sched& S, const Epi& E) {
;     ...
;             PG8_LDA(At, 1, 1); PG8_STAGE(PG8_SB(1, 0), b3, voffB); PG8_STAGE(PG8_SB(1, 1), b3 + hstepB, voffB); PG8_STAGE(PG8_SA(1, 0), a3, voffA);
;             PG8_WAIT_V(8); PG8_WAIT_L(0); PG8_BAR; PG8_MMA(1, 0, At, B0); PG8_MMA(1, 1, At, B1); PG8_BAR; PG8_SCHED;
;         }
;         if constexpr (ALIGN_EPI) { if (wr == 0) PG8_BAR; }
	s_mov_b32 m0, s86
	v_lshl_add_u64 v[142:143], v[142:143], 0, s[54:55]
	ds_read_b128 v[212:215], v167 offset:49152
	ds_read_b128 v[216:219], v167 offset:50176
	ds_read_b128 v[220:223], v167 offset:51200
	ds_read_b128 v[224:227], v167 offset:52224
	ds_read_b128 v[228:231], v167 offset:53248
	ds_read_b128 v[232:235], v167 offset:54272
	ds_read_b128 v[236:239], v167 offset:55296
	ds_read_b128 v[240:243], v167 offset:56320
	global_load_lds_dwordx4 v[142:143], off
	v_lshl_add_u64 v[142:143], v[174:175], 0, s[54:55]
	s_mov_b32 m0, s87
	s_nop 0
	global_load_lds_dwordx4 v[142:143], off
	v_lshl_add_u64 v[142:143], s[6:7], 0, v[132:133]
	s_mov_b32 m0, s96
	s_nop 0
	global_load_lds_dwordx4 v[142:143], off
	v_lshl_add_u64 v[142:143], s[6:7], 0, v[136:137]
	s_mov_b32 m0, s97
	s_nop 0
	global_load_lds_dwordx4 v[142:143], off
	v_lshl_add_u64 v[142:143], v[196:197], 0, s[54:55]
	s_mov_b32 m0, s92
	s_nop 0
	global_load_lds_dwordx4 v[142:143], off
	v_lshl_add_u64 v[142:143], v[244:245], 0, s[54:55]
	s_mov_b32 m0, s93
	s_nop 0
	global_load_lds_dwordx4 v[142:143], off
	s_waitcnt vmcnt(8)
	s_waitcnt lgkmcnt(0)
	s_barrier
	s_waitcnt lgkmcnt(0)
	v_mfma_f32_16x16x32_bf16 v[62:65], v[138:141], v[212:215], v[62:65]
	v_mfma_f32_16x16x32_bf16 v[58:61], v[184:187], v[212:215], v[58:61]
	v_mfma_f32_16x16x32_bf16 v[54:57], v[138:141], v[220:223], v[54:57]
	v_mfma_f32_16x16x32_bf16 v[46:49], v[184:187], v[220:223], v[46:49]
	v_mfma_f32_16x16x32_bf16 v[38:41], v[138:141], v[228:231], v[38:41]
	v_mfma_f32_16x16x32_bf16 v[30:33], v[184:187], v[228:231], v[30:33]
	v_mfma_f32_16x16x32_bf16 v[22:25], v[138:141], v[236:239], v[22:25]
	v_mfma_f32_16x16x32_bf16 v[14:17], v[184:187], v[236:239], v[14:17]
	v_mfma_f32_16x16x32_bf16 v[62:65], v[168:171], v[216:219], v[62:65]
	v_mfma_f32_16x16x32_bf16 v[58:61], v[188:191], v[216:219], v[58:61]
	v_mfma_f32_16x16x32_bf16 v[54:57], v[168:171], v[224:227], v[54:57]
	v_mfma_f32_16x16x32_bf16 v[46:49], v[188:191], v[224:227], v[46:49]
	v_mfma_f32_16x16x32_bf16 v[38:41], v[168:171], v[232:235], v[38:41]
	v_mfma_f32_16x16x32_bf16 v[30:33], v[188:191], v[232:235], v[30:33]
	v_mfma_f32_16x16x32_bf16 v[22:25], v[168:171], v[240:243], v[22:25]
	v_mfma_f32_16x16x32_bf16 v[14:17], v[188:191], v[240:243], v[14:17]
	v_mfma_f32_16x16x32_bf16 v[50:53], v[192:195], v[212:215], v[50:53]
	v_mfma_f32_16x16x32_bf16 v[42:45], v[204:207], v[212:215], v[42:45]
	v_mfma_f32_16x16x32_bf16 v[34:37], v[192:195], v[220:223], v[34:37]
	v_mfma_f32_16x16x32_bf16 v[26:29], v[204:207], v[220:223], v[26:29]
	v_mfma_f32_16x16x32_bf16 v[18:21], v[192:195], v[228:231], v[18:21]
	v_mfma_f32_16x16x32_bf16 v[10:13], v[204:207], v[228:231], v[10:13]
	v_mfma_f32_16x16x32_bf16 v[6:9], v[192:195], v[236:239], v[6:9]
	v_mfma_f32_16x16x32_bf16 v[2:5], v[204:207], v[236:239], v[2:5]
	v_mfma_f32_16x16x32_bf16 v[50:53], v[200:203], v[216:219], v[50:53]
	v_mfma_f32_16x16x32_bf16 v[42:45], v[208:211], v[216:219], v[42:45]
	v_mfma_f32_16x16x32_bf16 v[34:37], v[200:203], v[224:227], v[34:37]
	v_mfma_f32_16x16x32_bf16 v[26:29], v[208:211], v[224:227], v[26:29]
	v_mfma_f32_16x16x32_bf16 v[18:21], v[200:203], v[232:235], v[18:21]
	v_mfma_f32_16x16x32_bf16 v[10:13], v[208:211], v[232:235], v[10:13]
	v_mfma_f32_16x16x32_bf16 v[6:9], v[200:203], v[240:243], v[6:9]
	v_mfma_f32_16x16x32_bf16 v[2:5], v[208:211], v[240:243], v[2:5]
	s_barrier
	s_movk_i32 s34, 0x100
	s_andn2_b64 vcc, exec, s[2:3]
	s_mov_b64 s[6:7], -1
	s_mov_b64 s[2:3], 0
	s_cbranch_vccz .LBB0_307
	s_and_b64 vcc, exec, s[10:11]
	s_cbranch_vccz .LBB0_310
	s_barrier

; #define PG8_STAGE(bufoff, gbase, voff) do { _Pragma("unroll") for (int _i = 0; _i < 2; ++_i) \
;         __builtin_amdgcn_global_load_lds((const unsigned*)((const char*)(gbase) + (voff)[_i]), (PG8_LAS unsigned*)(lds + (bufoff) + ldsw + _i * 8192), 16, 0, 0); } while (0)
; #define PG8_LDA(dst, b, h) do { _Pragma("unroll") for (int m = 0; m < 4; ++m) _Pragma("unroll") for (int k = 0; k < 2; ++k) dst[m][k] = *(const PG8_LAS bf16x8*)(lds + PG8_SA(b, h) + aoff + m * 2048 + k * 1024); } while (0)
; #define PG8_LDB(dst, b, h) do { _Pragma("unroll") for (int n = 0; n < 2; ++n) _Pragma("unroll") for (int k = 0; k < 2; ++k) dst[n][k] = *(const PG8_LAS bf16x8*)(lds + PG8_SB(b, h) + boff + n * 2048 + k * 1024); } while (0)
; #define PG8_MMA(ai, bj, At, Bt) do { __builtin_amdgcn_s_setprio(1); _Pragma("unroll") for (int m = 0; m < 4; ++m) _Pragma("unroll") for (int n = 0; n < 2; ++n) _Pragma("unroll") for (int k = 0; k < 2; ++k) \
;         acc[ai][bj][m][n] = __builtin_amdgcn_mfma_f32_16x16x32_bf16(Bt[n][k], At[m][k], acc[ai][bj][m][n], 0, 0, 0); __builtin_amdgcn_s_setprio(0); } while (0)
; #define PG8_WAIT_V(n) asm volatile("s_waitcnt vmcnt(" #n ")" ::: "memory")
; #define PG8_WAIT_L(n) asm volatile("s_waitcnt lgkmcnt(" #n ")" ::: "memory")
; #define PG8_BAR __builtin_amdgcn_s_barrier()
; #define PG8_SCHED __builtin_amdgcn_sched_barrier(0)
; template <class Epi, class Sched>
; __device__ __forceinline__ void gemm_phase(PG8_LAS unsigned char* lds, const int tid, const Gemm g, const Sched& S, const Epi& E) {
;     ...
;             const bool last = (t == nt - 2);
;             const char* a1 = cA + (size_t)(t + 1) * kstep;
;             const char* a2 = last ? nA : cA + (size_t)(t + 2) * kstep; const char* b2 = last ? nB : cB + (size_t)(t + 2) * kstep;
;             const char* a3 = a2 + kstep; const char* b3 = b2 + kstep;
;             if (last && has_next) S.a_ready(nxt);
;             PG8_LDB(B0, 0, 0); PG8_LDB(B1, 0, 1); PG8_SCHED; PG8_LDA(At, 0, 0); PG8_STAGE(PG8_SA(1, 1), a1 + hstepA, voffA);
;             PG8_WAIT_V(8); PG8_WAIT_L(0); PG8_BAR; PG8_MMA(0, 0, At, B0); PG8_MMA(0, 1, At, B1); PG8_BAR; PG8_SCHED;
;             PG8_LDA(At, 0, 1); PG8_STAGE(PG8_SB(0, 0), b2, voffB); PG8_STAGE(PG8_SB(0, 1), b2 + hstepB, voffB); PG8_STAGE(PG8_SA(0, 0), a2, voffA);
.LBB0_503:
	v_add_u32_e32 v142, s15, v150
	ds_read_b128 v[168:171], v142
	ds_read_b128 v[184:187], v142 offset:1024
	ds_read_b128 v[188:191], v142 offset:2048
	ds_read_b128 v[192:195], v142 offset:3072
	v_add_u32_e32 v142, s40, v150
	ds_read_b128 v[200:203], v142
	ds_read_b128 v[204:207], v142 offset:1024
	ds_read_b128 v[208:211], v142 offset:2048
	ds_read_b128 v[212:215], v142 offset:3072
	s_add_u32 s26, s2, 0xfffc0080
	s_addc_u32 s27, s3, -1
	s_cmp_eq_u32 s93, 12
	s_cselect_b32 s35, s19, s27
	s_cselect_b32 s34, s36, s26
	s_cselect_b32 s27, s13, s92
	s_cselect_b32 s26, s86, s87
	v_lshl_add_u64 v[142:143], s[2:3], 0, v[140:141]
	s_add_i32 m0, s44, 0xc000
	ds_read_b128 v[216:219], v167
	ds_read_b128 v[220:223], v167 offset:1024
	ds_read_b128 v[224:227], v167 offset:2048
	ds_read_b128 v[228:231], v167 offset:3072
	ds_read_b128 v[232:235], v167 offset:4096
	ds_read_b128 v[236:239], v167 offset:5120
	ds_read_b128 v[240:243], v167 offset:6144
	ds_read_b128 v[244:247], v167 offset:7168
	global_load_lds_dwordx4 v[142:143], off
	v_lshl_add_u64 v[142:143], s[2:3], 0, v[138:139]
	s_add_i32 m0, s44, 0xe000
	s_nop 0
	global_load_lds_dwordx4 v[142:143], off
	s_waitcnt vmcnt(8)
	s_waitcnt lgkmcnt(0)
	s_barrier
	s_waitcnt lgkmcnt(0)
	v_mfma_f32_16x16x32_bf16 v[126:129], v[168:171], v[216:219], v[126:129]
	v_mfma_f32_16x16x32_bf16 v[122:125], v[188:191], v[216:219], v[122:125]
	v_mfma_f32_16x16x32_bf16 v[118:121], v[168:171], v[224:227], v[118:121]
	v_mfma_f32_16x16x32_bf16 v[114:117], v[188:191], v[224:227], v[114:117]
	v_mfma_f32_16x16x32_bf16 v[110:113], v[168:171], v[232:235], v[110:113]
	v_mfma_f32_16x16x32_bf16 v[106:109], v[188:191], v[232:235], v[106:109]
	v_mfma_f32_16x16x32_bf16 v[102:105], v[168:171], v[240:243], v[102:105]
	v_mfma_f32_16x16x32_bf16 v[98:101], v[188:191], v[240:243], v[98:101]
	v_mfma_f32_16x16x32_bf16 v[126:129], v[184:187], v[220:223], v[126:129]
	v_mfma_f32_16x16x32_bf16 v[122:125], v[192:195], v[220:223], v[122:125]
	v_mfma_f32_16x16x32_bf16 v[118:121], v[184:187], v[228:231], v[118:121]
	v_mfma_f32_16x16x32_bf16 v[114:117], v[192:195], v[228:231], v[114:117]
	v_mfma_f32_16x16x32_bf16 v[110:113], v[184:187], v[236:239], v[110:113]
	v_mfma_f32_16x16x32_bf16 v[106:109], v[192:195], v[236:239], v[106:109]
	v_mfma_f32_16x16x32_bf16 v[102:105], v[184:187], v[244:247], v[102:105]
	v_mfma_f32_16x16x32_bf16 v[98:101], v[192:195], v[244:247], v[98:101]
	v_mfma_f32_16x16x32_bf16 v[70:73], v[200:203], v[216:219], v[70:73]
	v_mfma_f32_16x16x32_bf16 v[66:69], v[208:211], v[216:219], v[66:69]
	v_mfma_f32_16x16x32_bf16 v[54:57], v[200:203], v[224:227], v[54:57]
	v_mfma_f32_16x16x32_bf16 v[50:53], v[208:211], v[224:227], v[50:53]
	v_mfma_f32_16x16x32_bf16 v[46:49], v[200:203], v[232:235], v[46:49]
	v_mfma_f32_16x16x32_bf16 v[42:45], v[208:211], v[232:235], v[42:45]
	v_mfma_f32_16x16x32_bf16 v[38:41], v[200:203], v[240:243], v[38:41]
	v_mfma_f32_16x16x32_bf16 v[34:37], v[208:211], v[240:243], v[34:37]
	v_mfma_f32_16x16x32_bf16 v[70:73], v[204:207], v[220:223], v[70:73]
	v_mfma_f32_16x16x32_bf16 v[66:69], v[212:215], v[220:223], v[66:69]
	v_mfma_f32_16x16x32_bf16 v[54:57], v[204:207], v[228:231], v[54:57]
	v_mfma_f32_16x16x32_bf16 v[50:53], v[212:215], v[228:231], v[50:53]
	v_mfma_f32_16x16x32_bf16 v[46:49], v[204:207], v[236:239], v[46:49]
	v_mfma_f32_16x16x32_bf16 v[42:45], v[212:215], v[236:239], v[42:45]
	v_mfma_f32_16x16x32_bf16 v[38:41], v[204:207], v[244:247], v[38:41]
	v_mfma_f32_16x16x32_bf16 v[34:37], v[212:215], v[244:247], v[34:37]
	s_barrier
	s_mov_b32 m0, s31
	v_lshl_add_u64 v[142:143], s[26:27], 0, v[134:135]
	s_add_u32 s62, s26, 0x40000
	ds_read_b128 v[216:219], v167 offset:16384
	ds_read_b128 v[220:223], v167 offset:17408
	ds_read_b128 v[224:227], v167 offset:18432
	ds_read_b128 v[228:231], v167 offset:19456
	ds_read_b128 v[232:235], v167 offset:20480
	ds_read_b128 v[236:239], v167 offset:21504
	ds_read_b128 v[240:243], v167 offset:22528
	ds_read_b128 v[244:247], v167 offset:23552
	global_load_lds_dwordx4 v[142:143], off
	v_lshl_add_u64 v[196:197], s[26:27], 0, v[130:131]
	s_mov_b32 m0, s39
	s_addc_u32 s63, s27, 0
	global_load_lds_dwordx4 v[196:197], off
	v_lshl_add_u64 v[248:249], s[62:63], 0, v[134:135]
	s_mov_b32 m0, s41
	v_lshl_add_u64 v[250:251], s[34:35], 0, v[132:133]
	global_load_lds_dwordx4 v[248:249], off
	v_lshl_add_u64 v[248:249], s[62:63], 0, v[130:131]
	s_mov_b32 m0, s42
	s_nop 0
	global_load_lds_dwordx4 v[248:249], off
	v_lshl_add_u64 v[248:249], s[34:35], 0, v[136:137]
	s_mov_b32 m0, s44
	s_nop 0
	global_load_lds_dwordx4 v[248:249], off
	s_mov_b32 m0, s45
	s_nop 0
	global_load_lds_dwordx4 v[250:251], off
	s_waitcnt vmcnt(8)
	s_waitcnt lgkmcnt(0)
	s_barrier
; #define PG8_STAGE(bufoff, gbase, voff) do { _Pragma("unroll") for (int _i = 0; _i < 2; ++_i) \
;         __builtin_amdgcn_global_load_lds((const unsigned*)((const char*)(gbase) + (voff)[_i]), (PG8_LAS unsigned*)(lds + (bufoff) + ldsw + _i * 8192), 16, 0, 0); } while (0)
; #define PG8_LDA(dst, b, h) do { _Pragma("unroll") for (int m = 0; m < 4; ++m) _Pragma("unroll") for (int k = 0; k < 2; ++k) dst[m][k] = *(const PG8_LAS bf16x8*)(lds + PG8_SA(b, h) + aoff + m * 2048 + k * 1024); } while (0)
; #define PG8_LDB(dst, b, h) do { _Pragma("unroll") for (int n = 0; n < 2; ++n) _Pragma("unroll") for (int k = 0; k < 2; ++k) dst[n][k] = *(const PG8_LAS bf16x8*)(lds + PG8_SB(b, h) + boff + n * 2048 + k * 1024); } while (0)
; #define PG8_MMA(ai, bj, At, Bt) do { __builtin_amdgcn_s_setprio(1); _Pragma("unroll") for (int m = 0; m < 4; ++m) _Pragma("unroll") for (int n = 0; n < 2; ++n) _Pragma("unroll") for (int k = 0; k < 2; ++k) \
;         acc[ai][bj][m][n] = __builtin_amdgcn_mfma_f32_16x16x32_bf16(Bt[n][k], At[m][k], acc[ai][bj][m][n], 0, 0, 0); __builtin_amdgcn_s_setprio(0); } while (0)
; #define PG8_WAIT_V(n) asm volatile("s_waitcnt vmcnt(" #n ")" ::: "memory")
; #define PG8_WAIT_L(n) asm volatile("s_waitcnt lgkmcnt(" #n ")" ::: "memory")
; #define PG8_BAR __builtin_amdgcn_s_barrier()
; #define PG8_SCHED __builtin_amdgcn_sched_barrier(0)
; template <class Epi, class Sched>
; __device__ __forceinline__ void gemm_phase(PG8_LAS unsigned char* lds, const int tid, const Gemm g, const Sched& S, const Epi& E) {
;     ...
;             PG8_WAIT_V(8); PG8_WAIT_L(0); PG8_BAR; PG8_MMA(1, 0, At, B0); PG8_MMA(1, 1, At, B1); PG8_BAR; PG8_SCHED;
;             PG8_LDB(B0, 1, 0); PG8_LDB(B1, 1, 1); PG8_SCHED; PG8_LDA(At, 1, 0); PG8_STAGE(PG8_SA(0, 1), a2 + hstepA, voffA);
;             PG8_WAIT_V(8); PG8_WAIT_L(0); PG8_BAR; PG8_MMA(0, 0, At, B0); PG8_MMA(0, 1, At, B1); PG8_BAR; PG8_SCHED;
	s_waitcnt lgkmcnt(0)
	v_mfma_f32_16x16x32_bf16 v[94:97], v[168:171], v[216:219], v[94:97]
	v_mfma_f32_16x16x32_bf16 v[90:93], v[188:191], v[216:219], v[90:93]
	v_mfma_f32_16x16x32_bf16 v[86:89], v[168:171], v[224:227], v[86:89]
	v_mfma_f32_16x16x32_bf16 v[82:85], v[188:191], v[224:227], v[82:85]
	v_mfma_f32_16x16x32_bf16 v[78:81], v[168:171], v[232:235], v[78:81]
	v_mfma_f32_16x16x32_bf16 v[74:77], v[188:191], v[232:235], v[74:77]
	v_mfma_f32_16x16x32_bf16 v[62:65], v[168:171], v[240:243], v[62:65]
	v_mfma_f32_16x16x32_bf16 v[58:61], v[188:191], v[240:243], v[58:61]
	v_mfma_f32_16x16x32_bf16 v[94:97], v[184:187], v[220:223], v[94:97]
	v_mfma_f32_16x16x32_bf16 v[90:93], v[192:195], v[220:223], v[90:93]
	v_mfma_f32_16x16x32_bf16 v[86:89], v[184:187], v[228:231], v[86:89]
	v_mfma_f32_16x16x32_bf16 v[82:85], v[192:195], v[228:231], v[82:85]
	v_mfma_f32_16x16x32_bf16 v[78:81], v[184:187], v[236:239], v[78:81]
	v_mfma_f32_16x16x32_bf16 v[74:77], v[192:195], v[236:239], v[74:77]
	v_mfma_f32_16x16x32_bf16 v[62:65], v[184:187], v[244:247], v[62:65]
	v_mfma_f32_16x16x32_bf16 v[58:61], v[192:195], v[244:247], v[58:61]
	v_mfma_f32_16x16x32_bf16 v[30:33], v[200:203], v[216:219], v[30:33]
	v_mfma_f32_16x16x32_bf16 v[26:29], v[208:211], v[216:219], v[26:29]
	v_mfma_f32_16x16x32_bf16 v[22:25], v[200:203], v[224:227], v[22:25]
	v_mfma_f32_16x16x32_bf16 v[18:21], v[208:211], v[224:227], v[18:21]
	v_mfma_f32_16x16x32_bf16 v[14:17], v[200:203], v[232:235], v[14:17]
	v_mfma_f32_16x16x32_bf16 v[10:13], v[208:211], v[232:235], v[10:13]
	v_mfma_f32_16x16x32_bf16 v[6:9], v[200:203], v[240:243], v[6:9]
	v_mfma_f32_16x16x32_bf16 v[2:5], v[208:211], v[240:243], v[2:5]
	v_mfma_f32_16x16x32_bf16 v[30:33], v[204:207], v[220:223], v[30:33]
	v_mfma_f32_16x16x32_bf16 v[26:29], v[212:215], v[220:223], v[26:29]
	v_mfma_f32_16x16x32_bf16 v[22:25], v[204:207], v[228:231], v[22:25]
	v_mfma_f32_16x16x32_bf16 v[18:21], v[212:215], v[228:231], v[18:21]
	v_mfma_f32_16x16x32_bf16 v[14:17], v[204:207], v[236:239], v[14:17]
	v_mfma_f32_16x16x32_bf16 v[10:13], v[212:215], v[236:239], v[10:13]
	v_mfma_f32_16x16x32_bf16 v[6:9], v[204:207], v[244:247], v[6:9]
	v_mfma_f32_16x16x32_bf16 v[2:5], v[212:215], v[244:247], v[2:5]
	s_barrier
	v_add_u32_e32 v174, s58, v150
	ds_read_b128 v[168:171], v174
	ds_read_b128 v[184:187], v174 offset:1024
	ds_read_b128 v[188:191], v174 offset:2048
	ds_read_b128 v[192:195], v174 offset:3072
	v_add_u32_e32 v174, s81, v150
	ds_read_b128 v[200:203], v174
	ds_read_b128 v[204:207], v174 offset:1024
	ds_read_b128 v[208:211], v174 offset:2048
	ds_read_b128 v[212:215], v174 offset:3072
	s_add_u32 s34, s34, 0x40000
	s_addc_u32 s35, s35, 0
	s_mov_b32 m0, s48
	v_lshl_add_u64 v[252:253], s[34:35], 0, v[136:137]
	ds_read_b128 v[216:219], v167 offset:32768
	ds_read_b128 v[220:223], v167 offset:33792
	ds_read_b128 v[224:227], v167 offset:34816
	ds_read_b128 v[228:231], v167 offset:35840
	ds_read_b128 v[232:235], v167 offset:36864
	ds_read_b128 v[236:239], v167 offset:37888
	ds_read_b128 v[240:243], v167 offset:38912
	ds_read_b128 v[244:247], v167 offset:39936
	global_load_lds_dwordx4 v[252:253], off
	v_lshl_add_u64 v[252:253], s[34:35], 0, v[132:133]
	s_mov_b32 m0, s49
	s_nop 0
	global_load_lds_dwordx4 v[252:253], off
	s_waitcnt vmcnt(8)
	s_waitcnt lgkmcnt(0)
	s_barrier
	s_waitcnt lgkmcnt(0)
	v_mfma_f32_16x16x32_bf16 v[126:129], v[168:171], v[216:219], v[126:129]
	v_mfma_f32_16x16x32_bf16 v[122:125], v[188:191], v[216:219], v[122:125]
	v_mfma_f32_16x16x32_bf16 v[118:121], v[168:171], v[224:227], v[118:121]
	v_mfma_f32_16x16x32_bf16 v[114:117], v[188:191], v[224:227], v[114:117]
	v_mfma_f32_16x16x32_bf16 v[110:113], v[168:171], v[232:235], v[110:113]
	v_mfma_f32_16x16x32_bf16 v[106:109], v[188:191], v[232:235], v[106:109]
	v_mfma_f32_16x16x32_bf16 v[102:105], v[168:171], v[240:243], v[102:105]
	v_mfma_f32_16x16x32_bf16 v[98:101], v[188:191], v[240:243], v[98:101]
	v_mfma_f32_16x16x32_bf16 v[126:129], v[184:187], v[220:223], v[126:129]
	v_mfma_f32_16x16x32_bf16 v[122:125], v[192:195], v[220:223], v[122:125]
	v_mfma_f32_16x16x32_bf16 v[118:121], v[184:187], v[228:231], v[118:121]
	v_mfma_f32_16x16x32_bf16 v[114:117], v[192:195], v[228:231], v[114:117]
	v_mfma_f32_16x16x32_bf16 v[110:113], v[184:187], v[236:239], v[110:113]
	v_mfma_f32_16x16x32_bf16 v[106:109], v[192:195], v[236:239], v[106:109]
	v_mfma_f32_16x16x32_bf16 v[102:105], v[184:187], v[244:247], v[102:105]
	v_mfma_f32_16x16x32_bf16 v[98:101], v[192:195], v[244:247], v[98:101]
	v_mfma_f32_16x16x32_bf16 v[70:73], v[200:203], v[216:219], v[70:73]
	v_mfma_f32_16x16x32_bf16 v[66:69], v[208:211], v[216:219], v[66:69]
	v_mfma_f32_16x16x32_bf16 v[54:57], v[200:203], v[224:227], v[54:57]
	v_mfma_f32_16x16x32_bf16 v[50:53], v[208:211], v[224:227], v[50:53]
	v_mfma_f32_16x16x32_bf16 v[46:49], v[200:203], v[232:235], v[46:49]
	v_mfma_f32_16x16x32_bf16 v[42:45], v[208:211], v[232:235], v[42:45]
	v_mfma_f32_16x16x32_bf16 v[38:41], v[200:203], v[240:243], v[38:41]
	v_mfma_f32_16x16x32_bf16 v[34:37], v[208:211], v[240:243], v[34:37]
	v_mfma_f32_16x16x32_bf16 v[70:73], v[204:207], v[220:223], v[70:73]
	v_mfma_f32_16x16x32_bf16 v[66:69], v[212:215], v[220:223], v[66:69]
	v_mfma_f32_16x16x32_bf16 v[54:57], v[204:207], v[228:231], v[54:57]
	v_mfma_f32_16x16x32_bf16 v[50:53], v[212:215], v[228:231], v[50:53]
	v_mfma_f32_16x16x32_bf16 v[46:49], v[204:207], v[236:239], v[46:49]
	v_mfma_f32_16x16x32_bf16 v[42:45], v[212:215], v[236:239], v[42:45]
	v_mfma_f32_16x16x32_bf16 v[38:41], v[204:207], v[244:247], v[38:41]
	v_mfma_f32_16x16x32_bf16 v[34:37], v[212:215], v[244:247], v[34:37]
	s_barrier
; #define PG8_STAGE(bufoff, gbase, voff) do { _Pragma("unroll") for (int _i = 0; _i < 2; ++_i) \
;         __builtin_amdgcn_global_load_lds((const unsigned*)((const char*)(gbase) + (voff)[_i]), (PG8_LAS unsigned*)(lds + (bufoff) + ldsw + _i * 8192), 16, 0, 0); } while (0)
; #define PG8_LDA(dst, b, h) do { _Pragma("unroll") for (int m = 0; m < 4; ++m) _Pragma("unroll") for (int k = 0; k < 2; ++k) dst[m][k] = *(const PG8_LAS bf16x8*)(lds + PG8_SA(b, h) + aoff + m * 2048 + k * 1024); } while (0)
; #define PG8_MMA(ai, bj, At, Bt) do { __builtin_amdgcn_s_setprio(1); _Pragma("unroll") for (int m = 0; m < 4; ++m) _Pragma("unroll") for (int n = 0; n < 2; ++n) _Pragma("unroll") for (int k = 0; k < 2; ++k) \
;         acc[ai][bj][m][n] = __builtin_amdgcn_mfma_f32_16x16x32_bf16(Bt[n][k], At[m][k], acc[ai][bj][m][n], 0, 0, 0); __builtin_amdgcn_s_setprio(0); } while (0)
; #define PG8_WAIT_V(n) asm volatile("s_waitcnt vmcnt(" #n ")" ::: "memory")
; #define PG8_WAIT_L(n) asm volatile("s_waitcnt lgkmcnt(" #n ")" ::: "memory")
; #define PG8_BAR __builtin_amdgcn_s_barrier()
; #define PG8_SCHED __builtin_amdgcn_sched_barrier(0)
; template <class Epi, class Sched>
; __device__ __forceinline__ void gemm_phase(PG8_LAS unsigned char* lds, const int tid, const Gemm g, const Sched& S, const Epi& E) {
;     ...
;             PG8_LDA(At, 1, 1); PG8_STAGE(PG8_SB(1, 0), b3, voffB); PG8_STAGE(PG8_SB(1, 1), b3 + hstepB, voffB); PG8_STAGE(PG8_SA(1, 0), a3, voffA);
;             PG8_WAIT_V(8); PG8_WAIT_L(0); PG8_BAR; PG8_MMA(1, 0, At, B0); PG8_MMA(1, 1, At, B1); PG8_BAR; PG8_SCHED;
;         }
;         if constexpr (ALIGN_EPI) { if (wr == 0) PG8_BAR; }
	s_mov_b32 m0, s59
	v_lshl_add_u64 v[142:143], v[142:143], 0, s[54:55]
	s_add_u32 s26, s26, 0x40080
	ds_read_b128 v[216:219], v167 offset:49152
	ds_read_b128 v[220:223], v167 offset:50176
	ds_read_b128 v[224:227], v167 offset:51200
	ds_read_b128 v[228:231], v167 offset:52224
	ds_read_b128 v[232:235], v167 offset:53248
	ds_read_b128 v[236:239], v167 offset:54272
	ds_read_b128 v[240:243], v167 offset:55296
	ds_read_b128 v[244:247], v167 offset:56320
	global_load_lds_dwordx4 v[142:143], off
	v_lshl_add_u64 v[142:143], v[196:197], 0, s[54:55]
	s_mov_b32 m0, s72
	s_addc_u32 s27, s27, 0
	global_load_lds_dwordx4 v[142:143], off
	v_lshl_add_u64 v[142:143], s[26:27], 0, v[134:135]
	s_mov_b32 m0, s82
	s_nop 0
	global_load_lds_dwordx4 v[142:143], off
	v_lshl_add_u64 v[142:143], s[26:27], 0, v[130:131]
	s_mov_b32 m0, s83
	s_nop 0
	global_load_lds_dwordx4 v[142:143], off
	v_lshl_add_u64 v[142:143], v[248:249], 0, s[54:55]
	s_mov_b32 m0, s73
	s_nop 0
	global_load_lds_dwordx4 v[142:143], off
	v_lshl_add_u64 v[142:143], v[250:251], 0, s[54:55]
	s_mov_b32 m0, s80
	s_nop 0
	global_load_lds_dwordx4 v[142:143], off
	s_waitcnt vmcnt(8)
	s_waitcnt lgkmcnt(0)
	s_barrier
	s_waitcnt lgkmcnt(0)
	v_mfma_f32_16x16x32_bf16 v[94:97], v[168:171], v[216:219], v[94:97]
	v_mfma_f32_16x16x32_bf16 v[90:93], v[188:191], v[216:219], v[90:93]
	v_mfma_f32_16x16x32_bf16 v[86:89], v[168:171], v[224:227], v[86:89]
	v_mfma_f32_16x16x32_bf16 v[82:85], v[188:191], v[224:227], v[82:85]
	v_mfma_f32_16x16x32_bf16 v[78:81], v[168:171], v[232:235], v[78:81]
	v_mfma_f32_16x16x32_bf16 v[74:77], v[188:191], v[232:235], v[74:77]
	v_mfma_f32_16x16x32_bf16 v[62:65], v[168:171], v[240:243], v[62:65]
	v_mfma_f32_16x16x32_bf16 v[58:61], v[188:191], v[240:243], v[58:61]
	v_mfma_f32_16x16x32_bf16 v[94:97], v[184:187], v[220:223], v[94:97]
	v_mfma_f32_16x16x32_bf16 v[90:93], v[192:195], v[220:223], v[90:93]
	v_mfma_f32_16x16x32_bf16 v[86:89], v[184:187], v[228:231], v[86:89]
	v_mfma_f32_16x16x32_bf16 v[82:85], v[192:195], v[228:231], v[82:85]
	v_mfma_f32_16x16x32_bf16 v[78:81], v[184:187], v[236:239], v[78:81]
	v_mfma_f32_16x16x32_bf16 v[74:77], v[192:195], v[236:239], v[74:77]
	v_mfma_f32_16x16x32_bf16 v[62:65], v[184:187], v[244:247], v[62:65]
	v_mfma_f32_16x16x32_bf16 v[58:61], v[192:195], v[244:247], v[58:61]
	v_mfma_f32_16x16x32_bf16 v[30:33], v[200:203], v[216:219], v[30:33]
	v_mfma_f32_16x16x32_bf16 v[26:29], v[208:211], v[216:219], v[26:29]
	v_mfma_f32_16x16x32_bf16 v[22:25], v[200:203], v[224:227], v[22:25]
	v_mfma_f32_16x16x32_bf16 v[18:21], v[208:211], v[224:227], v[18:21]
	v_mfma_f32_16x16x32_bf16 v[14:17], v[200:203], v[232:235], v[14:17]
	v_mfma_f32_16x16x32_bf16 v[10:13], v[208:211], v[232:235], v[10:13]
	v_mfma_f32_16x16x32_bf16 v[6:9], v[200:203], v[240:243], v[6:9]
	v_mfma_f32_16x16x32_bf16 v[2:5], v[208:211], v[240:243], v[2:5]
	v_mfma_f32_16x16x32_bf16 v[30:33], v[204:207], v[220:223], v[30:33]
	v_mfma_f32_16x16x32_bf16 v[26:29], v[212:215], v[220:223], v[26:29]
	v_mfma_f32_16x16x32_bf16 v[22:25], v[204:207], v[228:231], v[22:25]
	v_mfma_f32_16x16x32_bf16 v[18:21], v[212:215], v[228:231], v[18:21]
	v_mfma_f32_16x16x32_bf16 v[14:17], v[204:207], v[236:239], v[14:17]
	v_mfma_f32_16x16x32_bf16 v[10:13], v[212:215], v[236:239], v[10:13]
	v_mfma_f32_16x16x32_bf16 v[6:9], v[204:207], v[244:247], v[6:9]
	v_mfma_f32_16x16x32_bf16 v[2:5], v[212:215], v[244:247], v[2:5]
	s_barrier
	s_add_i32 s93, s93, 2
	s_add_u32 s87, s87, 0x100
	s_addc_u32 s92, s92, 0
	s_add_u32 s2, s2, 0x100
	s_addc_u32 s3, s3, 0
	s_cmp_gt_u32 s93, 13
	s_cbranch_scc0 .LBB0_503
	s_and_b64 vcc, exec, s[10:11]
	s_cbranch_vccz .LBB0_506
	s_barrier

; #define PG8_STAGE(bufoff, gbase, voff) do { _Pragma("unroll") for (int _i = 0; _i < 2; ++_i) \
;         __builtin_amdgcn_global_load_lds((const unsigned*)((const char*)(gbase) + (voff)[_i]), (PG8_LAS unsigned*)(lds + (bufoff) + ldsw + _i * 8192), 16, 0, 0); } while (0)
; #define PG8_LDA(dst, b, h) do { _Pragma("unroll") for (int m = 0; m < 4; ++m) _Pragma("unroll") for (int k = 0; k < 2; ++k) dst[m][k] = *(const PG8_LAS bf16x8*)(lds + PG8_SA(b, h) + aoff + m * 2048 + k * 1024); } while (0)
; #define PG8_LDB(dst, b, h) do { _Pragma("unroll") for (int n = 0; n < 2; ++n) _Pragma("unroll") for (int k = 0; k < 2; ++k) dst[n][k] = *(const PG8_LAS bf16x8*)(lds + PG8_SB(b, h) + boff + n * 2048 + k * 1024); } while (0)
; #define PG8_MMA(ai, bj, At, Bt) do { __builtin_amdgcn_s_setprio(1); _Pragma("unroll") for (int m = 0; m < 4; ++m) _Pragma("unroll") for (int n = 0; n < 2; ++n) _Pragma("unroll") for (int k = 0; k < 2; ++k) \
;         acc[ai][bj][m][n] = __builtin_amdgcn_mfma_f32_16x16x32_bf16(Bt[n][k], At[m][k], acc[ai][bj][m][n], 0, 0, 0); __builtin_amdgcn_s_setprio(0); } while (0)
; #define PG8_WAIT_V(n) asm volatile("s_waitcnt vmcnt(" #n ")" ::: "memory")
; #define PG8_WAIT_L(n) asm volatile("s_waitcnt lgkmcnt(" #n ")" ::: "memory")
; #define PG8_BAR __builtin_amdgcn_s_barrier()
; #define PG8_SCHED __builtin_amdgcn_sched_barrier(0)
; template <class Epi, class Sched>
; __device__ __forceinline__ void gemm_phase(PG8_LAS unsigned char* lds, const int tid, const Gemm g, const Sched& S, const Epi& E) {
;     ...
;             const bool last = (t == nt - 2);
;             const char* a1 = cA + (size_t)(t + 1) * kstep;
;             const char* a2 = last ? nA : cA + (size_t)(t + 2) * kstep; const char* b2 = last ? nB : cB + (size_t)(t + 2) * kstep;
;             const char* a3 = a2 + kstep; const char* b3 = b2 + kstep;
;             if (last && has_next) S.a_ready(nxt);
;             PG8_LDB(B0, 0, 0); PG8_LDB(B1, 0, 1); PG8_SCHED; PG8_LDA(At, 0, 0); PG8_STAGE(PG8_SA(1, 1), a1 + hstepA, voffA);
;             PG8_WAIT_V(8); PG8_WAIT_L(0); PG8_BAR; PG8_MMA(0, 0, At, B0); PG8_MMA(0, 1, At, B1); PG8_BAR; PG8_SCHED;
;             PG8_LDA(At, 0, 1); PG8_STAGE(PG8_SB(0, 0), b2, voffB); PG8_STAGE(PG8_SB(0, 1), b2 + hstepB, voffB); PG8_STAGE(PG8_SA(0, 0), a2, voffA);
.LBB0_826:
	v_add_u32_e32 v142, s19, v150
	ds_read_b128 v[168:171], v142
	ds_read_b128 v[184:187], v142 offset:1024
	ds_read_b128 v[188:191], v142 offset:2048
	ds_read_b128 v[192:195], v142 offset:3072
	v_add_u32_e32 v142, s39, v150
	ds_read_b128 v[200:203], v142
	ds_read_b128 v[204:207], v142 offset:1024
	ds_read_b128 v[208:211], v142 offset:2048
	ds_read_b128 v[212:215], v142 offset:3072
	s_add_u32 s26, s2, 0xfffc0080
	s_addc_u32 s27, s3, -1
	s_cmp_eq_u32 s87, 12
	s_cselect_b32 s35, s7, s27
	s_cselect_b32 s34, s15, s26
	s_cselect_b32 s27, s13, s86
	s_cselect_b32 s26, s36, s46
	v_lshl_add_u64 v[142:143], s[2:3], 0, v[140:141]
	s_add_i32 m0, s42, 0xc000
	ds_read_b128 v[216:219], v167
	ds_read_b128 v[220:223], v167 offset:1024
	ds_read_b128 v[224:227], v167 offset:2048
	ds_read_b128 v[228:231], v167 offset:3072
	ds_read_b128 v[232:235], v167 offset:4096
	ds_read_b128 v[236:239], v167 offset:5120
	ds_read_b128 v[240:243], v167 offset:6144
	ds_read_b128 v[244:247], v167 offset:7168
	global_load_lds_dwordx4 v[142:143], off
	v_lshl_add_u64 v[142:143], s[2:3], 0, v[138:139]
	s_add_i32 m0, s42, 0xe000
	s_nop 0
	global_load_lds_dwordx4 v[142:143], off
	s_waitcnt vmcnt(8)
	s_waitcnt lgkmcnt(0)
	s_barrier
	s_waitcnt lgkmcnt(0)
	v_mfma_f32_16x16x32_bf16 v[126:129], v[168:171], v[216:219], v[126:129]
	v_mfma_f32_16x16x32_bf16 v[122:125], v[188:191], v[216:219], v[122:125]
	v_mfma_f32_16x16x32_bf16 v[118:121], v[168:171], v[224:227], v[118:121]
	v_mfma_f32_16x16x32_bf16 v[110:113], v[188:191], v[224:227], v[110:113]
	v_mfma_f32_16x16x32_bf16 v[102:105], v[168:171], v[232:235], v[102:105]
	v_mfma_f32_16x16x32_bf16 v[94:97], v[188:191], v[232:235], v[94:97]
	v_mfma_f32_16x16x32_bf16 v[86:89], v[168:171], v[240:243], v[86:89]
	v_mfma_f32_16x16x32_bf16 v[78:81], v[188:191], v[240:243], v[78:81]
	v_mfma_f32_16x16x32_bf16 v[126:129], v[184:187], v[220:223], v[126:129]
	v_mfma_f32_16x16x32_bf16 v[122:125], v[192:195], v[220:223], v[122:125]
	v_mfma_f32_16x16x32_bf16 v[118:121], v[184:187], v[228:231], v[118:121]
	v_mfma_f32_16x16x32_bf16 v[110:113], v[192:195], v[228:231], v[110:113]
	v_mfma_f32_16x16x32_bf16 v[102:105], v[184:187], v[236:239], v[102:105]
	v_mfma_f32_16x16x32_bf16 v[94:97], v[192:195], v[236:239], v[94:97]
	v_mfma_f32_16x16x32_bf16 v[86:89], v[184:187], v[244:247], v[86:89]
	v_mfma_f32_16x16x32_bf16 v[78:81], v[192:195], v[244:247], v[78:81]
	v_mfma_f32_16x16x32_bf16 v[114:117], v[200:203], v[216:219], v[114:117]
	v_mfma_f32_16x16x32_bf16 v[106:109], v[208:211], v[216:219], v[106:109]
	v_mfma_f32_16x16x32_bf16 v[98:101], v[200:203], v[224:227], v[98:101]
	v_mfma_f32_16x16x32_bf16 v[90:93], v[208:211], v[224:227], v[90:93]
	v_mfma_f32_16x16x32_bf16 v[82:85], v[200:203], v[232:235], v[82:85]
	v_mfma_f32_16x16x32_bf16 v[74:77], v[208:211], v[232:235], v[74:77]
	v_mfma_f32_16x16x32_bf16 v[70:73], v[200:203], v[240:243], v[70:73]
	v_mfma_f32_16x16x32_bf16 v[66:69], v[208:211], v[240:243], v[66:69]
	v_mfma_f32_16x16x32_bf16 v[114:117], v[204:207], v[220:223], v[114:117]
	v_mfma_f32_16x16x32_bf16 v[106:109], v[212:215], v[220:223], v[106:109]
	v_mfma_f32_16x16x32_bf16 v[98:101], v[204:207], v[228:231], v[98:101]
	v_mfma_f32_16x16x32_bf16 v[90:93], v[212:215], v[228:231], v[90:93]
	v_mfma_f32_16x16x32_bf16 v[82:85], v[204:207], v[236:239], v[82:85]
	v_mfma_f32_16x16x32_bf16 v[74:77], v[212:215], v[236:239], v[74:77]
	v_mfma_f32_16x16x32_bf16 v[70:73], v[204:207], v[244:247], v[70:73]
	v_mfma_f32_16x16x32_bf16 v[66:69], v[212:215], v[244:247], v[66:69]
	s_barrier
	s_mov_b32 m0, s29
	v_lshl_add_u64 v[142:143], s[26:27], 0, v[132:133]
	s_add_u32 s62, s26, 0x40000
	ds_read_b128 v[216:219], v167 offset:16384
	ds_read_b128 v[220:223], v167 offset:17408
	ds_read_b128 v[224:227], v167 offset:18432
	ds_read_b128 v[228:231], v167 offset:19456
	ds_read_b128 v[232:235], v167 offset:20480
	ds_read_b128 v[236:239], v167 offset:21504
	ds_read_b128 v[240:243], v167 offset:22528
	ds_read_b128 v[244:247], v167 offset:23552
	global_load_lds_dwordx4 v[142:143], off
	v_lshl_add_u64 v[196:197], s[26:27], 0, v[136:137]
	s_mov_b32 m0, s31
	s_addc_u32 s63, s27, 0
	global_load_lds_dwordx4 v[196:197], off
	v_lshl_add_u64 v[248:249], s[62:63], 0, v[132:133]
	s_mov_b32 m0, s40
	v_lshl_add_u64 v[250:251], s[34:35], 0, v[134:135]
	global_load_lds_dwordx4 v[248:249], off
	v_lshl_add_u64 v[248:249], s[62:63], 0, v[136:137]
	s_mov_b32 m0, s41
	s_nop 0
	global_load_lds_dwordx4 v[248:249], off
	v_lshl_add_u64 v[248:249], s[34:35], 0, v[130:131]
	s_mov_b32 m0, s42
	s_nop 0
	global_load_lds_dwordx4 v[248:249], off
	s_mov_b32 m0, s44
	s_nop 0
	global_load_lds_dwordx4 v[250:251], off
	s_waitcnt vmcnt(8)
	s_waitcnt lgkmcnt(0)
	s_barrier
; #define PG8_STAGE(bufoff, gbase, voff) do { _Pragma("unroll") for (int _i = 0; _i < 2; ++_i) \
;         __builtin_amdgcn_global_load_lds((const unsigned*)((const char*)(gbase) + (voff)[_i]), (PG8_LAS unsigned*)(lds + (bufoff) + ldsw + _i * 8192), 16, 0, 0); } while (0)
; #define PG8_LDA(dst, b, h) do { _Pragma("unroll") for (int m = 0; m < 4; ++m) _Pragma("unroll") for (int k = 0; k < 2; ++k) dst[m][k] = *(const PG8_LAS bf16x8*)(lds + PG8_SA(b, h) + aoff + m * 2048 + k * 1024); } while (0)
; #define PG8_LDB(dst, b, h) do { _Pragma("unroll") for (int n = 0; n < 2; ++n) _Pragma("unroll") for (int k = 0; k < 2; ++k) dst[n][k] = *(const PG8_LAS bf16x8*)(lds + PG8_SB(b, h) + boff + n * 2048 + k * 1024); } while (0)
; #define PG8_MMA(ai, bj, At, Bt) do { __builtin_amdgcn_s_setprio(1); _Pragma("unroll") for (int m = 0; m < 4; ++m) _Pragma("unroll") for (int n = 0; n < 2; ++n) _Pragma("unroll") for (int k = 0; k < 2; ++k) \
;         acc[ai][bj][m][n] = __builtin_amdgcn_mfma_f32_16x16x32_bf16(Bt[n][k], At[m][k], acc[ai][bj][m][n], 0, 0, 0); __builtin_amdgcn_s_setprio(0); } while (0)
; #define PG8_WAIT_V(n) asm volatile("s_waitcnt vmcnt(" #n ")" ::: "memory")
; #define PG8_WAIT_L(n) asm volatile("s_waitcnt lgkmcnt(" #n ")" ::: "memory")
; #define PG8_BAR __builtin_amdgcn_s_barrier()
; #define PG8_SCHED __builtin_amdgcn_sched_barrier(0)
; template <class Epi, class Sched>
; __device__ __forceinline__ void gemm_phase(PG8_LAS unsigned char* lds, const int tid, const Gemm g, const Sched& S, const Epi& E) {
;     ...
;             PG8_WAIT_V(8); PG8_WAIT_L(0); PG8_BAR; PG8_MMA(1, 0, At, B0); PG8_MMA(1, 1, At, B1); PG8_BAR; PG8_SCHED;
;             PG8_LDB(B0, 1, 0); PG8_LDB(B1, 1, 1); PG8_SCHED; PG8_LDA(At, 1, 0); PG8_STAGE(PG8_SA(0, 1), a2 + hstepA, voffA);
;             PG8_WAIT_V(8); PG8_WAIT_L(0); PG8_BAR; PG8_MMA(0, 0, At, B0); PG8_MMA(0, 1, At, B1); PG8_BAR; PG8_SCHED;
	s_waitcnt lgkmcnt(0)
	v_mfma_f32_16x16x32_bf16 v[62:65], v[168:171], v[216:219], v[62:65]
	v_mfma_f32_16x16x32_bf16 v[58:61], v[188:191], v[216:219], v[58:61]
	v_mfma_f32_16x16x32_bf16 v[54:57], v[168:171], v[224:227], v[54:57]
	v_mfma_f32_16x16x32_bf16 v[46:49], v[188:191], v[224:227], v[46:49]
	v_mfma_f32_16x16x32_bf16 v[38:41], v[168:171], v[232:235], v[38:41]
	v_mfma_f32_16x16x32_bf16 v[30:33], v[188:191], v[232:235], v[30:33]
	v_mfma_f32_16x16x32_bf16 v[22:25], v[168:171], v[240:243], v[22:25]
	v_mfma_f32_16x16x32_bf16 v[14:17], v[188:191], v[240:243], v[14:17]
	v_mfma_f32_16x16x32_bf16 v[62:65], v[184:187], v[220:223], v[62:65]
	v_mfma_f32_16x16x32_bf16 v[58:61], v[192:195], v[220:223], v[58:61]
	v_mfma_f32_16x16x32_bf16 v[54:57], v[184:187], v[228:231], v[54:57]
	v_mfma_f32_16x16x32_bf16 v[46:49], v[192:195], v[228:231], v[46:49]
	v_mfma_f32_16x16x32_bf16 v[38:41], v[184:187], v[236:239], v[38:41]
	v_mfma_f32_16x16x32_bf16 v[30:33], v[192:195], v[236:239], v[30:33]
	v_mfma_f32_16x16x32_bf16 v[22:25], v[184:187], v[244:247], v[22:25]
	v_mfma_f32_16x16x32_bf16 v[14:17], v[192:195], v[244:247], v[14:17]
	v_mfma_f32_16x16x32_bf16 v[50:53], v[200:203], v[216:219], v[50:53]
	v_mfma_f32_16x16x32_bf16 v[42:45], v[208:211], v[216:219], v[42:45]
	v_mfma_f32_16x16x32_bf16 v[34:37], v[200:203], v[224:227], v[34:37]
	v_mfma_f32_16x16x32_bf16 v[26:29], v[208:211], v[224:227], v[26:29]
	v_mfma_f32_16x16x32_bf16 v[18:21], v[200:203], v[232:235], v[18:21]
	v_mfma_f32_16x16x32_bf16 v[10:13], v[208:211], v[232:235], v[10:13]
	v_mfma_f32_16x16x32_bf16 v[6:9], v[200:203], v[240:243], v[6:9]
	v_mfma_f32_16x16x32_bf16 v[2:5], v[208:211], v[240:243], v[2:5]
	v_mfma_f32_16x16x32_bf16 v[50:53], v[204:207], v[220:223], v[50:53]
	v_mfma_f32_16x16x32_bf16 v[42:45], v[212:215], v[220:223], v[42:45]
	v_mfma_f32_16x16x32_bf16 v[34:37], v[204:207], v[228:231], v[34:37]
	v_mfma_f32_16x16x32_bf16 v[26:29], v[212:215], v[228:231], v[26:29]
	v_mfma_f32_16x16x32_bf16 v[18:21], v[204:207], v[236:239], v[18:21]
	v_mfma_f32_16x16x32_bf16 v[10:13], v[212:215], v[236:239], v[10:13]
	v_mfma_f32_16x16x32_bf16 v[6:9], v[204:207], v[244:247], v[6:9]
	v_mfma_f32_16x16x32_bf16 v[2:5], v[212:215], v[244:247], v[2:5]
	s_barrier
	v_add_u32_e32 v174, s49, v150
	ds_read_b128 v[168:171], v174
	ds_read_b128 v[184:187], v174 offset:1024
	ds_read_b128 v[188:191], v174 offset:2048
	ds_read_b128 v[192:195], v174 offset:3072
	v_add_u32_e32 v174, s80, v150
	ds_read_b128 v[200:203], v174
	ds_read_b128 v[204:207], v174 offset:1024
	ds_read_b128 v[208:211], v174 offset:2048
	ds_read_b128 v[212:215], v174 offset:3072
	s_add_u32 s34, s34, 0x40000
	s_addc_u32 s35, s35, 0
	s_mov_b32 m0, s45
	v_lshl_add_u64 v[252:253], s[34:35], 0, v[130:131]
	ds_read_b128 v[216:219], v167 offset:32768
	ds_read_b128 v[220:223], v167 offset:33792
	ds_read_b128 v[224:227], v167 offset:34816
	ds_read_b128 v[228:231], v167 offset:35840
	ds_read_b128 v[232:235], v167 offset:36864
	ds_read_b128 v[236:239], v167 offset:37888
	ds_read_b128 v[240:243], v167 offset:38912
	ds_read_b128 v[244:247], v167 offset:39936
	global_load_lds_dwordx4 v[252:253], off
	v_lshl_add_u64 v[252:253], s[34:35], 0, v[134:135]
	s_mov_b32 m0, s48
	s_nop 0
	global_load_lds_dwordx4 v[252:253], off
	s_waitcnt vmcnt(8)
	s_waitcnt lgkmcnt(0)
	s_barrier
	s_waitcnt lgkmcnt(0)
	v_mfma_f32_16x16x32_bf16 v[126:129], v[168:171], v[216:219], v[126:129]
	v_mfma_f32_16x16x32_bf16 v[122:125], v[188:191], v[216:219], v[122:125]
	v_mfma_f32_16x16x32_bf16 v[118:121], v[168:171], v[224:227], v[118:121]
	v_mfma_f32_16x16x32_bf16 v[110:113], v[188:191], v[224:227], v[110:113]
	v_mfma_f32_16x16x32_bf16 v[102:105], v[168:171], v[232:235], v[102:105]
	v_mfma_f32_16x16x32_bf16 v[94:97], v[188:191], v[232:235], v[94:97]
	v_mfma_f32_16x16x32_bf16 v[86:89], v[168:171], v[240:243], v[86:89]
	v_mfma_f32_16x16x32_bf16 v[78:81], v[188:191], v[240:243], v[78:81]
	v_mfma_f32_16x16x32_bf16 v[126:129], v[184:187], v[220:223], v[126:129]
	v_mfma_f32_16x16x32_bf16 v[122:125], v[192:195], v[220:223], v[122:125]
	v_mfma_f32_16x16x32_bf16 v[118:121], v[184:187], v[228:231], v[118:121]
	v_mfma_f32_16x16x32_bf16 v[110:113], v[192:195], v[228:231], v[110:113]
	v_mfma_f32_16x16x32_bf16 v[102:105], v[184:187], v[236:239], v[102:105]
	v_mfma_f32_16x16x32_bf16 v[94:97], v[192:195], v[236:239], v[94:97]
	v_mfma_f32_16x16x32_bf16 v[86:89], v[184:187], v[244:247], v[86:89]
	v_mfma_f32_16x16x32_bf16 v[78:81], v[192:195], v[244:247], v[78:81]
	v_mfma_f32_16x16x32_bf16 v[114:117], v[200:203], v[216:219], v[114:117]
	v_mfma_f32_16x16x32_bf16 v[106:109], v[208:211], v[216:219], v[106:109]
	v_mfma_f32_16x16x32_bf16 v[98:101], v[200:203], v[224:227], v[98:101]
	v_mfma_f32_16x16x32_bf16 v[90:93], v[208:211], v[224:227], v[90:93]
	v_mfma_f32_16x16x32_bf16 v[82:85], v[200:203], v[232:235], v[82:85]
	v_mfma_f32_16x16x32_bf16 v[74:77], v[208:211], v[232:235], v[74:77]
	v_mfma_f32_16x16x32_bf16 v[70:73], v[200:203], v[240:243], v[70:73]
	v_mfma_f32_16x16x32_bf16 v[66:69], v[208:211], v[240:243], v[66:69]
	v_mfma_f32_16x16x32_bf16 v[114:117], v[204:207], v[220:223], v[114:117]
	v_mfma_f32_16x16x32_bf16 v[106:109], v[212:215], v[220:223], v[106:109]
	v_mfma_f32_16x16x32_bf16 v[98:101], v[204:207], v[228:231], v[98:101]
	v_mfma_f32_16x16x32_bf16 v[90:93], v[212:215], v[228:231], v[90:93]
	v_mfma_f32_16x16x32_bf16 v[82:85], v[204:207], v[236:239], v[82:85]
	v_mfma_f32_16x16x32_bf16 v[74:77], v[212:215], v[236:239], v[74:77]
	v_mfma_f32_16x16x32_bf16 v[70:73], v[204:207], v[244:247], v[70:73]
	v_mfma_f32_16x16x32_bf16 v[66:69], v[212:215], v[244:247], v[66:69]
	s_barrier
; #define PG8_STAGE(bufoff, gbase, voff) do { _Pragma("unroll") for (int _i = 0; _i < 2; ++_i) \
;         __builtin_amdgcn_global_load_lds((const unsigned*)((const char*)(gbase) + (voff)[_i]), (PG8_LAS unsigned*)(lds + (bufoff) + ldsw + _i * 8192), 16, 0, 0); } while (0)
; #define PG8_LDA(dst, b, h) do { _Pragma("unroll") for (int m = 0; m < 4; ++m) _Pragma("unroll") for (int k = 0; k < 2; ++k) dst[m][k] = *(const PG8_LAS bf16x8*)(lds + PG8_SA(b, h) + aoff + m * 2048 + k * 1024); } while (0)
; #define PG8_MMA(ai, bj, At, Bt) do { __builtin_amdgcn_s_setprio(1); _Pragma("unroll") for (int m = 0; m < 4; ++m) _Pragma("unroll") for (int n = 0; n < 2; ++n) _Pragma("unroll") for (int k = 0; k < 2; ++k) \
;         acc[ai][bj][m][n] = __builtin_amdgcn_mfma_f32_16x16x32_bf16(Bt[n][k], At[m][k], acc[ai][bj][m][n], 0, 0, 0); __builtin_amdgcn_s_setprio(0); } while (0)
; #define PG8_WAIT_V(n) asm volatile("s_waitcnt vmcnt(" #n ")" ::: "memory")
; #define PG8_WAIT_L(n) asm volatile("s_waitcnt lgkmcnt(" #n ")" ::: "memory")
; #define PG8_BAR __builtin_amdgcn_s_barrier()
; #define PG8_SCHED __builtin_amdgcn_sched_barrier(0)
; template <class Epi, class Sched>
; __device__ __forceinline__ void gemm_phase(PG8_LAS unsigned char* lds, const int tid, const Gemm g, const Sched& S, const Epi& E) {
;     ...
;             PG8_LDA(At, 1, 1); PG8_STAGE(PG8_SB(1, 0), b3, voffB); PG8_STAGE(PG8_SB(1, 1), b3 + hstepB, voffB); PG8_STAGE(PG8_SA(1, 0), a3, voffA);
;             PG8_WAIT_V(8); PG8_WAIT_L(0); PG8_BAR; PG8_MMA(1, 0, At, B0); PG8_MMA(1, 1, At, B1); PG8_BAR; PG8_SCHED;
;         }
;         if constexpr (ALIGN_EPI) { if (wr == 0) PG8_BAR; }
	s_mov_b32 m0, s58
	v_lshl_add_u64 v[142:143], v[142:143], 0, s[54:55]
	s_add_u32 s26, s26, 0x40080
	ds_read_b128 v[216:219], v167 offset:49152
	ds_read_b128 v[220:223], v167 offset:50176
	ds_read_b128 v[224:227], v167 offset:51200
	ds_read_b128 v[228:231], v167 offset:52224
	ds_read_b128 v[232:235], v167 offset:53248
	ds_read_b128 v[236:239], v167 offset:54272
	ds_read_b128 v[240:243], v167 offset:55296
	ds_read_b128 v[244:247], v167 offset:56320
	global_load_lds_dwordx4 v[142:143], off
	v_lshl_add_u64 v[142:143], v[196:197], 0, s[54:55]
	s_mov_b32 m0, s59
	s_addc_u32 s27, s27, 0
	global_load_lds_dwordx4 v[142:143], off
	v_lshl_add_u64 v[142:143], s[26:27], 0, v[132:133]
	s_mov_b32 m0, s81
	s_nop 0
	global_load_lds_dwordx4 v[142:143], off
	v_lshl_add_u64 v[142:143], s[26:27], 0, v[136:137]
	s_mov_b32 m0, s82
	s_nop 0
	global_load_lds_dwordx4 v[142:143], off
	v_lshl_add_u64 v[142:143], v[248:249], 0, s[54:55]
	s_mov_b32 m0, s72
	s_nop 0
	global_load_lds_dwordx4 v[142:143], off
	v_lshl_add_u64 v[142:143], v[250:251], 0, s[54:55]
	s_mov_b32 m0, s73
	s_nop 0
	global_load_lds_dwordx4 v[142:143], off
	s_waitcnt vmcnt(8)
	s_waitcnt lgkmcnt(0)
	s_barrier
	s_waitcnt lgkmcnt(0)
	v_mfma_f32_16x16x32_bf16 v[62:65], v[168:171], v[216:219], v[62:65]
	v_mfma_f32_16x16x32_bf16 v[58:61], v[188:191], v[216:219], v[58:61]
	v_mfma_f32_16x16x32_bf16 v[54:57], v[168:171], v[224:227], v[54:57]
	v_mfma_f32_16x16x32_bf16 v[46:49], v[188:191], v[224:227], v[46:49]
	v_mfma_f32_16x16x32_bf16 v[38:41], v[168:171], v[232:235], v[38:41]
	v_mfma_f32_16x16x32_bf16 v[30:33], v[188:191], v[232:235], v[30:33]
	v_mfma_f32_16x16x32_bf16 v[22:25], v[168:171], v[240:243], v[22:25]
	v_mfma_f32_16x16x32_bf16 v[14:17], v[188:191], v[240:243], v[14:17]
	v_mfma_f32_16x16x32_bf16 v[62:65], v[184:187], v[220:223], v[62:65]
	v_mfma_f32_16x16x32_bf16 v[58:61], v[192:195], v[220:223], v[58:61]
	v_mfma_f32_16x16x32_bf16 v[54:57], v[184:187], v[228:231], v[54:57]
	v_mfma_f32_16x16x32_bf16 v[46:49], v[192:195], v[228:231], v[46:49]
	v_mfma_f32_16x16x32_bf16 v[38:41], v[184:187], v[236:239], v[38:41]
	v_mfma_f32_16x16x32_bf16 v[30:33], v[192:195], v[236:239], v[30:33]
	v_mfma_f32_16x16x32_bf16 v[22:25], v[184:187], v[244:247], v[22:25]
	v_mfma_f32_16x16x32_bf16 v[14:17], v[192:195], v[244:247], v[14:17]
	v_mfma_f32_16x16x32_bf16 v[50:53], v[200:203], v[216:219], v[50:53]
	v_mfma_f32_16x16x32_bf16 v[42:45], v[208:211], v[216:219], v[42:45]
	v_mfma_f32_16x16x32_bf16 v[34:37], v[200:203], v[224:227], v[34:37]
	v_mfma_f32_16x16x32_bf16 v[26:29], v[208:211], v[224:227], v[26:29]
	v_mfma_f32_16x16x32_bf16 v[18:21], v[200:203], v[232:235], v[18:21]
	v_mfma_f32_16x16x32_bf16 v[10:13], v[208:211], v[232:235], v[10:13]
	v_mfma_f32_16x16x32_bf16 v[6:9], v[200:203], v[240:243], v[6:9]
	v_mfma_f32_16x16x32_bf16 v[2:5], v[208:211], v[240:243], v[2:5]
	v_mfma_f32_16x16x32_bf16 v[50:53], v[204:207], v[220:223], v[50:53]
	v_mfma_f32_16x16x32_bf16 v[42:45], v[212:215], v[220:223], v[42:45]
	v_mfma_f32_16x16x32_bf16 v[34:37], v[204:207], v[228:231], v[34:37]
	v_mfma_f32_16x16x32_bf16 v[26:29], v[212:215], v[228:231], v[26:29]
	v_mfma_f32_16x16x32_bf16 v[18:21], v[204:207], v[236:239], v[18:21]
	v_mfma_f32_16x16x32_bf16 v[10:13], v[212:215], v[236:239], v[10:13]
	v_mfma_f32_16x16x32_bf16 v[6:9], v[204:207], v[244:247], v[6:9]
	v_mfma_f32_16x16x32_bf16 v[2:5], v[212:215], v[244:247], v[2:5]
	s_barrier
	s_add_i32 s87, s87, 2
	s_add_u32 s46, s46, 0x100
	s_addc_u32 s86, s86, 0
	s_add_u32 s2, s2, 0x100
	s_addc_u32 s3, s3, 0
	s_cmp_gt_u32 s87, 13
	s_cbranch_scc0 .LBB0_826
	s_and_b64 vcc, exec, s[10:11]
	s_cbranch_vccz .LBB0_829
	s_barrier

; #define PG8_STAGE(bufoff, gbase, voff) do { _Pragma("unroll") for (int _i = 0; _i < 2; ++_i) \
;         __builtin_amdgcn_global_load_lds((const unsigned*)((const char*)(gbase) + (voff)[_i]), (PG8_LAS unsigned*)(lds + (bufoff) + ldsw + _i * 8192), 16, 0, 0); } while (0)
; #define PG8_LDA(dst, b, h) do { _Pragma("unroll") for (int m = 0; m < 4; ++m) _Pragma("unroll") for (int k = 0; k < 2; ++k) dst[m][k] = *(const PG8_LAS bf16x8*)(lds + PG8_SA(b, h) + aoff + m * 2048 + k * 1024); } while (0)
; #define PG8_LDB(dst, b, h) do { _Pragma("unroll") for (int n = 0; n < 2; ++n) _Pragma("unroll") for (int k = 0; k < 2; ++k) dst[n][k] = *(const PG8_LAS bf16x8*)(lds + PG8_SB(b, h) + boff + n * 2048 + k * 1024); } while (0)
; #define PG8_MMA(ai, bj, At, Bt) do { __builtin_amdgcn_s_setprio(1); _Pragma("unroll") for (int m = 0; m < 4; ++m) _Pragma("unroll") for (int n = 0; n < 2; ++n) _Pragma("unroll") for (int k = 0; k < 2; ++k) \
;         acc[ai][bj][m][n] = __builtin_amdgcn_mfma_f32_16x16x32_bf16(Bt[n][k], At[m][k], acc[ai][bj][m][n], 0, 0, 0); __builtin_amdgcn_s_setprio(0); } while (0)
; #define PG8_WAIT_V(n) asm volatile("s_waitcnt vmcnt(" #n ")" ::: "memory")
; #define PG8_WAIT_L(n) asm volatile("s_waitcnt lgkmcnt(" #n ")" ::: "memory")
; #define PG8_BAR __builtin_amdgcn_s_barrier()
; #define PG8_SCHED __builtin_amdgcn_sched_barrier(0)
; template <class Epi, class Sched>
; __device__ __forceinline__ void gemm_phase(PG8_LAS unsigned char* lds, const int tid, const Gemm g, const Sched& S, const Epi& E) {
;     ...
;             const bool last = (t == nt - 2);
;             const char* a1 = cA + (size_t)(t + 1) * kstep;
;             const char* a2 = last ? nA : cA + (size_t)(t + 2) * kstep; const char* b2 = last ? nB : cB + (size_t)(t + 2) * kstep;
;             const char* a3 = a2 + kstep; const char* b3 = b2 + kstep;
;             if (last && has_next) S.a_ready(nxt);
;             PG8_LDB(B0, 0, 0); PG8_LDB(B1, 0, 1); PG8_SCHED; PG8_LDA(At, 0, 0); PG8_STAGE(PG8_SA(1, 1), a1 + hstepA, voffA);
;             PG8_WAIT_V(8); PG8_WAIT_L(0); PG8_BAR; PG8_MMA(0, 0, At, B0); PG8_MMA(0, 1, At, B1); PG8_BAR; PG8_SCHED;
;             PG8_LDA(At, 0, 1); PG8_STAGE(PG8_SB(0, 0), b2, voffB); PG8_STAGE(PG8_SB(0, 1), b2 + hstepB, voffB); PG8_STAGE(PG8_SA(0, 0), a2, voffA);
.LBB0_884:
	v_add_u32_e32 v142, s19, v150
	ds_read_b128 v[138:141], v142
	ds_read_b128 v[168:171], v142 offset:1024
	ds_read_b128 v[184:187], v142 offset:2048
	ds_read_b128 v[188:191], v142 offset:3072
	v_add_u32_e32 v142, s31, v150
	ds_read_b128 v[192:195], v142
	ds_read_b128 v[200:203], v142 offset:1024
	ds_read_b128 v[204:207], v142 offset:2048
	ds_read_b128 v[208:211], v142 offset:3072
	s_add_u32 s20, s2, 0xfffc0080
	s_addc_u32 s21, s3, -1
	s_cmp_eq_u32 s85, 12
	s_cselect_b32 s25, s13, s21
	s_cselect_b32 s24, s36, s20
	s_cselect_b32 s21, s11, s84
	s_cselect_b32 s20, s82, s83
	v_lshl_add_u64 v[142:143], s[2:3], 0, v[136:137]
	s_add_i32 m0, s39, 0xc000
	ds_read_b128 v[212:215], v166
	ds_read_b128 v[216:219], v166 offset:1024
	ds_read_b128 v[220:223], v166 offset:2048
	ds_read_b128 v[224:227], v166 offset:3072
	ds_read_b128 v[228:231], v166 offset:4096
	ds_read_b128 v[232:235], v166 offset:5120
	ds_read_b128 v[236:239], v166 offset:6144
	ds_read_b128 v[240:243], v166 offset:7168
	global_load_lds_dwordx4 v[142:143], off
	v_lshl_add_u64 v[142:143], s[2:3], 0, v[134:135]
	s_add_i32 m0, s39, 0xe000
	s_nop 0
	global_load_lds_dwordx4 v[142:143], off
	s_waitcnt vmcnt(8)
	s_waitcnt lgkmcnt(0)
	s_barrier
	s_waitcnt lgkmcnt(0)
	v_mfma_f32_16x16x32_bf16 v[126:129], v[138:141], v[212:215], v[126:129]
	v_mfma_f32_16x16x32_bf16 v[122:125], v[184:187], v[212:215], v[122:125]
	v_mfma_f32_16x16x32_bf16 v[110:113], v[138:141], v[220:223], v[110:113]
	v_mfma_f32_16x16x32_bf16 v[106:109], v[184:187], v[220:223], v[106:109]
	v_mfma_f32_16x16x32_bf16 v[94:97], v[138:141], v[228:231], v[94:97]
	v_mfma_f32_16x16x32_bf16 v[90:93], v[184:187], v[228:231], v[90:93]
	v_mfma_f32_16x16x32_bf16 v[78:81], v[138:141], v[236:239], v[78:81]
	v_mfma_f32_16x16x32_bf16 v[74:77], v[184:187], v[236:239], v[74:77]
	v_mfma_f32_16x16x32_bf16 v[126:129], v[168:171], v[216:219], v[126:129]
	v_mfma_f32_16x16x32_bf16 v[122:125], v[188:191], v[216:219], v[122:125]
	v_mfma_f32_16x16x32_bf16 v[110:113], v[168:171], v[224:227], v[110:113]
	v_mfma_f32_16x16x32_bf16 v[106:109], v[188:191], v[224:227], v[106:109]
	v_mfma_f32_16x16x32_bf16 v[94:97], v[168:171], v[232:235], v[94:97]
	v_mfma_f32_16x16x32_bf16 v[90:93], v[188:191], v[232:235], v[90:93]
	v_mfma_f32_16x16x32_bf16 v[78:81], v[168:171], v[240:243], v[78:81]
	v_mfma_f32_16x16x32_bf16 v[74:77], v[188:191], v[240:243], v[74:77]
	v_mfma_f32_16x16x32_bf16 v[118:121], v[192:195], v[212:215], v[118:121]
	v_mfma_f32_16x16x32_bf16 v[114:117], v[204:207], v[212:215], v[114:117]
	v_mfma_f32_16x16x32_bf16 v[102:105], v[192:195], v[220:223], v[102:105]
	v_mfma_f32_16x16x32_bf16 v[98:101], v[204:207], v[220:223], v[98:101]
	v_mfma_f32_16x16x32_bf16 v[86:89], v[192:195], v[228:231], v[86:89]
	v_mfma_f32_16x16x32_bf16 v[82:85], v[204:207], v[228:231], v[82:85]
	v_mfma_f32_16x16x32_bf16 v[70:73], v[192:195], v[236:239], v[70:73]
	v_mfma_f32_16x16x32_bf16 v[66:69], v[204:207], v[236:239], v[66:69]
	v_mfma_f32_16x16x32_bf16 v[118:121], v[200:203], v[216:219], v[118:121]
	v_mfma_f32_16x16x32_bf16 v[114:117], v[208:211], v[216:219], v[114:117]
	v_mfma_f32_16x16x32_bf16 v[102:105], v[200:203], v[224:227], v[102:105]
	v_mfma_f32_16x16x32_bf16 v[98:101], v[208:211], v[224:227], v[98:101]
	v_mfma_f32_16x16x32_bf16 v[86:89], v[200:203], v[232:235], v[86:89]
	v_mfma_f32_16x16x32_bf16 v[82:85], v[208:211], v[232:235], v[82:85]
	v_mfma_f32_16x16x32_bf16 v[70:73], v[200:203], v[240:243], v[70:73]
	v_mfma_f32_16x16x32_bf16 v[66:69], v[208:211], v[240:243], v[66:69]
	s_barrier
	s_mov_b32 m0, s27
	v_lshl_add_u64 v[142:143], s[20:21], 0, v[130:131]
	s_add_u32 s86, s20, 0x40000
	ds_read_b128 v[212:215], v166 offset:16384
	ds_read_b128 v[216:219], v166 offset:17408
	ds_read_b128 v[220:223], v166 offset:18432
	ds_read_b128 v[224:227], v166 offset:19456
	ds_read_b128 v[228:231], v166 offset:20480
	ds_read_b128 v[232:235], v166 offset:21504
	ds_read_b128 v[236:239], v166 offset:22528
	ds_read_b128 v[240:243], v166 offset:23552
	global_load_lds_dwordx4 v[142:143], off
	v_lshl_add_u64 v[196:197], s[20:21], 0, v[132:133]
	s_mov_b32 m0, s29
	s_addc_u32 s87, s21, 0
	global_load_lds_dwordx4 v[196:197], off
	v_lshl_add_u64 v[244:245], s[86:87], 0, v[130:131]
	s_mov_b32 m0, s34
	v_lshl_add_u64 v[246:247], s[24:25], 0, v[132:133]
	global_load_lds_dwordx4 v[244:245], off
	v_lshl_add_u64 v[244:245], s[86:87], 0, v[132:133]
	s_mov_b32 m0, s35
	s_nop 0
	global_load_lds_dwordx4 v[244:245], off
	v_lshl_add_u64 v[244:245], s[24:25], 0, v[130:131]
	s_mov_b32 m0, s39
	s_nop 0
	global_load_lds_dwordx4 v[244:245], off
	s_mov_b32 m0, s40
	s_nop 0
	global_load_lds_dwordx4 v[246:247], off
	s_waitcnt vmcnt(8)
	s_waitcnt lgkmcnt(0)
	s_barrier
; #define PG8_STAGE(bufoff, gbase, voff) do { _Pragma("unroll") for (int _i = 0; _i < 2; ++_i) \
;         __builtin_amdgcn_global_load_lds((const unsigned*)((const char*)(gbase) + (voff)[_i]), (PG8_LAS unsigned*)(lds + (bufoff) + ldsw + _i * 8192), 16, 0, 0); } while (0)
; #define PG8_LDA(dst, b, h) do { _Pragma("unroll") for (int m = 0; m < 4; ++m) _Pragma("unroll") for (int k = 0; k < 2; ++k) dst[m][k] = *(const PG8_LAS bf16x8*)(lds + PG8_SA(b, h) + aoff + m * 2048 + k * 1024); } while (0)
; #define PG8_LDB(dst, b, h) do { _Pragma("unroll") for (int n = 0; n < 2; ++n) _Pragma("unroll") for (int k = 0; k < 2; ++k) dst[n][k] = *(const PG8_LAS bf16x8*)(lds + PG8_SB(b, h) + boff + n * 2048 + k * 1024); } while (0)
; #define PG8_MMA(ai, bj, At, Bt) do { __builtin_amdgcn_s_setprio(1); _Pragma("unroll") for (int m = 0; m < 4; ++m) _Pragma("unroll") for (int n = 0; n < 2; ++n) _Pragma("unroll") for (int k = 0; k < 2; ++k) \
;         acc[ai][bj][m][n] = __builtin_amdgcn_mfma_f32_16x16x32_bf16(Bt[n][k], At[m][k], acc[ai][bj][m][n], 0, 0, 0); __builtin_amdgcn_s_setprio(0); } while (0)
; #define PG8_WAIT_V(n) asm volatile("s_waitcnt vmcnt(" #n ")" ::: "memory")
; #define PG8_WAIT_L(n) asm volatile("s_waitcnt lgkmcnt(" #n ")" ::: "memory")
; #define PG8_BAR __builtin_amdgcn_s_barrier()
; #define PG8_SCHED __builtin_amdgcn_sched_barrier(0)
; template <class Epi, class Sched>
; __device__ __forceinline__ void gemm_phase(PG8_LAS unsigned char* lds, const int tid, const Gemm g, const Sched& S, const Epi& E) {
;     ...
;             PG8_WAIT_V(8); PG8_WAIT_L(0); PG8_BAR; PG8_MMA(1, 0, At, B0); PG8_MMA(1, 1, At, B1); PG8_BAR; PG8_SCHED;
;             PG8_LDB(B0, 1, 0); PG8_LDB(B1, 1, 1); PG8_SCHED; PG8_LDA(At, 1, 0); PG8_STAGE(PG8_SA(0, 1), a2 + hstepA, voffA);
;             PG8_WAIT_V(8); PG8_WAIT_L(0); PG8_BAR; PG8_MMA(0, 0, At, B0); PG8_MMA(0, 1, At, B1); PG8_BAR; PG8_SCHED;
	s_waitcnt lgkmcnt(0)
	v_mfma_f32_16x16x32_bf16 v[62:65], v[138:141], v[212:215], v[62:65]
	v_mfma_f32_16x16x32_bf16 v[58:61], v[184:187], v[212:215], v[58:61]
	v_mfma_f32_16x16x32_bf16 v[46:49], v[138:141], v[220:223], v[46:49]
	v_mfma_f32_16x16x32_bf16 v[42:45], v[184:187], v[220:223], v[42:45]
	v_mfma_f32_16x16x32_bf16 v[30:33], v[138:141], v[228:231], v[30:33]
	v_mfma_f32_16x16x32_bf16 v[26:29], v[184:187], v[228:231], v[26:29]
	v_mfma_f32_16x16x32_bf16 v[14:17], v[138:141], v[236:239], v[14:17]
	v_mfma_f32_16x16x32_bf16 v[10:13], v[184:187], v[236:239], v[10:13]
	v_mfma_f32_16x16x32_bf16 v[62:65], v[168:171], v[216:219], v[62:65]
	v_mfma_f32_16x16x32_bf16 v[58:61], v[188:191], v[216:219], v[58:61]
	v_mfma_f32_16x16x32_bf16 v[46:49], v[168:171], v[224:227], v[46:49]
	v_mfma_f32_16x16x32_bf16 v[42:45], v[188:191], v[224:227], v[42:45]
	v_mfma_f32_16x16x32_bf16 v[30:33], v[168:171], v[232:235], v[30:33]
	v_mfma_f32_16x16x32_bf16 v[26:29], v[188:191], v[232:235], v[26:29]
	v_mfma_f32_16x16x32_bf16 v[14:17], v[168:171], v[240:243], v[14:17]
	v_mfma_f32_16x16x32_bf16 v[10:13], v[188:191], v[240:243], v[10:13]
	v_mfma_f32_16x16x32_bf16 v[54:57], v[192:195], v[212:215], v[54:57]
	v_mfma_f32_16x16x32_bf16 v[50:53], v[204:207], v[212:215], v[50:53]
	v_mfma_f32_16x16x32_bf16 v[38:41], v[192:195], v[220:223], v[38:41]
	v_mfma_f32_16x16x32_bf16 v[34:37], v[204:207], v[220:223], v[34:37]
	v_mfma_f32_16x16x32_bf16 v[22:25], v[192:195], v[228:231], v[22:25]
	v_mfma_f32_16x16x32_bf16 v[18:21], v[204:207], v[228:231], v[18:21]
	v_mfma_f32_16x16x32_bf16 v[6:9], v[192:195], v[236:239], v[6:9]
	v_mfma_f32_16x16x32_bf16 v[2:5], v[204:207], v[236:239], v[2:5]
	v_mfma_f32_16x16x32_bf16 v[54:57], v[200:203], v[216:219], v[54:57]
	v_mfma_f32_16x16x32_bf16 v[50:53], v[208:211], v[216:219], v[50:53]
	v_mfma_f32_16x16x32_bf16 v[38:41], v[200:203], v[224:227], v[38:41]
	v_mfma_f32_16x16x32_bf16 v[34:37], v[208:211], v[224:227], v[34:37]
	v_mfma_f32_16x16x32_bf16 v[22:25], v[200:203], v[232:235], v[22:25]
	v_mfma_f32_16x16x32_bf16 v[18:21], v[208:211], v[232:235], v[18:21]
	v_mfma_f32_16x16x32_bf16 v[6:9], v[200:203], v[240:243], v[6:9]
	v_mfma_f32_16x16x32_bf16 v[2:5], v[208:211], v[240:243], v[2:5]
	s_barrier
	v_add_u32_e32 v167, s44, v150
	ds_read_b128 v[138:141], v167
	ds_read_b128 v[168:171], v167 offset:1024
	ds_read_b128 v[184:187], v167 offset:2048
	ds_read_b128 v[188:191], v167 offset:3072
	v_add_u32_e32 v167, s59, v150
	ds_read_b128 v[192:195], v167
	ds_read_b128 v[200:203], v167 offset:1024
	ds_read_b128 v[204:207], v167 offset:2048
	ds_read_b128 v[208:211], v167 offset:3072
	s_add_u32 s24, s24, 0x40000
	s_addc_u32 s25, s25, 0
	s_mov_b32 m0, s41
	v_lshl_add_u64 v[248:249], s[24:25], 0, v[130:131]
	ds_read_b128 v[212:215], v166 offset:32768
	ds_read_b128 v[216:219], v166 offset:33792
	ds_read_b128 v[220:223], v166 offset:34816
	ds_read_b128 v[224:227], v166 offset:35840
	ds_read_b128 v[228:231], v166 offset:36864
	ds_read_b128 v[232:235], v166 offset:37888
	ds_read_b128 v[236:239], v166 offset:38912
	ds_read_b128 v[240:243], v166 offset:39936
	global_load_lds_dwordx4 v[248:249], off
	v_lshl_add_u64 v[248:249], s[24:25], 0, v[132:133]
	s_mov_b32 m0, s42
	s_nop 0
	global_load_lds_dwordx4 v[248:249], off
	s_waitcnt vmcnt(8)
	s_waitcnt lgkmcnt(0)
	s_barrier
	s_waitcnt lgkmcnt(0)
	v_mfma_f32_16x16x32_bf16 v[126:129], v[138:141], v[212:215], v[126:129]
	v_mfma_f32_16x16x32_bf16 v[122:125], v[184:187], v[212:215], v[122:125]
	v_mfma_f32_16x16x32_bf16 v[110:113], v[138:141], v[220:223], v[110:113]
	v_mfma_f32_16x16x32_bf16 v[106:109], v[184:187], v[220:223], v[106:109]
	v_mfma_f32_16x16x32_bf16 v[94:97], v[138:141], v[228:231], v[94:97]
	v_mfma_f32_16x16x32_bf16 v[90:93], v[184:187], v[228:231], v[90:93]
	v_mfma_f32_16x16x32_bf16 v[78:81], v[138:141], v[236:239], v[78:81]
	v_mfma_f32_16x16x32_bf16 v[74:77], v[184:187], v[236:239], v[74:77]
	v_mfma_f32_16x16x32_bf16 v[126:129], v[168:171], v[216:219], v[126:129]
	v_mfma_f32_16x16x32_bf16 v[122:125], v[188:191], v[216:219], v[122:125]
	v_mfma_f32_16x16x32_bf16 v[110:113], v[168:171], v[224:227], v[110:113]
	v_mfma_f32_16x16x32_bf16 v[106:109], v[188:191], v[224:227], v[106:109]
	v_mfma_f32_16x16x32_bf16 v[94:97], v[168:171], v[232:235], v[94:97]
	v_mfma_f32_16x16x32_bf16 v[90:93], v[188:191], v[232:235], v[90:93]
	v_mfma_f32_16x16x32_bf16 v[78:81], v[168:171], v[240:243], v[78:81]
	v_mfma_f32_16x16x32_bf16 v[74:77], v[188:191], v[240:243], v[74:77]
	v_mfma_f32_16x16x32_bf16 v[118:121], v[192:195], v[212:215], v[118:121]
	v_mfma_f32_16x16x32_bf16 v[114:117], v[204:207], v[212:215], v[114:117]
	v_mfma_f32_16x16x32_bf16 v[102:105], v[192:195], v[220:223], v[102:105]
	v_mfma_f32_16x16x32_bf16 v[98:101], v[204:207], v[220:223], v[98:101]
	v_mfma_f32_16x16x32_bf16 v[86:89], v[192:195], v[228:231], v[86:89]
	v_mfma_f32_16x16x32_bf16 v[82:85], v[204:207], v[228:231], v[82:85]
	v_mfma_f32_16x16x32_bf16 v[70:73], v[192:195], v[236:239], v[70:73]
	v_mfma_f32_16x16x32_bf16 v[66:69], v[204:207], v[236:239], v[66:69]
	v_mfma_f32_16x16x32_bf16 v[118:121], v[200:203], v[216:219], v[118:121]
	v_mfma_f32_16x16x32_bf16 v[114:117], v[208:211], v[216:219], v[114:117]
	v_mfma_f32_16x16x32_bf16 v[102:105], v[200:203], v[224:227], v[102:105]
	v_mfma_f32_16x16x32_bf16 v[98:101], v[208:211], v[224:227], v[98:101]
	v_mfma_f32_16x16x32_bf16 v[86:89], v[200:203], v[232:235], v[86:89]
	v_mfma_f32_16x16x32_bf16 v[82:85], v[208:211], v[232:235], v[82:85]
	v_mfma_f32_16x16x32_bf16 v[70:73], v[200:203], v[240:243], v[70:73]
	v_mfma_f32_16x16x32_bf16 v[66:69], v[208:211], v[240:243], v[66:69]
	s_barrier
; #define PG8_STAGE(bufoff, gbase, voff) do { _Pragma("unroll") for (int _i = 0; _i < 2; ++_i) \
;         __builtin_amdgcn_global_load_lds((const unsigned*)((const char*)(gbase) + (voff)[_i]), (PG8_LAS unsigned*)(lds + (bufoff) + ldsw + _i * 8192), 16, 0, 0); } while (0)
; #define PG8_LDA(dst, b, h) do { _Pragma("unroll") for (int m = 0; m < 4; ++m) _Pragma("unroll") for (int k = 0; k < 2; ++k) dst[m][k] = *(const PG8_LAS bf16x8*)(lds + PG8_SA(b, h) + aoff + m * 2048 + k * 1024); } while (0)
; #define PG8_MMA(ai, bj, At, Bt) do { __builtin_amdgcn_s_setprio(1); _Pragma("unroll") for (int m = 0; m < 4; ++m) _Pragma("unroll") for (int n = 0; n < 2; ++n) _Pragma("unroll") for (int k = 0; k < 2; ++k) \
;         acc[ai][bj][m][n] = __builtin_amdgcn_mfma_f32_16x16x32_bf16(Bt[n][k], At[m][k], acc[ai][bj][m][n], 0, 0, 0); __builtin_amdgcn_s_setprio(0); } while (0)
; #define PG8_WAIT_V(n) asm volatile("s_waitcnt vmcnt(" #n ")" ::: "memory")
; #define PG8_WAIT_L(n) asm volatile("s_waitcnt lgkmcnt(" #n ")" ::: "memory")
; #define PG8_BAR __builtin_amdgcn_s_barrier()
; #define PG8_SCHED __builtin_amdgcn_sched_barrier(0)
; template <class Epi, class Sched>
; __device__ __forceinline__ void gemm_phase(PG8_LAS unsigned char* lds, const int tid, const Gemm g, const Sched& S, const Epi& E) {
;     ...
;             PG8_LDA(At, 1, 1); PG8_STAGE(PG8_SB(1, 0), b3, voffB); PG8_STAGE(PG8_SB(1, 1), b3 + hstepB, voffB); PG8_STAGE(PG8_SA(1, 0), a3, voffA);
;             PG8_WAIT_V(8); PG8_WAIT_L(0); PG8_BAR; PG8_MMA(1, 0, At, B0); PG8_MMA(1, 1, At, B1); PG8_BAR; PG8_SCHED;
;         }
;         if constexpr (ALIGN_EPI) { if (wr == 0) PG8_BAR; }
	s_mov_b32 m0, s45
	v_lshl_add_u64 v[142:143], v[142:143], 0, s[54:55]
	s_add_u32 s20, s20, 0x40080
	ds_read_b128 v[212:215], v166 offset:49152
	ds_read_b128 v[216:219], v166 offset:50176
	ds_read_b128 v[220:223], v166 offset:51200
	ds_read_b128 v[224:227], v166 offset:52224
	ds_read_b128 v[228:231], v166 offset:53248
	ds_read_b128 v[232:235], v166 offset:54272
	ds_read_b128 v[236:239], v166 offset:55296
	ds_read_b128 v[240:243], v166 offset:56320
	global_load_lds_dwordx4 v[142:143], off
	v_lshl_add_u64 v[142:143], v[196:197], 0, s[54:55]
	s_mov_b32 m0, s48
	s_addc_u32 s21, s21, 0
	global_load_lds_dwordx4 v[142:143], off
	v_lshl_add_u64 v[142:143], s[20:21], 0, v[130:131]
	s_mov_b32 m0, s72
	s_nop 0
	global_load_lds_dwordx4 v[142:143], off
	v_lshl_add_u64 v[142:143], s[20:21], 0, v[132:133]
	s_mov_b32 m0, s73
	s_nop 0
	global_load_lds_dwordx4 v[142:143], off
	v_lshl_add_u64 v[142:143], v[244:245], 0, s[54:55]
	s_mov_b32 m0, s49
	s_nop 0
	global_load_lds_dwordx4 v[142:143], off
	v_lshl_add_u64 v[142:143], v[246:247], 0, s[54:55]
	s_mov_b32 m0, s58
	s_nop 0
	global_load_lds_dwordx4 v[142:143], off
	s_waitcnt vmcnt(8)
	s_waitcnt lgkmcnt(0)
	s_barrier
	s_waitcnt lgkmcnt(0)
	v_mfma_f32_16x16x32_bf16 v[62:65], v[138:141], v[212:215], v[62:65]
	v_mfma_f32_16x16x32_bf16 v[58:61], v[184:187], v[212:215], v[58:61]
	v_mfma_f32_16x16x32_bf16 v[46:49], v[138:141], v[220:223], v[46:49]
	v_mfma_f32_16x16x32_bf16 v[42:45], v[184:187], v[220:223], v[42:45]
	v_mfma_f32_16x16x32_bf16 v[30:33], v[138:141], v[228:231], v[30:33]
	v_mfma_f32_16x16x32_bf16 v[26:29], v[184:187], v[228:231], v[26:29]
	v_mfma_f32_16x16x32_bf16 v[14:17], v[138:141], v[236:239], v[14:17]
	v_mfma_f32_16x16x32_bf16 v[10:13], v[184:187], v[236:239], v[10:13]
	v_mfma_f32_16x16x32_bf16 v[62:65], v[168:171], v[216:219], v[62:65]
	v_mfma_f32_16x16x32_bf16 v[58:61], v[188:191], v[216:219], v[58:61]
	v_mfma_f32_16x16x32_bf16 v[46:49], v[168:171], v[224:227], v[46:49]
	v_mfma_f32_16x16x32_bf16 v[42:45], v[188:191], v[224:227], v[42:45]
	v_mfma_f32_16x16x32_bf16 v[30:33], v[168:171], v[232:235], v[30:33]
	v_mfma_f32_16x16x32_bf16 v[26:29], v[188:191], v[232:235], v[26:29]
	v_mfma_f32_16x16x32_bf16 v[14:17], v[168:171], v[240:243], v[14:17]
	v_mfma_f32_16x16x32_bf16 v[10:13], v[188:191], v[240:243], v[10:13]
	v_mfma_f32_16x16x32_bf16 v[54:57], v[192:195], v[212:215], v[54:57]
	v_mfma_f32_16x16x32_bf16 v[50:53], v[204:207], v[212:215], v[50:53]
	v_mfma_f32_16x16x32_bf16 v[38:41], v[192:195], v[220:223], v[38:41]
	v_mfma_f32_16x16x32_bf16 v[34:37], v[204:207], v[220:223], v[34:37]
	v_mfma_f32_16x16x32_bf16 v[22:25], v[192:195], v[228:231], v[22:25]
	v_mfma_f32_16x16x32_bf16 v[18:21], v[204:207], v[228:231], v[18:21]
	v_mfma_f32_16x16x32_bf16 v[6:9], v[192:195], v[236:239], v[6:9]
	v_mfma_f32_16x16x32_bf16 v[2:5], v[204:207], v[236:239], v[2:5]
	v_mfma_f32_16x16x32_bf16 v[54:57], v[200:203], v[216:219], v[54:57]
	v_mfma_f32_16x16x32_bf16 v[50:53], v[208:211], v[216:219], v[50:53]
	v_mfma_f32_16x16x32_bf16 v[38:41], v[200:203], v[224:227], v[38:41]
	v_mfma_f32_16x16x32_bf16 v[34:37], v[208:211], v[224:227], v[34:37]
	v_mfma_f32_16x16x32_bf16 v[22:25], v[200:203], v[232:235], v[22:25]
	v_mfma_f32_16x16x32_bf16 v[18:21], v[208:211], v[232:235], v[18:21]
	v_mfma_f32_16x16x32_bf16 v[6:9], v[200:203], v[240:243], v[6:9]
	v_mfma_f32_16x16x32_bf16 v[2:5], v[208:211], v[240:243], v[2:5]
	s_barrier
	s_add_i32 s85, s85, 2
	s_add_u32 s83, s83, 0x100
	s_addc_u32 s84, s84, 0
	s_add_u32 s2, s2, 0x100
	s_addc_u32 s3, s3, 0
	s_cmp_gt_u32 s85, 13
	s_cbranch_scc0 .LBB0_884
	s_and_b64 vcc, exec, s[8:9]
	s_cbranch_vccz .LBB0_887
	s_barrier
